# SwiGLU epilogues use packed f32 math; PAB GEMM no longer stages the all-zero half of block-structured B (4 instead of 6 LDS-DMA per SP2, vmcnt 8->6)
# speedup vs baseline: 1.0142x; 1.0142x over previous
; __device__ __forceinline__ unsigned cvt_pk_bf16(float lo, float hi) { unsigned r; asm volatile("v_cvt_pk_bf16_f32 %0, %1, %2" : "=v"(r) : "v"(lo), "v"(hi)); return r; }
; __device__ __forceinline__ float fast_sigmoid(float x) { return __builtin_amdgcn_rcpf(1.0f + __builtin_amdgcn_exp2f(-1.4426950408889634f * x)); }
; __device__ __forceinline__ float silu_f(float x) { return x * fast_sigmoid(x); }
;     __device__ __forceinline__ void operator()(const f32x4 (&acc)[2][2][4][2], const Unit& u, int wr, int wc, int fr, int fq) const {
;     ...
;         for (int ai = 0; ai < 2; ++ai)
; #pragma unroll
;             for (int m = 0; m < 4; ++m) {
;                 bf16_t* p = O + (size_t)(row0 + ai * HALF + m * 16) * DFF_ + col0;
;                 const f32x4 a0 = acc[ai][0][m][0], a1 = acc[ai][0][m][1], b0 = acc[ai][1][m][0], b1 = acc[ai][1][m][1];
;                 float h[8];
; #pragma unroll
;                 for (int e = 0; e < 4; ++e) { h[e] = silu_f(a0[e]) * b0[e]; h[4 + e] = silu_f(a1[e]) * b1[e]; }
;                 u32x4 w; w.x = cvt_pk_bf16(h[0], h[1]); w.y = cvt_pk_bf16(h[2], h[3]); w.z = cvt_pk_bf16(h[4], h[5]); w.w = cvt_pk_bf16(h[6], h[7]);
;                 *(u32x4*)p = w;
.LBB0_235:
	s_andn2_b64 vcc, exec, s[4:5]
	s_mov_b64 s[4:5], -1
	v_mov_b32_e32 v160, 0xbfb8aa3b
	v_mov_b32_e32 v161, 0xbfb8aa3b
	v_mov_b32_e32 v162, 1.0
	v_mov_b32_e32 v163, 1.0
	v_lshl_or_b32 v164, s57, 7, v148
	v_lshl_add_u32 v166, s26, 8, v146
	v_mov_b64_e32 v[168:169], s[8:9]
	v_ashrrev_i32_e32 v165, 31, v164
	v_mad_i64_i32 v[170:171], s[34:35], v166, s56, v[168:169]
	v_lshlrev_b64 v[164:165], 1, v[164:165]
	v_lshl_add_u64 v[170:171], v[170:171], 0, v[164:165]
	v_pk_mul_f32 v[152:153], v[124:125], v[160:161]
	v_pk_mul_f32 v[154:155], v[126:127], v[160:161]
	v_pk_mul_f32 v[156:157], v[120:121], v[160:161]
	v_pk_mul_f32 v[158:159], v[122:123], v[160:161]
	v_exp_f32_e32 v152, v152
	v_exp_f32_e32 v153, v153
	v_exp_f32_e32 v154, v154
	v_exp_f32_e32 v155, v155
	v_exp_f32_e32 v156, v156
	v_exp_f32_e32 v157, v157
	v_exp_f32_e32 v158, v158
	v_exp_f32_e32 v159, v159
	v_pk_add_f32 v[152:153], v[152:153], v[162:163]
	v_pk_add_f32 v[154:155], v[154:155], v[162:163]
	v_pk_add_f32 v[156:157], v[156:157], v[162:163]
	v_pk_add_f32 v[158:159], v[158:159], v[162:163]
	v_rcp_f32_e32 v152, v152
	v_rcp_f32_e32 v153, v153
	v_rcp_f32_e32 v154, v154
	v_rcp_f32_e32 v155, v155
	v_rcp_f32_e32 v156, v156
	v_rcp_f32_e32 v157, v157
	v_rcp_f32_e32 v158, v158
	v_rcp_f32_e32 v159, v159
	v_pk_mul_f32 v[152:153], v[124:125], v[152:153]
	v_pk_mul_f32 v[154:155], v[126:127], v[154:155]
	v_pk_mul_f32 v[156:157], v[120:121], v[156:157]
	v_pk_mul_f32 v[158:159], v[122:123], v[158:159]
	v_pk_mul_f32 v[152:153], v[152:153], v[116:117]
	v_pk_mul_f32 v[154:155], v[154:155], v[118:119]
	v_pk_mul_f32 v[156:157], v[156:157], v[112:113]
	v_pk_mul_f32 v[158:159], v[158:159], v[114:115]
	v_cvt_pk_bf16_f32 v194, v152, v153
	v_cvt_pk_bf16_f32 v195, v154, v155
	v_cvt_pk_bf16_f32 v196, v156, v157
	v_cvt_pk_bf16_f32 v197, v158, v159
	global_store_dwordx4 v[170:171], v[194:197], off
	v_pk_mul_f32 v[152:153], v[108:109], v[160:161]
	v_pk_mul_f32 v[154:155], v[110:111], v[160:161]
	v_pk_mul_f32 v[156:157], v[104:105], v[160:161]
	v_pk_mul_f32 v[158:159], v[106:107], v[160:161]
	v_exp_f32_e32 v152, v152
	v_exp_f32_e32 v153, v153
	v_exp_f32_e32 v154, v154
	v_exp_f32_e32 v155, v155
	v_exp_f32_e32 v156, v156
	v_exp_f32_e32 v157, v157
	v_exp_f32_e32 v158, v158
	v_exp_f32_e32 v159, v159
	v_pk_add_f32 v[152:153], v[152:153], v[162:163]
	v_pk_add_f32 v[154:155], v[154:155], v[162:163]
	v_pk_add_f32 v[156:157], v[156:157], v[162:163]
	v_pk_add_f32 v[158:159], v[158:159], v[162:163]
	v_rcp_f32_e32 v152, v152
	v_rcp_f32_e32 v153, v153
	v_rcp_f32_e32 v154, v154
	v_rcp_f32_e32 v155, v155
	v_rcp_f32_e32 v156, v156
	v_rcp_f32_e32 v157, v157
	v_rcp_f32_e32 v158, v158
	v_rcp_f32_e32 v159, v159
	s_mov_b64 s[34:35], 0x16000
	v_lshl_add_u64 v[188:189], v[170:171], 0, s[34:35]
	v_pk_mul_f32 v[152:153], v[108:109], v[152:153]
	v_pk_mul_f32 v[154:155], v[110:111], v[154:155]
	v_pk_mul_f32 v[156:157], v[104:105], v[156:157]
	v_pk_mul_f32 v[158:159], v[106:107], v[158:159]
	v_pk_mul_f32 v[152:153], v[152:153], v[100:101]
	v_pk_mul_f32 v[154:155], v[154:155], v[102:103]
	v_pk_mul_f32 v[156:157], v[156:157], v[96:97]
	v_pk_mul_f32 v[158:159], v[158:159], v[98:99]
	v_cvt_pk_bf16_f32 v222, v152, v153
	v_cvt_pk_bf16_f32 v223, v154, v155
	v_cvt_pk_bf16_f32 v224, v156, v157
	v_cvt_pk_bf16_f32 v225, v158, v159
	global_store_dwordx4 v[188:189], v[222:225], off
	v_pk_mul_f32 v[152:153], v[92:93], v[160:161]
	v_pk_mul_f32 v[154:155], v[94:95], v[160:161]
	v_pk_mul_f32 v[156:157], v[88:89], v[160:161]
	v_pk_mul_f32 v[158:159], v[90:91], v[160:161]
	v_exp_f32_e32 v152, v152
	v_exp_f32_e32 v153, v153
	v_exp_f32_e32 v154, v154
	v_exp_f32_e32 v155, v155
	v_exp_f32_e32 v156, v156
	v_exp_f32_e32 v157, v157
	v_exp_f32_e32 v158, v158
	v_exp_f32_e32 v159, v159
	v_pk_add_f32 v[152:153], v[152:153], v[162:163]
	v_pk_add_f32 v[154:155], v[154:155], v[162:163]
	v_pk_add_f32 v[156:157], v[156:157], v[162:163]
	v_pk_add_f32 v[158:159], v[158:159], v[162:163]
	v_rcp_f32_e32 v152, v152
	v_rcp_f32_e32 v153, v153
	v_rcp_f32_e32 v154, v154
	v_rcp_f32_e32 v155, v155
	v_rcp_f32_e32 v156, v156
	v_rcp_f32_e32 v157, v157
	v_rcp_f32_e32 v158, v158
	v_rcp_f32_e32 v159, v159
	s_mov_b64 s[34:35], 0x2c000
	v_lshl_add_u64 v[190:191], v[170:171], 0, s[34:35]
	v_pk_mul_f32 v[152:153], v[92:93], v[152:153]
	v_pk_mul_f32 v[154:155], v[94:95], v[154:155]
	v_pk_mul_f32 v[156:157], v[88:89], v[156:157]
	v_pk_mul_f32 v[158:159], v[90:91], v[158:159]
	v_pk_mul_f32 v[152:153], v[152:153], v[84:85]
	v_pk_mul_f32 v[154:155], v[154:155], v[86:87]
	v_pk_mul_f32 v[156:157], v[156:157], v[80:81]
	v_pk_mul_f32 v[158:159], v[158:159], v[82:83]
	v_cvt_pk_bf16_f32 v226, v152, v153
	v_cvt_pk_bf16_f32 v227, v154, v155
	v_cvt_pk_bf16_f32 v228, v156, v157
	v_cvt_pk_bf16_f32 v229, v158, v159
	global_store_dwordx4 v[190:191], v[226:229], off
	v_pk_mul_f32 v[152:153], v[76:77], v[160:161]
	v_pk_mul_f32 v[154:155], v[78:79], v[160:161]
	v_pk_mul_f32 v[156:157], v[72:73], v[160:161]
	v_pk_mul_f32 v[158:159], v[74:75], v[160:161]
	v_exp_f32_e32 v152, v152
	v_exp_f32_e32 v153, v153
	v_exp_f32_e32 v154, v154
	v_exp_f32_e32 v155, v155
	v_exp_f32_e32 v156, v156
	v_exp_f32_e32 v157, v157
	v_exp_f32_e32 v158, v158
	v_exp_f32_e32 v159, v159
	v_pk_add_f32 v[152:153], v[152:153], v[162:163]
	v_pk_add_f32 v[154:155], v[154:155], v[162:163]
	v_pk_add_f32 v[156:157], v[156:157], v[162:163]
	v_pk_add_f32 v[158:159], v[158:159], v[162:163]
	v_rcp_f32_e32 v152, v152
	v_rcp_f32_e32 v153, v153
	v_rcp_f32_e32 v154, v154
	v_rcp_f32_e32 v155, v155
	v_rcp_f32_e32 v156, v156
	v_rcp_f32_e32 v157, v157
	v_rcp_f32_e32 v158, v158
	v_rcp_f32_e32 v159, v159
	s_mov_b64 s[34:35], 0x42000
; __device__ __forceinline__ unsigned cvt_pk_bf16(float lo, float hi) { unsigned r; asm volatile("v_cvt_pk_bf16_f32 %0, %1, %2" : "=v"(r) : "v"(lo), "v"(hi)); return r; }
; __device__ __forceinline__ float fast_sigmoid(float x) { return __builtin_amdgcn_rcpf(1.0f + __builtin_amdgcn_exp2f(-1.4426950408889634f * x)); }
; __device__ __forceinline__ float silu_f(float x) { return x * fast_sigmoid(x); }
;     __device__ __forceinline__ void operator()(const f32x4 (&acc)[2][2][4][2], const Unit& u, int wr, int wc, int fr, int fq) const {
;     ...
;         for (int ai = 0; ai < 2; ++ai)
; #pragma unroll
;             for (int m = 0; m < 4; ++m) {
;                 bf16_t* p = O + (size_t)(row0 + ai * HALF + m * 16) * DFF_ + col0;
;                 const f32x4 a0 = acc[ai][0][m][0], a1 = acc[ai][0][m][1], b0 = acc[ai][1][m][0], b1 = acc[ai][1][m][1];
;                 float h[8];
; #pragma unroll
;                 for (int e = 0; e < 4; ++e) { h[e] = silu_f(a0[e]) * b0[e]; h[4 + e] = silu_f(a1[e]) * b1[e]; }
;                 u32x4 w; w.x = cvt_pk_bf16(h[0], h[1]); w.y = cvt_pk_bf16(h[2], h[3]); w.z = cvt_pk_bf16(h[4], h[5]); w.w = cvt_pk_bf16(h[6], h[7]);
;                 *(u32x4*)p = w;
	v_lshl_add_u64 v[192:193], v[170:171], 0, s[34:35]
	v_pk_mul_f32 v[152:153], v[76:77], v[152:153]
	v_pk_mul_f32 v[154:155], v[78:79], v[154:155]
	v_pk_mul_f32 v[156:157], v[72:73], v[156:157]
	v_pk_mul_f32 v[158:159], v[74:75], v[158:159]
	v_pk_mul_f32 v[152:153], v[152:153], v[68:69]
	v_pk_mul_f32 v[154:155], v[154:155], v[70:71]
	v_pk_mul_f32 v[156:157], v[156:157], v[64:65]
	v_pk_mul_f32 v[158:159], v[158:159], v[66:67]
	v_cvt_pk_bf16_f32 v230, v152, v153
	v_cvt_pk_bf16_f32 v231, v154, v155
	v_cvt_pk_bf16_f32 v232, v156, v157
	v_cvt_pk_bf16_f32 v233, v158, v159
	global_store_dwordx4 v[192:193], v[230:233], off
	v_pk_mul_f32 v[152:153], v[60:61], v[160:161]
	v_pk_mul_f32 v[154:155], v[62:63], v[160:161]
	v_pk_mul_f32 v[156:157], v[56:57], v[160:161]
	v_pk_mul_f32 v[158:159], v[58:59], v[160:161]
	v_exp_f32_e32 v152, v152
	v_exp_f32_e32 v153, v153
	v_exp_f32_e32 v154, v154
	v_exp_f32_e32 v155, v155
	v_exp_f32_e32 v156, v156
	v_exp_f32_e32 v157, v157
	v_exp_f32_e32 v158, v158
	v_exp_f32_e32 v159, v159
	v_pk_add_f32 v[152:153], v[152:153], v[162:163]
	v_pk_add_f32 v[154:155], v[154:155], v[162:163]
	v_pk_add_f32 v[156:157], v[156:157], v[162:163]
	v_pk_add_f32 v[158:159], v[158:159], v[162:163]
	v_rcp_f32_e32 v152, v152
	v_rcp_f32_e32 v153, v153
	v_rcp_f32_e32 v154, v154
	v_rcp_f32_e32 v155, v155
	v_rcp_f32_e32 v156, v156
	v_rcp_f32_e32 v157, v157
	v_rcp_f32_e32 v158, v158
	v_rcp_f32_e32 v159, v159
	s_mov_b64 s[34:35], 0xb0000
	v_lshl_add_u64 v[186:187], v[170:171], 0, s[34:35]
	v_pk_mul_f32 v[152:153], v[60:61], v[152:153]
	v_pk_mul_f32 v[154:155], v[62:63], v[154:155]
	v_pk_mul_f32 v[156:157], v[56:57], v[156:157]
	v_pk_mul_f32 v[158:159], v[58:59], v[158:159]
	v_pk_mul_f32 v[152:153], v[152:153], v[52:53]
	v_pk_mul_f32 v[154:155], v[154:155], v[54:55]
	v_pk_mul_f32 v[156:157], v[156:157], v[48:49]
	v_pk_mul_f32 v[158:159], v[158:159], v[50:51]
	v_cvt_pk_bf16_f32 v194, v152, v153
	v_cvt_pk_bf16_f32 v195, v154, v155
	v_cvt_pk_bf16_f32 v196, v156, v157
	v_cvt_pk_bf16_f32 v197, v158, v159
	global_store_dwordx4 v[186:187], v[194:197], off
	v_pk_mul_f32 v[152:153], v[44:45], v[160:161]
	v_pk_mul_f32 v[154:155], v[46:47], v[160:161]
	v_pk_mul_f32 v[156:157], v[40:41], v[160:161]
	v_pk_mul_f32 v[158:159], v[42:43], v[160:161]
	v_exp_f32_e32 v152, v152
	v_exp_f32_e32 v153, v153
	v_exp_f32_e32 v154, v154
	v_exp_f32_e32 v155, v155
	v_exp_f32_e32 v156, v156
	v_exp_f32_e32 v157, v157
	v_exp_f32_e32 v158, v158
	v_exp_f32_e32 v159, v159
	v_pk_add_f32 v[152:153], v[152:153], v[162:163]
	v_pk_add_f32 v[154:155], v[154:155], v[162:163]
	v_pk_add_f32 v[156:157], v[156:157], v[162:163]
	v_pk_add_f32 v[158:159], v[158:159], v[162:163]
	v_rcp_f32_e32 v152, v152
	v_rcp_f32_e32 v153, v153
	v_rcp_f32_e32 v154, v154
	v_rcp_f32_e32 v155, v155
	v_rcp_f32_e32 v156, v156
	v_rcp_f32_e32 v157, v157
	v_rcp_f32_e32 v158, v158
	v_rcp_f32_e32 v159, v159
	s_mov_b64 s[34:35], 0xc6000
	v_lshl_add_u64 v[188:189], v[170:171], 0, s[34:35]
	v_pk_mul_f32 v[152:153], v[44:45], v[152:153]
	v_pk_mul_f32 v[154:155], v[46:47], v[154:155]
	v_pk_mul_f32 v[156:157], v[40:41], v[156:157]
	v_pk_mul_f32 v[158:159], v[42:43], v[158:159]
	v_pk_mul_f32 v[152:153], v[152:153], v[36:37]
	v_pk_mul_f32 v[154:155], v[154:155], v[38:39]
	v_pk_mul_f32 v[156:157], v[156:157], v[32:33]
	v_pk_mul_f32 v[158:159], v[158:159], v[34:35]
	v_cvt_pk_bf16_f32 v222, v152, v153
	v_cvt_pk_bf16_f32 v223, v154, v155
	v_cvt_pk_bf16_f32 v224, v156, v157
	v_cvt_pk_bf16_f32 v225, v158, v159
	global_store_dwordx4 v[188:189], v[222:225], off
	v_pk_mul_f32 v[152:153], v[28:29], v[160:161]
	v_pk_mul_f32 v[154:155], v[30:31], v[160:161]
	v_pk_mul_f32 v[156:157], v[24:25], v[160:161]
	v_pk_mul_f32 v[158:159], v[26:27], v[160:161]
	v_exp_f32_e32 v152, v152
	v_exp_f32_e32 v153, v153
	v_exp_f32_e32 v154, v154
	v_exp_f32_e32 v155, v155
	v_exp_f32_e32 v156, v156
	v_exp_f32_e32 v157, v157
	v_exp_f32_e32 v158, v158
	v_exp_f32_e32 v159, v159
	v_pk_add_f32 v[152:153], v[152:153], v[162:163]
	v_pk_add_f32 v[154:155], v[154:155], v[162:163]
	v_pk_add_f32 v[156:157], v[156:157], v[162:163]
	v_pk_add_f32 v[158:159], v[158:159], v[162:163]
	v_rcp_f32_e32 v152, v152
	v_rcp_f32_e32 v153, v153
	v_rcp_f32_e32 v154, v154
	v_rcp_f32_e32 v155, v155
	v_rcp_f32_e32 v156, v156
	v_rcp_f32_e32 v157, v157
	v_rcp_f32_e32 v158, v158
	v_rcp_f32_e32 v159, v159
	s_mov_b64 s[34:35], 0xdc000
	v_lshl_add_u64 v[190:191], v[170:171], 0, s[34:35]
	v_pk_mul_f32 v[152:153], v[28:29], v[152:153]
	v_pk_mul_f32 v[154:155], v[30:31], v[154:155]
	v_pk_mul_f32 v[156:157], v[24:25], v[156:157]
	v_pk_mul_f32 v[158:159], v[26:27], v[158:159]
	v_pk_mul_f32 v[152:153], v[152:153], v[20:21]
	v_pk_mul_f32 v[154:155], v[154:155], v[22:23]
	v_pk_mul_f32 v[156:157], v[156:157], v[16:17]
	v_pk_mul_f32 v[158:159], v[158:159], v[18:19]
	v_cvt_pk_bf16_f32 v226, v152, v153
	v_cvt_pk_bf16_f32 v227, v154, v155
	v_cvt_pk_bf16_f32 v228, v156, v157
	v_cvt_pk_bf16_f32 v229, v158, v159
	global_store_dwordx4 v[190:191], v[226:229], off
	v_pk_mul_f32 v[152:153], v[12:13], v[160:161]
	v_pk_mul_f32 v[154:155], v[14:15], v[160:161]
	v_pk_mul_f32 v[156:157], v[8:9], v[160:161]
	v_pk_mul_f32 v[158:159], v[10:11], v[160:161]
	v_exp_f32_e32 v152, v152
	v_exp_f32_e32 v153, v153
	v_exp_f32_e32 v154, v154
	v_exp_f32_e32 v155, v155
	v_exp_f32_e32 v156, v156
	v_exp_f32_e32 v157, v157
	v_exp_f32_e32 v158, v158
	v_exp_f32_e32 v159, v159
	v_pk_add_f32 v[152:153], v[152:153], v[162:163]
	v_pk_add_f32 v[154:155], v[154:155], v[162:163]
	v_pk_add_f32 v[156:157], v[156:157], v[162:163]
	v_pk_add_f32 v[158:159], v[158:159], v[162:163]
	v_rcp_f32_e32 v152, v152
	v_rcp_f32_e32 v153, v153
	v_rcp_f32_e32 v154, v154
	v_rcp_f32_e32 v155, v155
	v_rcp_f32_e32 v156, v156
	v_rcp_f32_e32 v157, v157
	v_rcp_f32_e32 v158, v158
	v_rcp_f32_e32 v159, v159
	s_mov_b64 s[34:35], 0xf2000
	v_lshl_add_u64 v[192:193], v[170:171], 0, s[34:35]
	v_pk_mul_f32 v[152:153], v[12:13], v[152:153]
	v_pk_mul_f32 v[154:155], v[14:15], v[154:155]
	v_pk_mul_f32 v[156:157], v[8:9], v[156:157]
	v_pk_mul_f32 v[158:159], v[10:11], v[158:159]
	v_pk_mul_f32 v[152:153], v[152:153], v[4:5]
	v_pk_mul_f32 v[154:155], v[154:155], v[6:7]
	v_pk_mul_f32 v[156:157], v[156:157], v[0:1]
	v_pk_mul_f32 v[158:159], v[158:159], v[2:3]
	v_cvt_pk_bf16_f32 v230, v152, v153
	v_cvt_pk_bf16_f32 v231, v154, v155
	v_cvt_pk_bf16_f32 v232, v156, v157
	v_cvt_pk_bf16_f32 v233, v158, v159
	global_store_dwordx4 v[192:193], v[230:233], off
	s_cbranch_vccnz .LBB0_224
	s_andn2_b64 vcc, exec, s[6:7]
	s_cbranch_vccnz .LBB0_223
	s_barrier
	s_branch .LBB0_223

; #define PG8_STAGE(bufoff, gbase, voff) do { _Pragma("unroll") for (int _i = 0; _i < 2; ++_i) \
;         __builtin_amdgcn_global_load_lds((const unsigned*)((const char*)(gbase) + (voff)[_i]), (PG8_LAS unsigned*)(lds + (bufoff) + ldsw + _i * 8192), 16, 0, 0); } while (0)
; #define PG8_LDA(dst, b, h) do { _Pragma("unroll") for (int m = 0; m < 4; ++m) _Pragma("unroll") for (int k = 0; k < 2; ++k) dst[m][k] = *(const PG8_LAS bf16x8*)(lds + PG8_SA(b, h) + aoff + m * 2048 + k * 1024); } while (0)
; #define PG8_LDB(dst, b, h) do { _Pragma("unroll") for (int n = 0; n < 2; ++n) _Pragma("unroll") for (int k = 0; k < 2; ++k) dst[n][k] = *(const PG8_LAS bf16x8*)(lds + PG8_SB(b, h) + boff + n * 2048 + k * 1024); } while (0)
; #define PG8_WAIT_V(n) asm volatile("s_waitcnt vmcnt(" #n ")" ::: "memory")
; #define PG8_WAIT_L(n) asm volatile("s_waitcnt lgkmcnt(" #n ")" ::: "memory")
; #define PG8_BAR __builtin_amdgcn_s_barrier()
; #define PG8_SCHED __builtin_amdgcn_sched_barrier(0)
; #define PG8_MMA2(ai) PG8_MMA(ai, 0, At, B0)
; #define PG8_MMA2(ai) PG8_MMA(ai, 1, At, B1)
; #define PG8_MMA2(ai) do { PG8_MMA(ai, 0, At, B0); PG8_MMA(ai, 1, At, B1); } while (0)
;     ...
;             PG8_LDB(B0, 0, 0); PG8_LDB(B1, 0, 1); PG8_SCHED; PG8_LDA(At, 0, 0); PG8_STAGE(PG8_SA(1, 1), a1 + hstep, voffA);
;             PG8_WAIT_V(8); PG8_WAIT_L(0); PG8_BAR; PG8_MMA2(0); PG8_BAR; PG8_SCHED;
;             PG8_LDA(At, 0, 1); PG8_STAGE(PG8_SB(0, 0), b2, voffB); PG8_STAGE(PG8_SB(0, 1), b2 + hstep, voffB); PG8_STAGE(PG8_SA(0, 0), a2, voffA);
;             PG8_WAIT_V(8); PG8_WAIT_L(0); PG8_BAR; PG8_MMA2(1); PG8_BAR; PG8_SCHED;
;             PG8_LDB(B0, 1, 0); PG8_LDB(B1, 1, 1); PG8_SCHED; PG8_LDA(At, 1, 0); PG8_STAGE(PG8_SA(0, 1), a2 + hstep, voffA);
;             PG8_WAIT_V(8); PG8_WAIT_L(0); PG8_BAR; PG8_MMA2(0); PG8_BAR; PG8_SCHED;
;             PG8_LDA(At, 1, 1); PG8_STAGE(PG8_SB(1, 0), b3, voffB); PG8_STAGE(PG8_SB(1, 1), b3 + hstep, voffB); PG8_STAGE(PG8_SA(1, 0), a3, voffA);
;             PG8_WAIT_V(8); PG8_WAIT_L(0); PG8_BAR; PG8_MMA2(1); PG8_BAR; PG8_SCHED;
.LBB0_1048:
	s_ashr_i32 s67, s66, 31
	ds_read_b128 v[0:3], v148
	ds_read_b128 v[4:7], v148 offset:1024
	ds_read_b128 v[8:11], v148 offset:2048
	ds_read_b128 v[12:15], v148 offset:3072
	s_lshl_b64 s[6:7], s[66:67], 19
	s_add_u32 s68, s29, s6
	s_addc_u32 s69, s84, s7
	s_ashr_i32 s65, s64, 31
	s_lshl_b64 s[6:7], s[64:65], 19
	s_add_u32 s70, s85, s6
	s_addc_u32 s71, s86, s7
	s_add_u32 s6, s74, 0x40080
	s_addc_u32 s7, s75, 0
	s_add_i32 s73, s83, 0xc000
	v_lshl_add_u64 v[48:49], s[6:7], 0, v[134:135]
	s_mov_b32 m0, s73
	s_add_i32 s65, s83, 0xe000
	ds_read_b128 v[16:19], v146
	ds_read_b128 v[20:23], v146 offset:1024
	ds_read_b128 v[24:27], v146 offset:2048
	ds_read_b128 v[28:31], v146 offset:3072
	ds_read_b128 v[32:35], v146 offset:4096
	ds_read_b128 v[36:39], v146 offset:5120
	ds_read_b128 v[40:43], v146 offset:6144
	ds_read_b128 v[44:47], v146 offset:7168
	global_load_lds_dwordx4 v[48:49], off
	v_lshl_add_u64 v[48:49], s[6:7], 0, v[130:131]
	s_mov_b32 m0, s65
	s_nop 0
	global_load_lds_dwordx4 v[48:49], off
	s_waitcnt vmcnt(6)
	s_waitcnt lgkmcnt(0)
	s_barrier
	s_setprio 1
	s_waitcnt lgkmcnt(0)
	v_mfma_f32_16x16x32_bf16 v[48:51], v[0:3], v[16:19], 0
	v_mfma_f32_16x16x32_bf16 v[16:19], v[8:11], v[16:19], 0
	v_mfma_f32_16x16x32_bf16 v[48:51], v[4:7], v[20:23], v[48:51]
	v_mfma_f32_16x16x32_bf16 v[16:19], v[12:15], v[20:23], v[16:19]
	v_mfma_f32_16x16x32_bf16 v[20:23], v[0:3], v[24:27], 0
	v_mfma_f32_16x16x32_bf16 v[24:27], v[8:11], v[24:27], 0
	v_mfma_f32_16x16x32_bf16 v[20:23], v[4:7], v[28:31], v[20:23]
	v_mfma_f32_16x16x32_bf16 v[24:27], v[12:15], v[28:31], v[24:27]
	v_mfma_f32_16x16x32_bf16 v[28:31], v[0:3], v[32:35], 0
	v_mfma_f32_16x16x32_bf16 v[32:35], v[8:11], v[32:35], 0
	v_mfma_f32_16x16x32_bf16 v[28:31], v[4:7], v[36:39], v[28:31]
	v_mfma_f32_16x16x32_bf16 v[32:35], v[12:15], v[36:39], v[32:35]
	v_mfma_f32_16x16x32_bf16 v[36:39], v[0:3], v[40:43], 0
	v_mfma_f32_16x16x32_bf16 v[40:43], v[8:11], v[40:43], 0
	v_mfma_f32_16x16x32_bf16 v[36:39], v[4:7], v[44:47], v[36:39]
	v_mfma_f32_16x16x32_bf16 v[40:43], v[12:15], v[44:47], v[40:43]
	s_setprio 0
	s_barrier
	v_lshl_add_u64 v[56:57], s[76:77], 0, v[132:133]
	s_add_i32 s67, s3, s87
	v_lshl_add_u64 v[58:59], v[56:57], 0, s[36:37]
	s_mov_b32 m0, s67
	s_add_i32 s6, s67, 0x2000
	ds_read_b128 v[44:47], v146 offset:16384
	ds_read_b128 v[52:55], v146 offset:17408
	ds_read_b128 v[64:67], v146 offset:18432
	ds_read_b128 v[68:71], v146 offset:19456
	ds_read_b128 v[72:75], v146 offset:20480
	ds_read_b128 v[76:79], v146 offset:21504
	ds_read_b128 v[80:83], v146 offset:22528
	ds_read_b128 v[84:87], v146 offset:23552
	global_load_lds_dwordx4 v[58:59], off
	v_lshl_add_u64 v[58:59], s[76:77], 0, v[128:129]
	s_add_u32 s8, s76, 0x40100
	v_lshl_add_u64 v[60:61], v[58:59], 0, s[36:37]
	s_mov_b32 m0, s6
	s_addc_u32 s9, s77, 0
	s_add_i32 vcc_lo, s96, s87
	global_load_lds_dwordx4 v[60:61], off
	v_lshl_add_u64 v[60:61], s[8:9], 0, v[132:133]
	s_mov_b32 m0, vcc_lo
	s_add_i32 vcc_hi, vcc_lo, 0x2000
	v_lshl_add_u64 v[60:61], s[8:9], 0, v[128:129]
	s_mov_b32 m0, vcc_hi
	s_nop 0
	v_lshl_add_u64 v[60:61], s[74:75], 0, v[134:135]
	v_lshl_add_u64 v[62:63], v[60:61], 0, s[36:37]
	s_mov_b32 m0, s83
	s_nop 0
	global_load_lds_dwordx4 v[62:63], off
	v_lshl_add_u64 v[62:63], s[74:75], 0, v[130:131]
	v_lshl_add_u64 v[88:89], v[62:63], 0, s[36:37]
	s_mov_b32 m0, s89
	s_nop 0
	global_load_lds_dwordx4 v[88:89], off
	s_waitcnt vmcnt(6)
	s_waitcnt lgkmcnt(0)
	s_barrier
	s_setprio 1
	s_waitcnt lgkmcnt(0)
	v_mfma_f32_16x16x32_bf16 v[88:91], v[0:3], v[44:47], 0
	v_mfma_f32_16x16x32_bf16 v[44:47], v[8:11], v[44:47], 0
	v_mfma_f32_16x16x32_bf16 v[88:91], v[4:7], v[52:55], v[88:91]
	v_mfma_f32_16x16x32_bf16 v[44:47], v[12:15], v[52:55], v[44:47]
	v_mfma_f32_16x16x32_bf16 v[52:55], v[0:3], v[64:67], 0
	v_mfma_f32_16x16x32_bf16 v[64:67], v[8:11], v[64:67], 0
	v_mfma_f32_16x16x32_bf16 v[52:55], v[4:7], v[68:71], v[52:55]
	v_mfma_f32_16x16x32_bf16 v[64:67], v[12:15], v[68:71], v[64:67]
	v_mfma_f32_16x16x32_bf16 v[68:71], v[0:3], v[72:75], 0
	v_mfma_f32_16x16x32_bf16 v[0:3], v[0:3], v[80:83], 0
	v_mfma_f32_16x16x32_bf16 v[68:71], v[4:7], v[76:79], v[68:71]
	v_mfma_f32_16x16x32_bf16 v[72:75], v[8:11], v[72:75], 0
	v_mfma_f32_16x16x32_bf16 v[2:5], v[4:7], v[84:87], v[0:3]
	v_mfma_f32_16x16x32_bf16 v[6:9], v[8:11], v[80:83], 0
	v_mfma_f32_16x16x32_bf16 v[72:75], v[12:15], v[76:79], v[72:75]
	v_mfma_f32_16x16x32_bf16 v[6:9], v[12:15], v[84:87], v[6:9]
	s_setprio 0
	s_barrier
	s_add_i32 s7, 0, 0x18000
	v_add_u32_e32 v0, s7, v145
	ds_read_b128 v[10:13], v0
	ds_read_b128 v[76:79], v0 offset:1024
	ds_read_b128 v[80:83], v0 offset:2048
	ds_read_b128 v[84:87], v0 offset:3072
	s_add_u32 s8, s74, 0x40100
	s_addc_u32 s9, s75, 0
	s_mov_b32 m0, s90
	v_lshl_add_u64 v[14:15], s[8:9], 0, v[134:135]
	ds_read_b128 v[92:95], v146 offset:32768
	ds_read_b128 v[96:99], v146 offset:33792
	ds_read_b128 v[100:103], v146 offset:34816
	ds_read_b128 v[104:107], v146 offset:35840
	ds_read_b128 v[108:111], v146 offset:36864
	ds_read_b128 v[112:115], v146 offset:37888
	ds_read_b128 v[116:119], v146 offset:38912
	ds_read_b128 v[120:123], v146 offset:39936
	global_load_lds_dwordx4 v[14:15], off
	v_lshl_add_u64 v[14:15], s[8:9], 0, v[130:131]
	s_mov_b32 m0, s91
	s_nop 0
	global_load_lds_dwordx4 v[14:15], off
	s_waitcnt vmcnt(6)
	s_waitcnt lgkmcnt(0)
	s_barrier
; #define PG8_STAGE(bufoff, gbase, voff) do { _Pragma("unroll") for (int _i = 0; _i < 2; ++_i) \
;         __builtin_amdgcn_global_load_lds((const unsigned*)((const char*)(gbase) + (voff)[_i]), (PG8_LAS unsigned*)(lds + (bufoff) + ldsw + _i * 8192), 16, 0, 0); } while (0)
; #define PG8_LDA(dst, b, h) do { _Pragma("unroll") for (int m = 0; m < 4; ++m) _Pragma("unroll") for (int k = 0; k < 2; ++k) dst[m][k] = *(const PG8_LAS bf16x8*)(lds + PG8_SA(b, h) + aoff + m * 2048 + k * 1024); } while (0)
; #define PG8_LDB(dst, b, h) do { _Pragma("unroll") for (int n = 0; n < 2; ++n) _Pragma("unroll") for (int k = 0; k < 2; ++k) dst[n][k] = *(const PG8_LAS bf16x8*)(lds + PG8_SB(b, h) + boff + n * 2048 + k * 1024); } while (0)
; #define PG8_WAIT_V(n) asm volatile("s_waitcnt vmcnt(" #n ")" ::: "memory")
; #define PG8_WAIT_L(n) asm volatile("s_waitcnt lgkmcnt(" #n ")" ::: "memory")
; #define PG8_BAR __builtin_amdgcn_s_barrier()
; #define PG8_SCHED __builtin_amdgcn_sched_barrier(0)
; #define PG8_MMA2(ai) PG8_MMA(ai, 0, At, B0)
; #define PG8_MMA2(ai) PG8_MMA(ai, 1, At, B1)
; #define PG8_MMA2(ai) do { PG8_MMA(ai, 0, At, B0); PG8_MMA(ai, 1, At, B1); } while (0)
;     ...
;             PG8_LDB(B0, 0, 0); PG8_LDB(B1, 0, 1); PG8_SCHED; PG8_LDA(At, 0, 0); PG8_STAGE(PG8_SA(1, 1), a1 + hstep, voffA);
;             PG8_WAIT_V(8); PG8_WAIT_L(0); PG8_BAR; PG8_MMA2(0); PG8_BAR; PG8_SCHED;
;             PG8_LDA(At, 0, 1); PG8_STAGE(PG8_SB(0, 0), b2, voffB); PG8_STAGE(PG8_SB(0, 1), b2 + hstep, voffB); PG8_STAGE(PG8_SA(0, 0), a2, voffA);
;             PG8_WAIT_V(8); PG8_WAIT_L(0); PG8_BAR; PG8_MMA2(1); PG8_BAR; PG8_SCHED;
;             PG8_LDB(B0, 1, 0); PG8_LDB(B1, 1, 1); PG8_SCHED; PG8_LDA(At, 1, 0); PG8_STAGE(PG8_SA(0, 1), a2 + hstep, voffA);
;             PG8_WAIT_V(8); PG8_WAIT_L(0); PG8_BAR; PG8_MMA2(0); PG8_BAR; PG8_SCHED;
;             PG8_LDA(At, 1, 1); PG8_STAGE(PG8_SB(1, 0), b3, voffB); PG8_STAGE(PG8_SB(1, 1), b3 + hstep, voffB); PG8_STAGE(PG8_SA(1, 0), a3, voffA);
;             PG8_WAIT_V(8); PG8_WAIT_L(0); PG8_BAR; PG8_MMA2(1); PG8_BAR; PG8_SCHED;
	s_setprio 1
	s_waitcnt lgkmcnt(0)
	v_mfma_f32_16x16x32_bf16 v[48:51], v[10:13], v[92:95], v[48:51]
	v_mfma_f32_16x16x32_bf16 v[14:17], v[80:83], v[92:95], v[16:19]
	v_mfma_f32_16x16x32_bf16 v[18:21], v[10:13], v[100:103], v[20:23]
	v_mfma_f32_16x16x32_bf16 v[22:25], v[80:83], v[100:103], v[24:27]
	v_mfma_f32_16x16x32_bf16 v[26:29], v[10:13], v[108:111], v[28:31]
	v_mfma_f32_16x16x32_bf16 v[30:33], v[80:83], v[108:111], v[32:35]
	v_mfma_f32_16x16x32_bf16 v[34:37], v[10:13], v[116:119], v[36:39]
	v_mfma_f32_16x16x32_bf16 v[38:41], v[80:83], v[116:119], v[40:43]
	v_mfma_f32_16x16x32_bf16 v[48:51], v[76:79], v[96:99], v[48:51]
	v_mfma_f32_16x16x32_bf16 v[14:17], v[84:87], v[96:99], v[14:17]
	v_mfma_f32_16x16x32_bf16 v[18:21], v[76:79], v[104:107], v[18:21]
	v_mfma_f32_16x16x32_bf16 v[22:25], v[84:87], v[104:107], v[22:25]
	v_mfma_f32_16x16x32_bf16 v[26:29], v[76:79], v[112:115], v[26:29]
	v_mfma_f32_16x16x32_bf16 v[30:33], v[84:87], v[112:115], v[30:33]
	v_mfma_f32_16x16x32_bf16 v[34:37], v[76:79], v[120:123], v[34:37]
	v_mfma_f32_16x16x32_bf16 v[38:41], v[84:87], v[120:123], v[38:41]
	s_setprio 0
	s_barrier
	s_add_i32 s9, s7, s87
	s_add_i32 s82, s9, 0x2000
	s_add_u32 s78, s76, 0x40180
	v_lshl_add_u64 v[42:43], v[56:57], 0, s[38:39]
	s_mov_b32 m0, s9
	s_addc_u32 s79, s77, 0
	s_add_i32 s34, 0, 0x1c000
	ds_read_b128 v[92:95], v146 offset:49152
	ds_read_b128 v[96:99], v146 offset:50176
	ds_read_b128 v[100:103], v146 offset:51200
	ds_read_b128 v[104:107], v146 offset:52224
	ds_read_b128 v[108:111], v146 offset:53248
	ds_read_b128 v[112:115], v146 offset:54272
	ds_read_b128 v[116:119], v146 offset:55296
	ds_read_b128 v[120:123], v146 offset:56320
	global_load_lds_dwordx4 v[42:43], off
	v_lshl_add_u64 v[42:43], v[58:59], 0, s[38:39]
	s_mov_b32 m0, s82
	s_add_i32 s7, s34, s87
	global_load_lds_dwordx4 v[42:43], off
	v_lshl_add_u64 v[42:43], s[78:79], 0, v[132:133]
	s_mov_b32 m0, s7
	s_add_i32 s8, s7, 0x2000
	v_lshl_add_u64 v[42:43], s[78:79], 0, v[128:129]
	s_mov_b32 m0, s8
	s_nop 0
	v_lshl_add_u64 v[42:43], v[60:61], 0, s[38:39]
	s_mov_b32 m0, s92
	s_nop 0
	global_load_lds_dwordx4 v[42:43], off
	v_lshl_add_u64 v[42:43], v[62:63], 0, s[38:39]
	s_mov_b32 m0, s93
	s_nop 0
	global_load_lds_dwordx4 v[42:43], off
	s_waitcnt vmcnt(6)
	s_waitcnt lgkmcnt(0)
	s_barrier
	s_setprio 1
	s_waitcnt lgkmcnt(0)
	v_mfma_f32_16x16x32_bf16 v[88:91], v[10:13], v[92:95], v[88:91]
	v_mfma_f32_16x16x32_bf16 v[42:45], v[80:83], v[92:95], v[44:47]
	v_mfma_f32_16x16x32_bf16 v[52:55], v[10:13], v[100:103], v[52:55]
	v_mfma_f32_16x16x32_bf16 v[64:67], v[80:83], v[100:103], v[64:67]
	v_mfma_f32_16x16x32_bf16 v[68:71], v[10:13], v[108:111], v[68:71]
	v_mfma_f32_16x16x32_bf16 v[72:75], v[80:83], v[108:111], v[72:75]
	v_mfma_f32_16x16x32_bf16 v[2:5], v[10:13], v[116:119], v[2:5]
	v_mfma_f32_16x16x32_bf16 v[6:9], v[80:83], v[116:119], v[6:9]
	v_mfma_f32_16x16x32_bf16 v[88:91], v[76:79], v[96:99], v[88:91]
	v_mfma_f32_16x16x32_bf16 v[42:45], v[84:87], v[96:99], v[42:45]
	v_mfma_f32_16x16x32_bf16 v[52:55], v[76:79], v[104:107], v[52:55]
	v_mfma_f32_16x16x32_bf16 v[64:67], v[84:87], v[104:107], v[64:67]
	v_mfma_f32_16x16x32_bf16 v[68:71], v[76:79], v[112:115], v[68:71]
	v_mfma_f32_16x16x32_bf16 v[72:75], v[84:87], v[112:115], v[72:75]
	v_mfma_f32_16x16x32_bf16 v[2:5], v[76:79], v[120:123], v[2:5]
	v_mfma_f32_16x16x32_bf16 v[6:9], v[84:87], v[120:123], v[6:9]
	s_setprio 0
	s_barrier
	ds_read_b128 v[10:13], v148
	ds_read_b128 v[76:79], v148 offset:1024
	ds_read_b128 v[80:83], v148 offset:2048
	ds_read_b128 v[84:87], v148 offset:3072
	s_add_u32 s78, s74, 0x40180
	s_addc_u32 s79, s75, 0
	s_mov_b32 m0, s73
	v_lshl_add_u64 v[46:47], s[78:79], 0, v[134:135]
	ds_read_b128 v[92:95], v146
	ds_read_b128 v[96:99], v146 offset:1024
	ds_read_b128 v[100:103], v146 offset:2048
	ds_read_b128 v[104:107], v146 offset:3072
	ds_read_b128 v[108:111], v146 offset:4096
	ds_read_b128 v[112:115], v146 offset:5120
	ds_read_b128 v[116:119], v146 offset:6144
	ds_read_b128 v[120:123], v146 offset:7168
	global_load_lds_dwordx4 v[46:47], off
	v_lshl_add_u64 v[46:47], s[78:79], 0, v[130:131]
	s_mov_b32 m0, s65
	s_nop 0
	global_load_lds_dwordx4 v[46:47], off
	s_waitcnt vmcnt(6)
	s_waitcnt lgkmcnt(0)
	s_barrier
	s_setprio 1
	s_waitcnt lgkmcnt(0)
	v_mfma_f32_16x16x32_bf16 v[46:49], v[10:13], v[92:95], v[48:51]
	v_mfma_f32_16x16x32_bf16 v[14:17], v[80:83], v[92:95], v[14:17]
	v_mfma_f32_16x16x32_bf16 v[18:21], v[10:13], v[100:103], v[18:21]
	v_mfma_f32_16x16x32_bf16 v[22:25], v[80:83], v[100:103], v[22:25]
	v_mfma_f32_16x16x32_bf16 v[26:29], v[10:13], v[108:111], v[26:29]
	v_mfma_f32_16x16x32_bf16 v[30:33], v[80:83], v[108:111], v[30:33]
	v_mfma_f32_16x16x32_bf16 v[34:37], v[10:13], v[116:119], v[34:37]
	v_mfma_f32_16x16x32_bf16 v[38:41], v[80:83], v[116:119], v[38:41]
	v_mfma_f32_16x16x32_bf16 v[46:49], v[76:79], v[96:99], v[46:49]
	v_mfma_f32_16x16x32_bf16 v[14:17], v[84:87], v[96:99], v[14:17]
	v_mfma_f32_16x16x32_bf16 v[18:21], v[76:79], v[104:107], v[18:21]
	v_mfma_f32_16x16x32_bf16 v[22:25], v[84:87], v[104:107], v[22:25]
	v_mfma_f32_16x16x32_bf16 v[26:29], v[76:79], v[112:115], v[26:29]
	v_mfma_f32_16x16x32_bf16 v[30:33], v[84:87], v[112:115], v[30:33]
	v_mfma_f32_16x16x32_bf16 v[34:37], v[76:79], v[120:123], v[34:37]
	v_mfma_f32_16x16x32_bf16 v[38:41], v[84:87], v[120:123], v[38:41]
	s_setprio 0
	s_barrier
; #define PG8_STAGE(bufoff, gbase, voff) do { _Pragma("unroll") for (int _i = 0; _i < 2; ++_i) \
;         __builtin_amdgcn_global_load_lds((const unsigned*)((const char*)(gbase) + (voff)[_i]), (PG8_LAS unsigned*)(lds + (bufoff) + ldsw + _i * 8192), 16, 0, 0); } while (0)
; #define PG8_LDA(dst, b, h) do { _Pragma("unroll") for (int m = 0; m < 4; ++m) _Pragma("unroll") for (int k = 0; k < 2; ++k) dst[m][k] = *(const PG8_LAS bf16x8*)(lds + PG8_SA(b, h) + aoff + m * 2048 + k * 1024); } while (0)
; #define PG8_LDB(dst, b, h) do { _Pragma("unroll") for (int n = 0; n < 2; ++n) _Pragma("unroll") for (int k = 0; k < 2; ++k) dst[n][k] = *(const PG8_LAS bf16x8*)(lds + PG8_SB(b, h) + boff + n * 2048 + k * 1024); } while (0)
; #define PG8_WAIT_V(n) asm volatile("s_waitcnt vmcnt(" #n ")" ::: "memory")
; #define PG8_WAIT_L(n) asm volatile("s_waitcnt lgkmcnt(" #n ")" ::: "memory")
; #define PG8_BAR __builtin_amdgcn_s_barrier()
; #define PG8_SCHED __builtin_amdgcn_sched_barrier(0)
; #define PG8_MMA2(ai) PG8_MMA(ai, 0, At, B0)
; #define PG8_MMA2(ai) PG8_MMA(ai, 1, At, B1)
; #define PG8_MMA2(ai) do { PG8_MMA(ai, 0, At, B0); PG8_MMA(ai, 1, At, B1); } while (0)
;     ...
;             PG8_LDB(B0, 0, 0); PG8_LDB(B1, 0, 1); PG8_SCHED; PG8_LDA(At, 0, 0); PG8_STAGE(PG8_SA(1, 1), a1 + hstep, voffA);
;             PG8_WAIT_V(8); PG8_WAIT_L(0); PG8_BAR; PG8_MMA2(0); PG8_BAR; PG8_SCHED;
;             PG8_LDA(At, 0, 1); PG8_STAGE(PG8_SB(0, 0), b2, voffB); PG8_STAGE(PG8_SB(0, 1), b2 + hstep, voffB); PG8_STAGE(PG8_SA(0, 0), a2, voffA);
;             PG8_WAIT_V(8); PG8_WAIT_L(0); PG8_BAR; PG8_MMA2(1); PG8_BAR; PG8_SCHED;
;             PG8_LDB(B0, 1, 0); PG8_LDB(B1, 1, 1); PG8_SCHED; PG8_LDA(At, 1, 0); PG8_STAGE(PG8_SA(0, 1), a2 + hstep, voffA);
;             PG8_WAIT_V(8); PG8_WAIT_L(0); PG8_BAR; PG8_MMA2(0); PG8_BAR; PG8_SCHED;
;             PG8_LDA(At, 1, 1); PG8_STAGE(PG8_SB(1, 0), b3, voffB); PG8_STAGE(PG8_SB(1, 1), b3 + hstep, voffB); PG8_STAGE(PG8_SA(1, 0), a3, voffA);
;             PG8_WAIT_V(8); PG8_WAIT_L(0); PG8_BAR; PG8_MMA2(1); PG8_BAR; PG8_SCHED;
	s_mov_b32 m0, s67
	v_lshl_add_u64 v[50:51], v[56:57], 0, s[40:41]
	s_add_u32 s78, s76, 0x40200
	ds_read_b128 v[92:95], v146 offset:16384
	ds_read_b128 v[96:99], v146 offset:17408
	ds_read_b128 v[100:103], v146 offset:18432
	ds_read_b128 v[104:107], v146 offset:19456
	ds_read_b128 v[108:111], v146 offset:20480
	ds_read_b128 v[112:115], v146 offset:21504
	ds_read_b128 v[116:119], v146 offset:22528
	ds_read_b128 v[120:123], v146 offset:23552
	global_load_lds_dwordx4 v[50:51], off
	v_lshl_add_u64 v[50:51], v[58:59], 0, s[40:41]
	s_mov_b32 m0, s6
	s_addc_u32 s79, s77, 0
	global_load_lds_dwordx4 v[50:51], off
	v_lshl_add_u64 v[50:51], s[78:79], 0, v[132:133]
	s_mov_b32 m0, vcc_lo
	s_nop 0
	v_lshl_add_u64 v[50:51], s[78:79], 0, v[128:129]
	s_mov_b32 m0, vcc_hi
	s_nop 0
	v_lshl_add_u64 v[50:51], v[60:61], 0, s[40:41]
	s_mov_b32 m0, s83
	s_nop 0
	global_load_lds_dwordx4 v[50:51], off
	v_lshl_add_u64 v[50:51], v[62:63], 0, s[40:41]
	s_mov_b32 m0, s89
	s_nop 0
	global_load_lds_dwordx4 v[50:51], off
	s_waitcnt vmcnt(6)
	s_waitcnt lgkmcnt(0)
	s_barrier
	s_setprio 1
	s_waitcnt lgkmcnt(0)
	v_mfma_f32_16x16x32_bf16 v[88:91], v[10:13], v[92:95], v[88:91]
	v_mfma_f32_16x16x32_bf16 v[42:45], v[80:83], v[92:95], v[42:45]
	v_mfma_f32_16x16x32_bf16 v[50:53], v[10:13], v[100:103], v[52:55]
	v_mfma_f32_16x16x32_bf16 v[64:67], v[80:83], v[100:103], v[64:67]
	v_mfma_f32_16x16x32_bf16 v[68:71], v[10:13], v[108:111], v[68:71]
	v_mfma_f32_16x16x32_bf16 v[72:75], v[80:83], v[108:111], v[72:75]
	v_mfma_f32_16x16x32_bf16 v[2:5], v[10:13], v[116:119], v[2:5]
	v_mfma_f32_16x16x32_bf16 v[6:9], v[80:83], v[116:119], v[6:9]
	v_mfma_f32_16x16x32_bf16 v[88:91], v[76:79], v[96:99], v[88:91]
	v_mfma_f32_16x16x32_bf16 v[42:45], v[84:87], v[96:99], v[42:45]
	v_mfma_f32_16x16x32_bf16 v[50:53], v[76:79], v[104:107], v[50:53]
	v_mfma_f32_16x16x32_bf16 v[64:67], v[84:87], v[104:107], v[64:67]
	v_mfma_f32_16x16x32_bf16 v[68:71], v[76:79], v[112:115], v[68:71]
	v_mfma_f32_16x16x32_bf16 v[72:75], v[84:87], v[112:115], v[72:75]
	v_mfma_f32_16x16x32_bf16 v[2:5], v[76:79], v[120:123], v[2:5]
	v_mfma_f32_16x16x32_bf16 v[6:9], v[84:87], v[120:123], v[6:9]
	s_setprio 0
	s_barrier
	ds_read_b128 v[10:13], v0
	ds_read_b128 v[76:79], v0 offset:1024
	ds_read_b128 v[80:83], v0 offset:2048
	ds_read_b128 v[84:87], v0 offset:3072
	s_add_u32 s78, s74, 0x40200
	s_addc_u32 s79, s75, 0
	s_mov_b32 m0, s90
	v_lshl_add_u64 v[54:55], s[78:79], 0, v[134:135]
	ds_read_b128 v[92:95], v146 offset:32768
	ds_read_b128 v[96:99], v146 offset:33792
	ds_read_b128 v[100:103], v146 offset:34816
	ds_read_b128 v[104:107], v146 offset:35840
	ds_read_b128 v[108:111], v146 offset:36864
	ds_read_b128 v[112:115], v146 offset:37888
	ds_read_b128 v[116:119], v146 offset:38912
	ds_read_b128 v[120:123], v146 offset:39936
	global_load_lds_dwordx4 v[54:55], off
	v_lshl_add_u64 v[54:55], s[78:79], 0, v[130:131]
	s_mov_b32 m0, s91
	s_nop 0
	global_load_lds_dwordx4 v[54:55], off
	s_waitcnt vmcnt(6)
	s_waitcnt lgkmcnt(0)
	s_barrier
	s_setprio 1
	s_waitcnt lgkmcnt(0)
	v_mfma_f32_16x16x32_bf16 v[46:49], v[10:13], v[92:95], v[46:49]
	v_mfma_f32_16x16x32_bf16 v[14:17], v[80:83], v[92:95], v[14:17]
	v_mfma_f32_16x16x32_bf16 v[18:21], v[10:13], v[100:103], v[18:21]
	v_mfma_f32_16x16x32_bf16 v[22:25], v[80:83], v[100:103], v[22:25]
	v_mfma_f32_16x16x32_bf16 v[26:29], v[10:13], v[108:111], v[26:29]
	v_mfma_f32_16x16x32_bf16 v[30:33], v[80:83], v[108:111], v[30:33]
	v_mfma_f32_16x16x32_bf16 v[34:37], v[10:13], v[116:119], v[34:37]
	v_mfma_f32_16x16x32_bf16 v[38:41], v[80:83], v[116:119], v[38:41]
	v_mfma_f32_16x16x32_bf16 v[46:49], v[76:79], v[96:99], v[46:49]
	v_mfma_f32_16x16x32_bf16 v[14:17], v[84:87], v[96:99], v[14:17]
	v_mfma_f32_16x16x32_bf16 v[18:21], v[76:79], v[104:107], v[18:21]
	v_mfma_f32_16x16x32_bf16 v[22:25], v[84:87], v[104:107], v[22:25]
	v_mfma_f32_16x16x32_bf16 v[26:29], v[76:79], v[112:115], v[26:29]
	v_mfma_f32_16x16x32_bf16 v[30:33], v[84:87], v[112:115], v[30:33]
	v_mfma_f32_16x16x32_bf16 v[34:37], v[76:79], v[120:123], v[34:37]
	v_mfma_f32_16x16x32_bf16 v[38:41], v[84:87], v[120:123], v[38:41]
	s_setprio 0
	s_barrier
	s_mov_b32 m0, s9
	v_lshl_add_u64 v[54:55], v[56:57], 0, s[42:43]
	s_add_u32 s78, s76, 0x40280
	ds_read_b128 v[92:95], v146 offset:49152
	ds_read_b128 v[96:99], v146 offset:50176
	ds_read_b128 v[100:103], v146 offset:51200
	ds_read_b128 v[104:107], v146 offset:52224
	ds_read_b128 v[108:111], v146 offset:53248
	ds_read_b128 v[112:115], v146 offset:54272
	ds_read_b128 v[116:119], v146 offset:55296
	ds_read_b128 v[120:123], v146 offset:56320
	global_load_lds_dwordx4 v[54:55], off
	v_lshl_add_u64 v[54:55], v[58:59], 0, s[42:43]
	s_mov_b32 m0, s82
	s_addc_u32 s79, s77, 0
	global_load_lds_dwordx4 v[54:55], off
	v_lshl_add_u64 v[54:55], s[78:79], 0, v[132:133]
	s_mov_b32 m0, s7
	s_nop 0
	v_lshl_add_u64 v[54:55], s[78:79], 0, v[128:129]
	s_mov_b32 m0, s8
	s_nop 0
	v_lshl_add_u64 v[54:55], v[60:61], 0, s[42:43]
	s_mov_b32 m0, s92
	s_nop 0
	global_load_lds_dwordx4 v[54:55], off
	v_lshl_add_u64 v[54:55], v[62:63], 0, s[42:43]
	s_mov_b32 m0, s93
	s_nop 0
	global_load_lds_dwordx4 v[54:55], off
	s_waitcnt vmcnt(6)
	s_waitcnt lgkmcnt(0)
	s_barrier
; #define PG8_STAGE(bufoff, gbase, voff) do { _Pragma("unroll") for (int _i = 0; _i < 2; ++_i) \
;         __builtin_amdgcn_global_load_lds((const unsigned*)((const char*)(gbase) + (voff)[_i]), (PG8_LAS unsigned*)(lds + (bufoff) + ldsw + _i * 8192), 16, 0, 0); } while (0)
; #define PG8_LDA(dst, b, h) do { _Pragma("unroll") for (int m = 0; m < 4; ++m) _Pragma("unroll") for (int k = 0; k < 2; ++k) dst[m][k] = *(const PG8_LAS bf16x8*)(lds + PG8_SA(b, h) + aoff + m * 2048 + k * 1024); } while (0)
; #define PG8_LDB(dst, b, h) do { _Pragma("unroll") for (int n = 0; n < 2; ++n) _Pragma("unroll") for (int k = 0; k < 2; ++k) dst[n][k] = *(const PG8_LAS bf16x8*)(lds + PG8_SB(b, h) + boff + n * 2048 + k * 1024); } while (0)
; #define PG8_WAIT_V(n) asm volatile("s_waitcnt vmcnt(" #n ")" ::: "memory")
; #define PG8_WAIT_L(n) asm volatile("s_waitcnt lgkmcnt(" #n ")" ::: "memory")
; #define PG8_BAR __builtin_amdgcn_s_barrier()
; #define PG8_SCHED __builtin_amdgcn_sched_barrier(0)
; #define PG8_MMA2(ai) PG8_MMA(ai, 0, At, B0)
; #define PG8_MMA2(ai) PG8_MMA(ai, 1, At, B1)
; #define PG8_MMA2(ai) do { PG8_MMA(ai, 0, At, B0); PG8_MMA(ai, 1, At, B1); } while (0)
;     ...
;             PG8_LDB(B0, 0, 0); PG8_LDB(B1, 0, 1); PG8_SCHED; PG8_LDA(At, 0, 0); PG8_STAGE(PG8_SA(1, 1), a1 + hstep, voffA);
;             PG8_WAIT_V(8); PG8_WAIT_L(0); PG8_BAR; PG8_MMA2(0); PG8_BAR; PG8_SCHED;
;             PG8_LDA(At, 0, 1); PG8_STAGE(PG8_SB(0, 0), b2, voffB); PG8_STAGE(PG8_SB(0, 1), b2 + hstep, voffB); PG8_STAGE(PG8_SA(0, 0), a2, voffA);
;             PG8_WAIT_V(8); PG8_WAIT_L(0); PG8_BAR; PG8_MMA2(1); PG8_BAR; PG8_SCHED;
;             PG8_LDB(B0, 1, 0); PG8_LDB(B1, 1, 1); PG8_SCHED; PG8_LDA(At, 1, 0); PG8_STAGE(PG8_SA(0, 1), a2 + hstep, voffA);
;             PG8_WAIT_V(8); PG8_WAIT_L(0); PG8_BAR; PG8_MMA2(0); PG8_BAR; PG8_SCHED;
;             PG8_LDA(At, 1, 1); PG8_STAGE(PG8_SB(1, 0), b3, voffB); PG8_STAGE(PG8_SB(1, 1), b3 + hstep, voffB); PG8_STAGE(PG8_SA(1, 0), a3, voffA);
;             PG8_WAIT_V(8); PG8_WAIT_L(0); PG8_BAR; PG8_MMA2(1); PG8_BAR; PG8_SCHED;
	s_setprio 1
	s_waitcnt lgkmcnt(0)
	v_mfma_f32_16x16x32_bf16 v[88:91], v[10:13], v[92:95], v[88:91]
	v_mfma_f32_16x16x32_bf16 v[42:45], v[80:83], v[92:95], v[42:45]
	v_mfma_f32_16x16x32_bf16 v[50:53], v[10:13], v[100:103], v[50:53]
	v_mfma_f32_16x16x32_bf16 v[64:67], v[80:83], v[100:103], v[64:67]
	v_mfma_f32_16x16x32_bf16 v[68:71], v[10:13], v[108:111], v[68:71]
	v_mfma_f32_16x16x32_bf16 v[72:75], v[80:83], v[108:111], v[72:75]
	v_mfma_f32_16x16x32_bf16 v[2:5], v[10:13], v[116:119], v[2:5]
	v_mfma_f32_16x16x32_bf16 v[6:9], v[80:83], v[116:119], v[6:9]
	v_mfma_f32_16x16x32_bf16 v[88:91], v[76:79], v[96:99], v[88:91]
	v_mfma_f32_16x16x32_bf16 v[42:45], v[84:87], v[96:99], v[42:45]
	v_mfma_f32_16x16x32_bf16 v[50:53], v[76:79], v[104:107], v[50:53]
	v_mfma_f32_16x16x32_bf16 v[64:67], v[84:87], v[104:107], v[64:67]
	v_mfma_f32_16x16x32_bf16 v[68:71], v[76:79], v[112:115], v[68:71]
	v_mfma_f32_16x16x32_bf16 v[72:75], v[84:87], v[112:115], v[72:75]
	v_mfma_f32_16x16x32_bf16 v[2:5], v[76:79], v[120:123], v[2:5]
	v_mfma_f32_16x16x32_bf16 v[6:9], v[84:87], v[120:123], v[6:9]
	s_setprio 0
	s_barrier
	ds_read_b128 v[10:13], v148
	ds_read_b128 v[76:79], v148 offset:1024
	ds_read_b128 v[80:83], v148 offset:2048
	ds_read_b128 v[84:87], v148 offset:3072
	s_add_u32 s78, s74, 0x40280
	s_addc_u32 s79, s75, 0
	s_mov_b32 m0, s73
	v_lshl_add_u64 v[54:55], s[78:79], 0, v[134:135]
	ds_read_b128 v[92:95], v146
	ds_read_b128 v[96:99], v146 offset:1024
	ds_read_b128 v[100:103], v146 offset:2048
	ds_read_b128 v[104:107], v146 offset:3072
	ds_read_b128 v[108:111], v146 offset:4096
	ds_read_b128 v[112:115], v146 offset:5120
	ds_read_b128 v[116:119], v146 offset:6144
	ds_read_b128 v[120:123], v146 offset:7168
	global_load_lds_dwordx4 v[54:55], off
	v_lshl_add_u64 v[54:55], s[78:79], 0, v[130:131]
	s_mov_b32 m0, s65
	s_nop 0
	global_load_lds_dwordx4 v[54:55], off
	s_waitcnt vmcnt(6)
	s_waitcnt lgkmcnt(0)
	s_barrier
	s_setprio 1
	s_waitcnt lgkmcnt(0)
	v_mfma_f32_16x16x32_bf16 v[46:49], v[10:13], v[92:95], v[46:49]
	v_mfma_f32_16x16x32_bf16 v[14:17], v[80:83], v[92:95], v[14:17]
	v_mfma_f32_16x16x32_bf16 v[18:21], v[10:13], v[100:103], v[18:21]
	v_mfma_f32_16x16x32_bf16 v[22:25], v[80:83], v[100:103], v[22:25]
	v_mfma_f32_16x16x32_bf16 v[26:29], v[10:13], v[108:111], v[26:29]
	v_mfma_f32_16x16x32_bf16 v[30:33], v[80:83], v[108:111], v[30:33]
	v_mfma_f32_16x16x32_bf16 v[34:37], v[10:13], v[116:119], v[34:37]
	v_mfma_f32_16x16x32_bf16 v[38:41], v[80:83], v[116:119], v[38:41]
	v_mfma_f32_16x16x32_bf16 v[46:49], v[76:79], v[96:99], v[46:49]
	v_mfma_f32_16x16x32_bf16 v[14:17], v[84:87], v[96:99], v[14:17]
	v_mfma_f32_16x16x32_bf16 v[18:21], v[76:79], v[104:107], v[18:21]
	v_mfma_f32_16x16x32_bf16 v[22:25], v[84:87], v[104:107], v[22:25]
	v_mfma_f32_16x16x32_bf16 v[26:29], v[76:79], v[112:115], v[26:29]
	v_mfma_f32_16x16x32_bf16 v[30:33], v[84:87], v[112:115], v[30:33]
	v_mfma_f32_16x16x32_bf16 v[34:37], v[76:79], v[120:123], v[34:37]
	v_mfma_f32_16x16x32_bf16 v[38:41], v[84:87], v[120:123], v[38:41]
	s_setprio 0
	s_barrier
	s_mov_b32 m0, s67
	v_lshl_add_u64 v[54:55], v[56:57], 0, s[44:45]
	s_add_u32 s78, s76, 0x40300
	ds_read_b128 v[92:95], v146 offset:16384
	ds_read_b128 v[96:99], v146 offset:17408
	ds_read_b128 v[100:103], v146 offset:18432
	ds_read_b128 v[104:107], v146 offset:19456
	ds_read_b128 v[108:111], v146 offset:20480
	ds_read_b128 v[112:115], v146 offset:21504
	ds_read_b128 v[116:119], v146 offset:22528
	ds_read_b128 v[120:123], v146 offset:23552
	global_load_lds_dwordx4 v[54:55], off
	v_lshl_add_u64 v[54:55], v[58:59], 0, s[44:45]
	s_mov_b32 m0, s6
	s_addc_u32 s79, s77, 0
	global_load_lds_dwordx4 v[54:55], off
	v_lshl_add_u64 v[54:55], s[78:79], 0, v[132:133]
	s_mov_b32 m0, vcc_lo
	s_nop 0
	v_lshl_add_u64 v[54:55], s[78:79], 0, v[128:129]
	s_mov_b32 m0, vcc_hi
	s_nop 0
	v_lshl_add_u64 v[54:55], v[60:61], 0, s[44:45]
	s_mov_b32 m0, s83
	s_nop 0
	global_load_lds_dwordx4 v[54:55], off
	v_lshl_add_u64 v[54:55], v[62:63], 0, s[44:45]
	s_mov_b32 m0, s89
	s_nop 0
	global_load_lds_dwordx4 v[54:55], off
	s_waitcnt vmcnt(6)
	s_waitcnt lgkmcnt(0)
	s_barrier
	s_setprio 1
	s_waitcnt lgkmcnt(0)
	v_mfma_f32_16x16x32_bf16 v[88:91], v[10:13], v[92:95], v[88:91]
	v_mfma_f32_16x16x32_bf16 v[42:45], v[80:83], v[92:95], v[42:45]
	v_mfma_f32_16x16x32_bf16 v[50:53], v[10:13], v[100:103], v[50:53]
	v_mfma_f32_16x16x32_bf16 v[64:67], v[80:83], v[100:103], v[64:67]
	v_mfma_f32_16x16x32_bf16 v[68:71], v[10:13], v[108:111], v[68:71]
	v_mfma_f32_16x16x32_bf16 v[72:75], v[80:83], v[108:111], v[72:75]
	v_mfma_f32_16x16x32_bf16 v[2:5], v[10:13], v[116:119], v[2:5]
	v_mfma_f32_16x16x32_bf16 v[6:9], v[80:83], v[116:119], v[6:9]
	v_mfma_f32_16x16x32_bf16 v[88:91], v[76:79], v[96:99], v[88:91]
	v_mfma_f32_16x16x32_bf16 v[42:45], v[84:87], v[96:99], v[42:45]
	v_mfma_f32_16x16x32_bf16 v[50:53], v[76:79], v[104:107], v[50:53]
	v_mfma_f32_16x16x32_bf16 v[64:67], v[84:87], v[104:107], v[64:67]
	v_mfma_f32_16x16x32_bf16 v[68:71], v[76:79], v[112:115], v[68:71]
	v_mfma_f32_16x16x32_bf16 v[72:75], v[84:87], v[112:115], v[72:75]
	v_mfma_f32_16x16x32_bf16 v[2:5], v[76:79], v[120:123], v[2:5]
	v_mfma_f32_16x16x32_bf16 v[6:9], v[84:87], v[120:123], v[6:9]
	s_setprio 0
	s_barrier
	ds_read_b128 v[10:13], v0
	ds_read_b128 v[76:79], v0 offset:1024
	ds_read_b128 v[80:83], v0 offset:2048
	ds_read_b128 v[84:87], v0 offset:3072
	s_add_u32 s78, s74, 0x40300
	s_addc_u32 s79, s75, 0
	s_mov_b32 m0, s90
	v_lshl_add_u64 v[54:55], s[78:79], 0, v[134:135]
	ds_read_b128 v[92:95], v146 offset:32768
	ds_read_b128 v[96:99], v146 offset:33792
	ds_read_b128 v[100:103], v146 offset:34816
	ds_read_b128 v[104:107], v146 offset:35840
	ds_read_b128 v[108:111], v146 offset:36864
	ds_read_b128 v[112:115], v146 offset:37888
	ds_read_b128 v[116:119], v146 offset:38912
	ds_read_b128 v[120:123], v146 offset:39936
	global_load_lds_dwordx4 v[54:55], off
	v_lshl_add_u64 v[54:55], s[78:79], 0, v[130:131]
	s_mov_b32 m0, s91
	s_nop 0
	global_load_lds_dwordx4 v[54:55], off
	s_waitcnt vmcnt(6)
	s_waitcnt lgkmcnt(0)
	s_barrier
; #define PG8_STAGE(bufoff, gbase, voff) do { _Pragma("unroll") for (int _i = 0; _i < 2; ++_i) \
;         __builtin_amdgcn_global_load_lds((const unsigned*)((const char*)(gbase) + (voff)[_i]), (PG8_LAS unsigned*)(lds + (bufoff) + ldsw + _i * 8192), 16, 0, 0); } while (0)
; #define PG8_LDA(dst, b, h) do { _Pragma("unroll") for (int m = 0; m < 4; ++m) _Pragma("unroll") for (int k = 0; k < 2; ++k) dst[m][k] = *(const PG8_LAS bf16x8*)(lds + PG8_SA(b, h) + aoff + m * 2048 + k * 1024); } while (0)
; #define PG8_LDB(dst, b, h) do { _Pragma("unroll") for (int n = 0; n < 2; ++n) _Pragma("unroll") for (int k = 0; k < 2; ++k) dst[n][k] = *(const PG8_LAS bf16x8*)(lds + PG8_SB(b, h) + boff + n * 2048 + k * 1024); } while (0)
; #define PG8_WAIT_V(n) asm volatile("s_waitcnt vmcnt(" #n ")" ::: "memory")
; #define PG8_WAIT_L(n) asm volatile("s_waitcnt lgkmcnt(" #n ")" ::: "memory")
; #define PG8_BAR __builtin_amdgcn_s_barrier()
; #define PG8_SCHED __builtin_amdgcn_sched_barrier(0)
; #define PG8_MMA2(ai) PG8_MMA(ai, 0, At, B0)
; #define PG8_MMA2(ai) PG8_MMA(ai, 1, At, B1)
; #define PG8_MMA2(ai) do { PG8_MMA(ai, 0, At, B0); PG8_MMA(ai, 1, At, B1); } while (0)
;     ...
;             PG8_LDB(B0, 0, 0); PG8_LDB(B1, 0, 1); PG8_SCHED; PG8_LDA(At, 0, 0); PG8_STAGE(PG8_SA(1, 1), a1 + hstep, voffA);
;             PG8_WAIT_V(8); PG8_WAIT_L(0); PG8_BAR; PG8_MMA2(0); PG8_BAR; PG8_SCHED;
;             PG8_LDA(At, 0, 1); PG8_STAGE(PG8_SB(0, 0), b2, voffB); PG8_STAGE(PG8_SB(0, 1), b2 + hstep, voffB); PG8_STAGE(PG8_SA(0, 0), a2, voffA);
;             PG8_WAIT_V(8); PG8_WAIT_L(0); PG8_BAR; PG8_MMA2(1); PG8_BAR; PG8_SCHED;
;             PG8_LDB(B0, 1, 0); PG8_LDB(B1, 1, 1); PG8_SCHED; PG8_LDA(At, 1, 0); PG8_STAGE(PG8_SA(0, 1), a2 + hstep, voffA);
;             PG8_WAIT_V(8); PG8_WAIT_L(0); PG8_BAR; PG8_MMA2(0); PG8_BAR; PG8_SCHED;
;             PG8_LDA(At, 1, 1); PG8_STAGE(PG8_SB(1, 0), b3, voffB); PG8_STAGE(PG8_SB(1, 1), b3 + hstep, voffB); PG8_STAGE(PG8_SA(1, 0), a3, voffA);
;             PG8_WAIT_V(8); PG8_WAIT_L(0); PG8_BAR; PG8_MMA2(1); PG8_BAR; PG8_SCHED;
	s_setprio 1
	s_waitcnt lgkmcnt(0)
	v_mfma_f32_16x16x32_bf16 v[46:49], v[10:13], v[92:95], v[46:49]
	v_mfma_f32_16x16x32_bf16 v[14:17], v[80:83], v[92:95], v[14:17]
	v_mfma_f32_16x16x32_bf16 v[18:21], v[10:13], v[100:103], v[18:21]
	v_mfma_f32_16x16x32_bf16 v[22:25], v[80:83], v[100:103], v[22:25]
	v_mfma_f32_16x16x32_bf16 v[26:29], v[10:13], v[108:111], v[26:29]
	v_mfma_f32_16x16x32_bf16 v[30:33], v[80:83], v[108:111], v[30:33]
	v_mfma_f32_16x16x32_bf16 v[34:37], v[10:13], v[116:119], v[34:37]
	v_mfma_f32_16x16x32_bf16 v[38:41], v[80:83], v[116:119], v[38:41]
	v_mfma_f32_16x16x32_bf16 v[46:49], v[76:79], v[96:99], v[46:49]
	v_mfma_f32_16x16x32_bf16 v[14:17], v[84:87], v[96:99], v[14:17]
	v_mfma_f32_16x16x32_bf16 v[18:21], v[76:79], v[104:107], v[18:21]
	v_mfma_f32_16x16x32_bf16 v[22:25], v[84:87], v[104:107], v[22:25]
	v_mfma_f32_16x16x32_bf16 v[26:29], v[76:79], v[112:115], v[26:29]
	v_mfma_f32_16x16x32_bf16 v[30:33], v[84:87], v[112:115], v[30:33]
	v_mfma_f32_16x16x32_bf16 v[34:37], v[76:79], v[120:123], v[34:37]
	v_mfma_f32_16x16x32_bf16 v[38:41], v[84:87], v[120:123], v[38:41]
	s_setprio 0
	s_barrier
	s_mov_b32 m0, s9
	v_lshl_add_u64 v[54:55], v[56:57], 0, s[46:47]
	s_add_u32 s78, s76, 0x40380
	ds_read_b128 v[92:95], v146 offset:49152
	ds_read_b128 v[96:99], v146 offset:50176
	ds_read_b128 v[100:103], v146 offset:51200
	ds_read_b128 v[104:107], v146 offset:52224
	ds_read_b128 v[108:111], v146 offset:53248
	ds_read_b128 v[112:115], v146 offset:54272
	ds_read_b128 v[116:119], v146 offset:55296
	ds_read_b128 v[120:123], v146 offset:56320
	global_load_lds_dwordx4 v[54:55], off
	v_lshl_add_u64 v[54:55], v[58:59], 0, s[46:47]
	s_mov_b32 m0, s82
	s_addc_u32 s79, s77, 0
	global_load_lds_dwordx4 v[54:55], off
	v_lshl_add_u64 v[54:55], s[78:79], 0, v[132:133]
	s_mov_b32 m0, s7
	s_nop 0
	v_lshl_add_u64 v[54:55], s[78:79], 0, v[128:129]
	s_mov_b32 m0, s8
	s_nop 0
	v_lshl_add_u64 v[54:55], v[60:61], 0, s[46:47]
	s_mov_b32 m0, s92
	s_nop 0
	global_load_lds_dwordx4 v[54:55], off
	v_lshl_add_u64 v[54:55], v[62:63], 0, s[46:47]
	s_mov_b32 m0, s93
	s_nop 0
	global_load_lds_dwordx4 v[54:55], off
	s_waitcnt vmcnt(6)
	s_waitcnt lgkmcnt(0)
	s_barrier
	s_setprio 1
	s_waitcnt lgkmcnt(0)
	v_mfma_f32_16x16x32_bf16 v[88:91], v[10:13], v[92:95], v[88:91]
	v_mfma_f32_16x16x32_bf16 v[42:45], v[80:83], v[92:95], v[42:45]
	v_mfma_f32_16x16x32_bf16 v[50:53], v[10:13], v[100:103], v[50:53]
	v_mfma_f32_16x16x32_bf16 v[64:67], v[80:83], v[100:103], v[64:67]
	v_mfma_f32_16x16x32_bf16 v[68:71], v[10:13], v[108:111], v[68:71]
	v_mfma_f32_16x16x32_bf16 v[72:75], v[80:83], v[108:111], v[72:75]
	v_mfma_f32_16x16x32_bf16 v[2:5], v[10:13], v[116:119], v[2:5]
	v_mfma_f32_16x16x32_bf16 v[6:9], v[80:83], v[116:119], v[6:9]
	v_mfma_f32_16x16x32_bf16 v[88:91], v[76:79], v[96:99], v[88:91]
	v_mfma_f32_16x16x32_bf16 v[42:45], v[84:87], v[96:99], v[42:45]
	v_mfma_f32_16x16x32_bf16 v[50:53], v[76:79], v[104:107], v[50:53]
	v_mfma_f32_16x16x32_bf16 v[64:67], v[84:87], v[104:107], v[64:67]
	v_mfma_f32_16x16x32_bf16 v[68:71], v[76:79], v[112:115], v[68:71]
	v_mfma_f32_16x16x32_bf16 v[72:75], v[84:87], v[112:115], v[72:75]
	v_mfma_f32_16x16x32_bf16 v[2:5], v[76:79], v[120:123], v[2:5]
	v_mfma_f32_16x16x32_bf16 v[6:9], v[84:87], v[120:123], v[6:9]
	s_setprio 0
	s_barrier
	ds_read_b128 v[10:13], v148
	ds_read_b128 v[76:79], v148 offset:1024
	ds_read_b128 v[80:83], v148 offset:2048
	ds_read_b128 v[84:87], v148 offset:3072
	s_add_u32 s78, s74, 0x40380
	s_addc_u32 s79, s75, 0
	s_mov_b32 m0, s73
	v_lshl_add_u64 v[54:55], s[78:79], 0, v[134:135]
	ds_read_b128 v[92:95], v146
	ds_read_b128 v[96:99], v146 offset:1024
	ds_read_b128 v[100:103], v146 offset:2048
	ds_read_b128 v[104:107], v146 offset:3072
	ds_read_b128 v[108:111], v146 offset:4096
	ds_read_b128 v[112:115], v146 offset:5120
	ds_read_b128 v[116:119], v146 offset:6144
	ds_read_b128 v[120:123], v146 offset:7168
	global_load_lds_dwordx4 v[54:55], off
	v_lshl_add_u64 v[54:55], s[78:79], 0, v[130:131]
	s_mov_b32 m0, s65
	s_nop 0
	global_load_lds_dwordx4 v[54:55], off
	s_waitcnt vmcnt(6)
	s_waitcnt lgkmcnt(0)
	s_barrier
	s_setprio 1
	s_waitcnt lgkmcnt(0)
	v_mfma_f32_16x16x32_bf16 v[46:49], v[10:13], v[92:95], v[46:49]
	v_mfma_f32_16x16x32_bf16 v[14:17], v[80:83], v[92:95], v[14:17]
	v_mfma_f32_16x16x32_bf16 v[18:21], v[10:13], v[100:103], v[18:21]
	v_mfma_f32_16x16x32_bf16 v[22:25], v[80:83], v[100:103], v[22:25]
	v_mfma_f32_16x16x32_bf16 v[26:29], v[10:13], v[108:111], v[26:29]
	v_mfma_f32_16x16x32_bf16 v[30:33], v[80:83], v[108:111], v[30:33]
	v_mfma_f32_16x16x32_bf16 v[34:37], v[10:13], v[116:119], v[34:37]
	v_mfma_f32_16x16x32_bf16 v[38:41], v[80:83], v[116:119], v[38:41]
	v_mfma_f32_16x16x32_bf16 v[46:49], v[76:79], v[96:99], v[46:49]
	v_mfma_f32_16x16x32_bf16 v[14:17], v[84:87], v[96:99], v[14:17]
	v_mfma_f32_16x16x32_bf16 v[18:21], v[76:79], v[104:107], v[18:21]
	v_mfma_f32_16x16x32_bf16 v[22:25], v[84:87], v[104:107], v[22:25]
	v_mfma_f32_16x16x32_bf16 v[26:29], v[76:79], v[112:115], v[26:29]
	v_mfma_f32_16x16x32_bf16 v[30:33], v[84:87], v[112:115], v[30:33]
	v_mfma_f32_16x16x32_bf16 v[34:37], v[76:79], v[120:123], v[34:37]
	v_mfma_f32_16x16x32_bf16 v[92:95], v[84:87], v[120:123], v[38:41]
	s_setprio 0
	s_barrier
; #define PG8_STAGE(bufoff, gbase, voff) do { _Pragma("unroll") for (int _i = 0; _i < 2; ++_i) \
;         __builtin_amdgcn_global_load_lds((const unsigned*)((const char*)(gbase) + (voff)[_i]), (PG8_LAS unsigned*)(lds + (bufoff) + ldsw + _i * 8192), 16, 0, 0); } while (0)
; #define PG8_LDA(dst, b, h) do { _Pragma("unroll") for (int m = 0; m < 4; ++m) _Pragma("unroll") for (int k = 0; k < 2; ++k) dst[m][k] = *(const PG8_LAS bf16x8*)(lds + PG8_SA(b, h) + aoff + m * 2048 + k * 1024); } while (0)
; #define PG8_LDB(dst, b, h) do { _Pragma("unroll") for (int n = 0; n < 2; ++n) _Pragma("unroll") for (int k = 0; k < 2; ++k) dst[n][k] = *(const PG8_LAS bf16x8*)(lds + PG8_SB(b, h) + boff + n * 2048 + k * 1024); } while (0)
; #define PG8_WAIT_V(n) asm volatile("s_waitcnt vmcnt(" #n ")" ::: "memory")
; #define PG8_WAIT_L(n) asm volatile("s_waitcnt lgkmcnt(" #n ")" ::: "memory")
; #define PG8_BAR __builtin_amdgcn_s_barrier()
; #define PG8_SCHED __builtin_amdgcn_sched_barrier(0)
; #define PG8_MMA2(ai) PG8_MMA(ai, 0, At, B0)
; #define PG8_MMA2(ai) PG8_MMA(ai, 1, At, B1)
; #define PG8_MMA2(ai) do { PG8_MMA(ai, 0, At, B0); PG8_MMA(ai, 1, At, B1); } while (0)
;     ...
;             PG8_LDA(At, 0, 1); PG8_STAGE(PG8_SB(0, 0), b2, voffB); PG8_STAGE(PG8_SB(0, 1), b2 + hstep, voffB); PG8_STAGE(PG8_SA(0, 0), a2, voffA);
;             PG8_WAIT_V(8); PG8_WAIT_L(0); PG8_BAR; PG8_MMA2(1); PG8_BAR; PG8_SCHED;
;             PG8_LDB(B0, 1, 0); PG8_LDB(B1, 1, 1); PG8_SCHED; PG8_LDA(At, 1, 0); PG8_STAGE(PG8_SA(0, 1), a2 + hstep, voffA);
;             PG8_WAIT_V(8); PG8_WAIT_L(0); PG8_BAR; PG8_MMA2(0); PG8_BAR; PG8_SCHED;
;             PG8_LDA(At, 1, 1); PG8_STAGE(PG8_SB(1, 0), b3, voffB); PG8_STAGE(PG8_SB(1, 1), b3 + hstep, voffB); PG8_STAGE(PG8_SA(1, 0), a3, voffA);
;             PG8_WAIT_V(8); PG8_WAIT_L(0); PG8_BAR; PG8_MMA2(1); PG8_BAR; PG8_SCHED;
	s_mov_b32 m0, s67
	v_lshl_add_u64 v[54:55], v[56:57], 0, s[48:49]
	s_add_u32 s78, s76, 0x40400
	ds_read_b128 v[38:41], v146 offset:16384
	ds_read_b128 v[96:99], v146 offset:17408
	ds_read_b128 v[100:103], v146 offset:18432
	ds_read_b128 v[104:107], v146 offset:19456
	ds_read_b128 v[108:111], v146 offset:20480
	ds_read_b128 v[112:115], v146 offset:21504
	ds_read_b128 v[116:119], v146 offset:22528
	ds_read_b128 v[120:123], v146 offset:23552
	v_lshl_add_u64 v[54:55], v[58:59], 0, s[48:49]
	s_mov_b32 m0, s6
	s_addc_u32 s79, s77, 0
	v_lshl_add_u64 v[54:55], s[78:79], 0, v[132:133]
	s_mov_b32 m0, vcc_lo
	s_nop 0
	global_load_lds_dwordx4 v[54:55], off
	v_lshl_add_u64 v[54:55], s[78:79], 0, v[128:129]
	s_mov_b32 m0, vcc_hi
	s_nop 0
	global_load_lds_dwordx4 v[54:55], off
	v_lshl_add_u64 v[54:55], v[60:61], 0, s[48:49]
	s_mov_b32 m0, s83
	s_nop 0
	global_load_lds_dwordx4 v[54:55], off
	v_lshl_add_u64 v[54:55], v[62:63], 0, s[48:49]
	s_mov_b32 m0, s89
	s_nop 0
	global_load_lds_dwordx4 v[54:55], off
	s_waitcnt vmcnt(6)
	s_waitcnt lgkmcnt(0)
	s_barrier
	s_setprio 1
	s_waitcnt lgkmcnt(0)
	v_mfma_f32_16x16x32_bf16 v[88:91], v[10:13], v[38:41], v[88:91]
	v_mfma_f32_16x16x32_bf16 v[38:41], v[80:83], v[38:41], v[42:45]
	v_mfma_f32_16x16x32_bf16 v[88:91], v[76:79], v[96:99], v[88:91]
	v_mfma_f32_16x16x32_bf16 v[96:99], v[84:87], v[96:99], v[38:41]
	v_mfma_f32_16x16x32_bf16 v[38:41], v[10:13], v[100:103], v[50:53]
	v_mfma_f32_16x16x32_bf16 v[124:127], v[76:79], v[104:107], v[38:41]
	v_mfma_f32_16x16x32_bf16 v[38:41], v[80:83], v[100:103], v[64:67]
	v_mfma_f32_16x16x32_bf16 v[100:103], v[84:87], v[104:107], v[38:41]
	v_mfma_f32_16x16x32_bf16 v[38:41], v[10:13], v[108:111], v[68:71]
	v_mfma_f32_16x16x32_bf16 v[68:71], v[76:79], v[112:115], v[38:41]
	v_mfma_f32_16x16x32_bf16 v[38:41], v[80:83], v[108:111], v[72:75]
	v_mfma_f32_16x16x32_bf16 v[2:5], v[10:13], v[116:119], v[2:5]
	v_mfma_f32_16x16x32_bf16 v[6:9], v[80:83], v[116:119], v[6:9]
	v_mfma_f32_16x16x32_bf16 v[104:107], v[84:87], v[112:115], v[38:41]
	v_mfma_f32_16x16x32_bf16 v[2:5], v[76:79], v[120:123], v[2:5]
	v_mfma_f32_16x16x32_bf16 v[76:79], v[84:87], v[120:123], v[6:9]
	s_setprio 0
	s_barrier
	ds_read_b128 v[80:83], v0
	ds_read_b128 v[84:87], v0 offset:1024
	ds_read_b128 v[108:111], v0 offset:2048
	ds_read_b128 v[112:115], v0 offset:3072
	s_add_u32 s78, s74, 0x40400
	s_addc_u32 s79, s75, 0
	s_mov_b32 m0, s90
	v_lshl_add_u64 v[0:1], s[78:79], 0, v[134:135]
	ds_read_b128 v[6:9], v146 offset:32768
	ds_read_b128 v[10:13], v146 offset:33792
	ds_read_b128 v[38:41], v146 offset:34816
	ds_read_b128 v[42:45], v146 offset:35840
	ds_read_b128 v[116:119], v146 offset:36864
	ds_read_b128 v[120:123], v146 offset:37888
	ds_read_b128 v[140:143], v146 offset:38912
	ds_read_b128 v[150:153], v146 offset:39936
	global_load_lds_dwordx4 v[0:1], off
	v_lshl_add_u64 v[0:1], s[78:79], 0, v[130:131]
	s_mov_b32 m0, s91
	s_nop 0
	global_load_lds_dwordx4 v[0:1], off
	s_waitcnt vmcnt(6)
	s_waitcnt lgkmcnt(0)
	s_barrier
	s_setprio 1
	s_waitcnt lgkmcnt(0)
	v_mfma_f32_16x16x32_bf16 v[46:49], v[80:83], v[6:9], v[46:49]
	v_mfma_f32_16x16x32_bf16 v[6:9], v[108:111], v[6:9], v[14:17]
	v_mfma_f32_16x16x32_bf16 v[64:67], v[112:115], v[10:13], v[6:9]
	v_mfma_f32_16x16x32_bf16 v[6:9], v[80:83], v[38:41], v[18:21]
	v_mfma_f32_16x16x32_bf16 v[52:55], v[84:87], v[42:45], v[6:9]
	v_mfma_f32_16x16x32_bf16 v[6:9], v[108:111], v[38:41], v[22:25]
	v_mfma_f32_16x16x32_bf16 v[72:75], v[84:87], v[10:13], v[46:49]
	v_mfma_f32_16x16x32_bf16 v[48:51], v[112:115], v[42:45], v[6:9]
	v_mfma_f32_16x16x32_bf16 v[6:9], v[80:83], v[116:119], v[26:29]
	v_mfma_f32_16x16x32_bf16 v[44:47], v[84:87], v[120:123], v[6:9]
	v_mfma_f32_16x16x32_bf16 v[6:9], v[108:111], v[116:119], v[30:33]
	v_mfma_f32_16x16x32_bf16 v[40:43], v[112:115], v[120:123], v[6:9]
	v_mfma_f32_16x16x32_bf16 v[6:9], v[80:83], v[140:143], v[34:37]
	v_mfma_f32_16x16x32_bf16 v[36:39], v[84:87], v[150:153], v[6:9]
	v_mfma_f32_16x16x32_bf16 v[6:9], v[108:111], v[140:143], v[92:95]
	v_mfma_f32_16x16x32_bf16 v[32:35], v[112:115], v[150:153], v[6:9]
	s_setprio 0
	s_barrier
	s_mov_b32 m0, s9
	v_lshl_add_u64 v[0:1], v[56:57], 0, s[50:51]
	s_add_u32 s78, s76, 0x40480
	s_nop 1
	ds_read_b128 v[6:9], v146 offset:49152
	ds_read_b128 v[10:13], v146 offset:50176
	ds_read_b128 v[14:17], v146 offset:51200
	ds_read_b128 v[92:95], v146 offset:52224
	ds_read_b128 v[116:119], v146 offset:53248
	ds_read_b128 v[120:123], v146 offset:54272
	ds_read_b128 v[140:143], v146 offset:55296
	ds_read_b128 v[150:153], v146 offset:56320
	v_lshl_add_u64 v[0:1], v[58:59], 0, s[50:51]
	s_mov_b32 m0, s82
	s_addc_u32 s79, s77, 0
	v_lshl_add_u64 v[0:1], s[78:79], 0, v[132:133]
	s_mov_b32 m0, s7
	s_nop 0
	global_load_lds_dwordx4 v[0:1], off
	v_lshl_add_u64 v[0:1], s[78:79], 0, v[128:129]
	s_mov_b32 m0, s8
	s_nop 0
	global_load_lds_dwordx4 v[0:1], off
	v_lshl_add_u64 v[0:1], v[60:61], 0, s[50:51]
	s_mov_b32 m0, s92
	s_nop 0
	global_load_lds_dwordx4 v[0:1], off
	v_lshl_add_u64 v[0:1], v[62:63], 0, s[50:51]
	s_mov_b32 m0, s93
	s_nop 0
	global_load_lds_dwordx4 v[0:1], off
	s_waitcnt vmcnt(6)
	s_waitcnt lgkmcnt(0)
	s_barrier
; #define PG8_STAGE(bufoff, gbase, voff) do { _Pragma("unroll") for (int _i = 0; _i < 2; ++_i) \
;         __builtin_amdgcn_global_load_lds((const unsigned*)((const char*)(gbase) + (voff)[_i]), (PG8_LAS unsigned*)(lds + (bufoff) + ldsw + _i * 8192), 16, 0, 0); } while (0)
; #define PG8_LDA(dst, b, h) do { _Pragma("unroll") for (int m = 0; m < 4; ++m) _Pragma("unroll") for (int k = 0; k < 2; ++k) dst[m][k] = *(const PG8_LAS bf16x8*)(lds + PG8_SA(b, h) + aoff + m * 2048 + k * 1024); } while (0)
; #define PG8_LDB(dst, b, h) do { _Pragma("unroll") for (int n = 0; n < 2; ++n) _Pragma("unroll") for (int k = 0; k < 2; ++k) dst[n][k] = *(const PG8_LAS bf16x8*)(lds + PG8_SB(b, h) + boff + n * 2048 + k * 1024); } while (0)
; #define PG8_WAIT_V(n) asm volatile("s_waitcnt vmcnt(" #n ")" ::: "memory")
; #define PG8_WAIT_L(n) asm volatile("s_waitcnt lgkmcnt(" #n ")" ::: "memory")
; #define PG8_BAR __builtin_amdgcn_s_barrier()
; #define PG8_SCHED __builtin_amdgcn_sched_barrier(0)
; #define PG8_MMA2(ai) PG8_MMA(ai, 0, At, B0)
; #define PG8_MMA2(ai) PG8_MMA(ai, 1, At, B1)
; #define PG8_MMA2(ai) do { PG8_MMA(ai, 0, At, B0); PG8_MMA(ai, 1, At, B1); } while (0)
;     ...
;             PG8_LDB(B0, 0, 0); PG8_LDB(B1, 0, 1); PG8_SCHED; PG8_LDA(At, 0, 0); PG8_STAGE(PG8_SA(1, 1), a1 + hstep, voffA);
;             PG8_WAIT_V(8); PG8_WAIT_L(0); PG8_BAR; PG8_MMA2(0); PG8_BAR; PG8_SCHED;
;             PG8_LDA(At, 0, 1); PG8_STAGE(PG8_SB(0, 0), b2, voffB); PG8_STAGE(PG8_SB(0, 1), b2 + hstep, voffB); PG8_STAGE(PG8_SA(0, 0), a2, voffA);
;             PG8_WAIT_V(8); PG8_WAIT_L(0); PG8_BAR; PG8_MMA2(1); PG8_BAR; PG8_SCHED;
	s_setprio 1
	s_waitcnt lgkmcnt(0)
	v_mfma_f32_16x16x32_bf16 v[18:21], v[80:83], v[6:9], v[88:91]
	v_mfma_f32_16x16x32_bf16 v[6:9], v[108:111], v[6:9], v[96:99]
	v_mfma_f32_16x16x32_bf16 v[24:27], v[112:115], v[10:13], v[6:9]
	v_mfma_f32_16x16x32_bf16 v[6:9], v[80:83], v[14:17], v[124:127]
	v_mfma_f32_16x16x32_bf16 v[28:31], v[84:87], v[10:13], v[18:21]
	v_mfma_f32_16x16x32_bf16 v[20:23], v[84:87], v[92:95], v[6:9]
	v_mfma_f32_16x16x32_bf16 v[6:9], v[108:111], v[14:17], v[100:103]
	v_mfma_f32_16x16x32_bf16 v[16:19], v[112:115], v[92:95], v[6:9]
	v_mfma_f32_16x16x32_bf16 v[6:9], v[80:83], v[116:119], v[68:71]
	v_mfma_f32_16x16x32_bf16 v[12:15], v[84:87], v[120:123], v[6:9]
	v_mfma_f32_16x16x32_bf16 v[6:9], v[108:111], v[116:119], v[104:107]
	v_mfma_f32_16x16x32_bf16 v[0:3], v[80:83], v[140:143], v[2:5]
	v_mfma_f32_16x16x32_bf16 v[8:11], v[112:115], v[120:123], v[6:9]
	v_mfma_f32_16x16x32_bf16 v[4:7], v[84:87], v[150:153], v[0:3]
	v_mfma_f32_16x16x32_bf16 v[0:3], v[108:111], v[140:143], v[76:79]
	v_mfma_f32_16x16x32_bf16 v[0:3], v[112:115], v[150:153], v[0:3]
	s_setprio 0
	s_barrier
	ds_read_b128 v[68:71], v149
	ds_read_b128 v[76:79], v149 offset:1024
	ds_read_b128 v[80:83], v149 offset:2048
	ds_read_b128 v[84:87], v149 offset:3072
	s_and_b64 s[78:79], s[4:5], exec
	s_cselect_b32 s81, s69, s75
	s_cselect_b32 s80, s68, s74
	s_cselect_b32 s79, s71, s77
	s_cselect_b32 s78, s70, s76
	s_add_u32 s16, s74, 0x40480
	s_addc_u32 s17, s75, 0
	s_mov_b32 m0, s73
	v_lshl_add_u64 v[120:121], s[16:17], 0, v[134:135]
	ds_read_b128 v[88:91], v146
	ds_read_b128 v[92:95], v146 offset:1024
	ds_read_b128 v[96:99], v146 offset:2048
	ds_read_b128 v[100:103], v146 offset:3072
	ds_read_b128 v[104:107], v146 offset:4096
	ds_read_b128 v[108:111], v146 offset:5120
	ds_read_b128 v[112:115], v146 offset:6144
	ds_read_b128 v[116:119], v146 offset:7168
	global_load_lds_dwordx4 v[120:121], off
	v_lshl_add_u64 v[120:121], s[16:17], 0, v[130:131]
	s_mov_b32 m0, s65
	s_nop 0
	global_load_lds_dwordx4 v[120:121], off
	s_waitcnt vmcnt(6)
	s_waitcnt lgkmcnt(0)
	s_barrier
	s_setprio 1
	s_waitcnt lgkmcnt(0)
	v_mfma_f32_16x16x32_bf16 v[120:123], v[68:71], v[88:91], 0
	v_mfma_f32_16x16x32_bf16 v[88:91], v[80:83], v[88:91], 0
	v_mfma_f32_16x16x32_bf16 v[120:123], v[76:79], v[92:95], v[120:123]
	v_mfma_f32_16x16x32_bf16 v[88:91], v[84:87], v[92:95], v[88:91]
	v_mfma_f32_16x16x32_bf16 v[92:95], v[68:71], v[96:99], 0
	v_mfma_f32_16x16x32_bf16 v[96:99], v[80:83], v[96:99], 0
	v_mfma_f32_16x16x32_bf16 v[92:95], v[76:79], v[100:103], v[92:95]
	v_mfma_f32_16x16x32_bf16 v[96:99], v[84:87], v[100:103], v[96:99]
	v_mfma_f32_16x16x32_bf16 v[100:103], v[68:71], v[104:107], 0
	v_mfma_f32_16x16x32_bf16 v[104:107], v[80:83], v[104:107], 0
	v_mfma_f32_16x16x32_bf16 v[100:103], v[76:79], v[108:111], v[100:103]
	v_mfma_f32_16x16x32_bf16 v[104:107], v[84:87], v[108:111], v[104:107]
	v_mfma_f32_16x16x32_bf16 v[108:111], v[68:71], v[112:115], 0
	v_mfma_f32_16x16x32_bf16 v[112:115], v[80:83], v[112:115], 0
	v_mfma_f32_16x16x32_bf16 v[108:111], v[76:79], v[116:119], v[108:111]
	v_mfma_f32_16x16x32_bf16 v[112:115], v[84:87], v[116:119], v[112:115]
	s_setprio 0
	s_barrier
	s_mov_b32 m0, s67
	v_lshl_add_u64 v[170:171], v[56:57], 0, s[52:53]
	s_add_u32 s16, s76, 0x40500
	ds_read_b128 v[116:119], v146 offset:16384
	ds_read_b128 v[124:127], v146 offset:17408
	ds_read_b128 v[140:143], v146 offset:18432
	ds_read_b128 v[150:153], v146 offset:19456
	ds_read_b128 v[154:157], v146 offset:20480
	ds_read_b128 v[158:161], v146 offset:21504
	ds_read_b128 v[162:165], v146 offset:22528
	ds_read_b128 v[166:169], v146 offset:23552
	v_lshl_add_u64 v[170:171], v[58:59], 0, s[52:53]
	s_mov_b32 m0, s6
	s_addc_u32 s17, s77, 0
	v_lshl_add_u64 v[170:171], s[16:17], 0, v[132:133]
	s_mov_b32 m0, vcc_lo
	s_nop 0
	global_load_lds_dwordx4 v[170:171], off
	v_lshl_add_u64 v[170:171], s[16:17], 0, v[128:129]
	s_mov_b32 m0, vcc_hi
	s_nop 0
	global_load_lds_dwordx4 v[170:171], off
	v_lshl_add_u64 v[170:171], v[60:61], 0, s[52:53]
	s_mov_b32 m0, s83
	s_nop 0
	global_load_lds_dwordx4 v[170:171], off
	v_lshl_add_u64 v[170:171], v[62:63], 0, s[52:53]
	s_mov_b32 m0, s89
	s_nop 0
	global_load_lds_dwordx4 v[170:171], off
	s_waitcnt vmcnt(6)
	s_waitcnt lgkmcnt(0)
	s_barrier
	s_setprio 1
	s_waitcnt lgkmcnt(0)
	v_mfma_f32_16x16x32_bf16 v[170:173], v[68:71], v[116:119], 0
	v_mfma_f32_16x16x32_bf16 v[116:119], v[80:83], v[116:119], 0
	v_mfma_f32_16x16x32_bf16 v[170:173], v[76:79], v[124:127], v[170:173]
	v_mfma_f32_16x16x32_bf16 v[116:119], v[84:87], v[124:127], v[116:119]
	v_mfma_f32_16x16x32_bf16 v[124:127], v[68:71], v[140:143], 0
	v_mfma_f32_16x16x32_bf16 v[140:143], v[80:83], v[140:143], 0
	v_mfma_f32_16x16x32_bf16 v[124:127], v[76:79], v[150:153], v[124:127]
	v_mfma_f32_16x16x32_bf16 v[140:143], v[84:87], v[150:153], v[140:143]
	v_mfma_f32_16x16x32_bf16 v[150:153], v[68:71], v[154:157], 0
	v_mfma_f32_16x16x32_bf16 v[68:71], v[68:71], v[162:165], 0
	v_mfma_f32_16x16x32_bf16 v[150:153], v[76:79], v[158:161], v[150:153]
	v_mfma_f32_16x16x32_bf16 v[76:79], v[76:79], v[166:169], v[68:71]
	v_mfma_f32_16x16x32_bf16 v[68:71], v[80:83], v[162:165], 0
	v_mfma_f32_16x16x32_bf16 v[154:157], v[80:83], v[154:157], 0
	v_mfma_f32_16x16x32_bf16 v[80:83], v[84:87], v[166:169], v[68:71]
	v_mfma_f32_16x16x32_bf16 v[154:157], v[84:87], v[158:161], v[154:157]
	s_setprio 0
	s_barrier
; #define PG8_STAGE(bufoff, gbase, voff) do { _Pragma("unroll") for (int _i = 0; _i < 2; ++_i) \
;         __builtin_amdgcn_global_load_lds((const unsigned*)((const char*)(gbase) + (voff)[_i]), (PG8_LAS unsigned*)(lds + (bufoff) + ldsw + _i * 8192), 16, 0, 0); } while (0)
; #define PG8_LDA(dst, b, h) do { _Pragma("unroll") for (int m = 0; m < 4; ++m) _Pragma("unroll") for (int k = 0; k < 2; ++k) dst[m][k] = *(const PG8_LAS bf16x8*)(lds + PG8_SA(b, h) + aoff + m * 2048 + k * 1024); } while (0)
; #define PG8_LDB(dst, b, h) do { _Pragma("unroll") for (int n = 0; n < 2; ++n) _Pragma("unroll") for (int k = 0; k < 2; ++k) dst[n][k] = *(const PG8_LAS bf16x8*)(lds + PG8_SB(b, h) + boff + n * 2048 + k * 1024); } while (0)
; #define PG8_WAIT_V(n) asm volatile("s_waitcnt vmcnt(" #n ")" ::: "memory")
; #define PG8_WAIT_L(n) asm volatile("s_waitcnt lgkmcnt(" #n ")" ::: "memory")
; #define PG8_BAR __builtin_amdgcn_s_barrier()
; #define PG8_SCHED __builtin_amdgcn_sched_barrier(0)
; #define PG8_MMA2(ai) PG8_MMA(ai, 0, At, B0)
; #define PG8_MMA2(ai) PG8_MMA(ai, 1, At, B1)
; #define PG8_MMA2(ai) do { PG8_MMA(ai, 0, At, B0); PG8_MMA(ai, 1, At, B1); } while (0)
;     ...
;             PG8_LDB(B0, 0, 0); PG8_LDB(B1, 0, 1); PG8_SCHED; PG8_LDA(At, 0, 0); PG8_STAGE(PG8_SA(1, 1), a1 + hstep, voffA);
;             PG8_WAIT_V(8); PG8_WAIT_L(0); PG8_BAR; PG8_MMA2(0); PG8_BAR; PG8_SCHED;
;             PG8_LDA(At, 0, 1); PG8_STAGE(PG8_SB(0, 0), b2, voffB); PG8_STAGE(PG8_SB(0, 1), b2 + hstep, voffB); PG8_STAGE(PG8_SA(0, 0), a2, voffA);
;             PG8_WAIT_V(8); PG8_WAIT_L(0); PG8_BAR; PG8_MMA2(1); PG8_BAR; PG8_SCHED;
;             PG8_LDB(B0, 1, 0); PG8_LDB(B1, 1, 1); PG8_SCHED; PG8_LDA(At, 1, 0); PG8_STAGE(PG8_SA(0, 1), a2 + hstep, voffA);
;             PG8_WAIT_V(8); PG8_WAIT_L(0); PG8_BAR; PG8_MMA2(0); PG8_BAR; PG8_SCHED;
;             PG8_LDA(At, 1, 1); PG8_STAGE(PG8_SB(1, 0), b3, voffB); PG8_STAGE(PG8_SB(1, 1), b3 + hstep, voffB); PG8_STAGE(PG8_SA(1, 0), a3, voffA);
;             PG8_WAIT_V(8); PG8_WAIT_L(0); PG8_BAR; PG8_MMA2(1); PG8_BAR; PG8_SCHED;
	s_nop 2
	v_add_u32_e32 v68, s34, v145
	ds_read_b128 v[84:87], v68
	ds_read_b128 v[158:161], v68 offset:1024
	ds_read_b128 v[162:165], v68 offset:2048
	ds_read_b128 v[166:169], v68 offset:3072
	s_add_u32 s16, s74, 0x40500
	s_addc_u32 s17, s75, 0
	s_mov_b32 m0, s90
	v_lshl_add_u64 v[70:71], s[16:17], 0, v[134:135]
	ds_read_b128 v[174:177], v146 offset:32768
	ds_read_b128 v[178:181], v146 offset:33792
	ds_read_b128 v[182:185], v146 offset:34816
	ds_read_b128 v[186:189], v146 offset:35840
	ds_read_b128 v[190:193], v146 offset:36864
	ds_read_b128 v[194:197], v146 offset:37888
	ds_read_b128 v[212:215], v146 offset:38912
	ds_read_b128 v[216:219], v146 offset:39936
	global_load_lds_dwordx4 v[70:71], off
	v_lshl_add_u64 v[70:71], s[16:17], 0, v[130:131]
	s_mov_b32 m0, s91
	s_nop 0
	global_load_lds_dwordx4 v[70:71], off
	s_waitcnt vmcnt(6)
	s_waitcnt lgkmcnt(0)
	s_barrier
	s_setprio 1
	s_waitcnt lgkmcnt(0)
	v_mfma_f32_16x16x32_bf16 v[120:123], v[84:87], v[174:177], v[120:123]
	v_mfma_f32_16x16x32_bf16 v[88:91], v[162:165], v[174:177], v[88:91]
	v_mfma_f32_16x16x32_bf16 v[92:95], v[84:87], v[182:185], v[92:95]
	v_mfma_f32_16x16x32_bf16 v[96:99], v[162:165], v[182:185], v[96:99]
	v_mfma_f32_16x16x32_bf16 v[100:103], v[84:87], v[190:193], v[100:103]
	v_mfma_f32_16x16x32_bf16 v[104:107], v[162:165], v[190:193], v[104:107]
	v_mfma_f32_16x16x32_bf16 v[108:111], v[84:87], v[212:215], v[108:111]
	v_mfma_f32_16x16x32_bf16 v[112:115], v[162:165], v[212:215], v[112:115]
	v_mfma_f32_16x16x32_bf16 v[120:123], v[158:161], v[178:181], v[120:123]
	v_mfma_f32_16x16x32_bf16 v[88:91], v[166:169], v[178:181], v[88:91]
	v_mfma_f32_16x16x32_bf16 v[92:95], v[158:161], v[186:189], v[92:95]
	v_mfma_f32_16x16x32_bf16 v[96:99], v[166:169], v[186:189], v[96:99]
	v_mfma_f32_16x16x32_bf16 v[100:103], v[158:161], v[194:197], v[100:103]
	v_mfma_f32_16x16x32_bf16 v[104:107], v[166:169], v[194:197], v[104:107]
	v_mfma_f32_16x16x32_bf16 v[108:111], v[158:161], v[216:219], v[108:111]
	v_mfma_f32_16x16x32_bf16 v[112:115], v[166:169], v[216:219], v[112:115]
	s_setprio 0
	s_barrier
	s_mov_b32 m0, s9
	v_lshl_add_u64 v[70:71], v[56:57], 0, s[54:55]
	s_add_u32 s16, s76, 0x40580
	ds_read_b128 v[174:177], v146 offset:49152
	ds_read_b128 v[178:181], v146 offset:50176
	ds_read_b128 v[182:185], v146 offset:51200
	ds_read_b128 v[186:189], v146 offset:52224
	ds_read_b128 v[190:193], v146 offset:53248
	ds_read_b128 v[194:197], v146 offset:54272
	ds_read_b128 v[212:215], v146 offset:55296
	ds_read_b128 v[216:219], v146 offset:56320
	v_lshl_add_u64 v[70:71], v[58:59], 0, s[54:55]
	s_mov_b32 m0, s82
	s_addc_u32 s17, s77, 0
	v_lshl_add_u64 v[70:71], s[16:17], 0, v[132:133]
	s_mov_b32 m0, s7
	s_nop 0
	global_load_lds_dwordx4 v[70:71], off
	v_lshl_add_u64 v[70:71], s[16:17], 0, v[128:129]
	s_mov_b32 m0, s8
	s_nop 0
	global_load_lds_dwordx4 v[70:71], off
	v_lshl_add_u64 v[70:71], v[60:61], 0, s[54:55]
	s_mov_b32 m0, s92
	s_nop 0
	global_load_lds_dwordx4 v[70:71], off
	v_lshl_add_u64 v[70:71], v[62:63], 0, s[54:55]
	s_mov_b32 m0, s93
	s_nop 0
	global_load_lds_dwordx4 v[70:71], off
	s_waitcnt vmcnt(6)
	s_waitcnt lgkmcnt(0)
	s_barrier
	s_setprio 1
	s_waitcnt lgkmcnt(0)
	v_mfma_f32_16x16x32_bf16 v[116:119], v[162:165], v[174:177], v[116:119]
	v_mfma_f32_16x16x32_bf16 v[124:127], v[84:87], v[182:185], v[124:127]
	v_mfma_f32_16x16x32_bf16 v[76:79], v[84:87], v[212:215], v[76:79]
	v_mfma_f32_16x16x32_bf16 v[80:83], v[162:165], v[212:215], v[80:83]
	v_mfma_f32_16x16x32_bf16 v[170:173], v[84:87], v[174:177], v[170:173]
	v_mfma_f32_16x16x32_bf16 v[116:119], v[166:169], v[178:181], v[116:119]
	v_mfma_f32_16x16x32_bf16 v[124:127], v[158:161], v[186:189], v[124:127]
	v_mfma_f32_16x16x32_bf16 v[140:143], v[162:165], v[182:185], v[140:143]
	v_mfma_f32_16x16x32_bf16 v[150:153], v[84:87], v[190:193], v[150:153]
	v_mfma_f32_16x16x32_bf16 v[154:157], v[162:165], v[190:193], v[154:157]
	v_mfma_f32_16x16x32_bf16 v[76:79], v[158:161], v[216:219], v[76:79]
	v_mfma_f32_16x16x32_bf16 v[80:83], v[166:169], v[216:219], v[80:83]
	v_mfma_f32_16x16x32_bf16 v[170:173], v[158:161], v[178:181], v[170:173]
	v_mfma_f32_16x16x32_bf16 v[140:143], v[166:169], v[186:189], v[140:143]
	v_mfma_f32_16x16x32_bf16 v[150:153], v[158:161], v[194:197], v[150:153]
	v_mfma_f32_16x16x32_bf16 v[154:157], v[166:169], v[194:197], v[154:157]
	s_setprio 0
	s_barrier
	ds_read_b128 v[84:87], v149
	ds_read_b128 v[158:161], v149 offset:1024
	ds_read_b128 v[162:165], v149 offset:2048
	ds_read_b128 v[166:169], v149 offset:3072
	s_add_u32 s16, s74, 0x40580
	s_addc_u32 s17, s75, 0
	s_mov_b32 m0, s73
	v_lshl_add_u64 v[70:71], s[16:17], 0, v[134:135]
	ds_read_b128 v[174:177], v146
	ds_read_b128 v[178:181], v146 offset:1024
	ds_read_b128 v[182:185], v146 offset:2048
	ds_read_b128 v[186:189], v146 offset:3072
	ds_read_b128 v[190:193], v146 offset:4096
	ds_read_b128 v[194:197], v146 offset:5120
	ds_read_b128 v[212:215], v146 offset:6144
	ds_read_b128 v[216:219], v146 offset:7168
	global_load_lds_dwordx4 v[70:71], off
	v_lshl_add_u64 v[70:71], s[16:17], 0, v[130:131]
	s_mov_b32 m0, s65
	s_nop 0
	global_load_lds_dwordx4 v[70:71], off
	s_waitcnt vmcnt(6)
	s_waitcnt lgkmcnt(0)
	s_barrier
; #define PG8_STAGE(bufoff, gbase, voff) do { _Pragma("unroll") for (int _i = 0; _i < 2; ++_i) \
;         __builtin_amdgcn_global_load_lds((const unsigned*)((const char*)(gbase) + (voff)[_i]), (PG8_LAS unsigned*)(lds + (bufoff) + ldsw + _i * 8192), 16, 0, 0); } while (0)
; #define PG8_LDA(dst, b, h) do { _Pragma("unroll") for (int m = 0; m < 4; ++m) _Pragma("unroll") for (int k = 0; k < 2; ++k) dst[m][k] = *(const PG8_LAS bf16x8*)(lds + PG8_SA(b, h) + aoff + m * 2048 + k * 1024); } while (0)
; #define PG8_LDB(dst, b, h) do { _Pragma("unroll") for (int n = 0; n < 2; ++n) _Pragma("unroll") for (int k = 0; k < 2; ++k) dst[n][k] = *(const PG8_LAS bf16x8*)(lds + PG8_SB(b, h) + boff + n * 2048 + k * 1024); } while (0)
; #define PG8_WAIT_V(n) asm volatile("s_waitcnt vmcnt(" #n ")" ::: "memory")
; #define PG8_WAIT_L(n) asm volatile("s_waitcnt lgkmcnt(" #n ")" ::: "memory")
; #define PG8_BAR __builtin_amdgcn_s_barrier()
; #define PG8_SCHED __builtin_amdgcn_sched_barrier(0)
; #define PG8_MMA2(ai) PG8_MMA(ai, 0, At, B0)
; #define PG8_MMA2(ai) PG8_MMA(ai, 1, At, B1)
; #define PG8_MMA2(ai) do { PG8_MMA(ai, 0, At, B0); PG8_MMA(ai, 1, At, B1); } while (0)
;     ...
;             PG8_LDB(B0, 0, 0); PG8_LDB(B1, 0, 1); PG8_SCHED; PG8_LDA(At, 0, 0); PG8_STAGE(PG8_SA(1, 1), a1 + hstep, voffA);
;             PG8_WAIT_V(8); PG8_WAIT_L(0); PG8_BAR; PG8_MMA2(0); PG8_BAR; PG8_SCHED;
;             PG8_LDA(At, 0, 1); PG8_STAGE(PG8_SB(0, 0), b2, voffB); PG8_STAGE(PG8_SB(0, 1), b2 + hstep, voffB); PG8_STAGE(PG8_SA(0, 0), a2, voffA);
;             PG8_WAIT_V(8); PG8_WAIT_L(0); PG8_BAR; PG8_MMA2(1); PG8_BAR; PG8_SCHED;
;             PG8_LDB(B0, 1, 0); PG8_LDB(B1, 1, 1); PG8_SCHED; PG8_LDA(At, 1, 0); PG8_STAGE(PG8_SA(0, 1), a2 + hstep, voffA);
;             PG8_WAIT_V(8); PG8_WAIT_L(0); PG8_BAR; PG8_MMA2(0); PG8_BAR; PG8_SCHED;
;             PG8_LDA(At, 1, 1); PG8_STAGE(PG8_SB(1, 0), b3, voffB); PG8_STAGE(PG8_SB(1, 1), b3 + hstep, voffB); PG8_STAGE(PG8_SA(1, 0), a3, voffA);
;             PG8_WAIT_V(8); PG8_WAIT_L(0); PG8_BAR; PG8_MMA2(1); PG8_BAR; PG8_SCHED;
	s_setprio 1
	s_waitcnt lgkmcnt(0)
	v_mfma_f32_16x16x32_bf16 v[120:123], v[84:87], v[174:177], v[120:123]
	v_mfma_f32_16x16x32_bf16 v[88:91], v[162:165], v[174:177], v[88:91]
	v_mfma_f32_16x16x32_bf16 v[92:95], v[84:87], v[182:185], v[92:95]
	v_mfma_f32_16x16x32_bf16 v[96:99], v[162:165], v[182:185], v[96:99]
	v_mfma_f32_16x16x32_bf16 v[100:103], v[84:87], v[190:193], v[100:103]
	v_mfma_f32_16x16x32_bf16 v[104:107], v[162:165], v[190:193], v[104:107]
	v_mfma_f32_16x16x32_bf16 v[108:111], v[84:87], v[212:215], v[108:111]
	v_mfma_f32_16x16x32_bf16 v[112:115], v[162:165], v[212:215], v[112:115]
	v_mfma_f32_16x16x32_bf16 v[120:123], v[158:161], v[178:181], v[120:123]
	v_mfma_f32_16x16x32_bf16 v[88:91], v[166:169], v[178:181], v[88:91]
	v_mfma_f32_16x16x32_bf16 v[92:95], v[158:161], v[186:189], v[92:95]
	v_mfma_f32_16x16x32_bf16 v[96:99], v[166:169], v[186:189], v[96:99]
	v_mfma_f32_16x16x32_bf16 v[100:103], v[158:161], v[194:197], v[100:103]
	v_mfma_f32_16x16x32_bf16 v[104:107], v[166:169], v[194:197], v[104:107]
	v_mfma_f32_16x16x32_bf16 v[108:111], v[158:161], v[216:219], v[108:111]
	v_mfma_f32_16x16x32_bf16 v[112:115], v[166:169], v[216:219], v[112:115]
	s_setprio 0
	s_barrier
	s_mov_b32 m0, s67
	v_lshl_add_u64 v[70:71], v[56:57], 0, s[56:57]
	s_add_u32 s16, s76, 0x40600
	ds_read_b128 v[174:177], v146 offset:16384
	ds_read_b128 v[178:181], v146 offset:17408
	ds_read_b128 v[182:185], v146 offset:18432
	ds_read_b128 v[186:189], v146 offset:19456
	ds_read_b128 v[190:193], v146 offset:20480
	ds_read_b128 v[194:197], v146 offset:21504
	ds_read_b128 v[212:215], v146 offset:22528
	ds_read_b128 v[216:219], v146 offset:23552
	v_lshl_add_u64 v[70:71], v[58:59], 0, s[56:57]
	s_mov_b32 m0, s6
	s_addc_u32 s17, s77, 0
	v_lshl_add_u64 v[70:71], s[16:17], 0, v[132:133]
	s_mov_b32 m0, vcc_lo
	s_nop 0
	global_load_lds_dwordx4 v[70:71], off
	v_lshl_add_u64 v[70:71], s[16:17], 0, v[128:129]
	s_mov_b32 m0, vcc_hi
	s_nop 0
	global_load_lds_dwordx4 v[70:71], off
	v_lshl_add_u64 v[70:71], v[60:61], 0, s[56:57]
	s_mov_b32 m0, s83
	s_nop 0
	global_load_lds_dwordx4 v[70:71], off
	v_lshl_add_u64 v[70:71], v[62:63], 0, s[56:57]
	s_mov_b32 m0, s89
	s_nop 0
	global_load_lds_dwordx4 v[70:71], off
	s_waitcnt vmcnt(6)
	s_waitcnt lgkmcnt(0)
	s_barrier
	s_setprio 1
	s_waitcnt lgkmcnt(0)
	v_mfma_f32_16x16x32_bf16 v[116:119], v[162:165], v[174:177], v[116:119]
	v_mfma_f32_16x16x32_bf16 v[124:127], v[84:87], v[182:185], v[124:127]
	v_mfma_f32_16x16x32_bf16 v[76:79], v[84:87], v[212:215], v[76:79]
	v_mfma_f32_16x16x32_bf16 v[80:83], v[162:165], v[212:215], v[80:83]
	v_mfma_f32_16x16x32_bf16 v[170:173], v[84:87], v[174:177], v[170:173]
	v_mfma_f32_16x16x32_bf16 v[116:119], v[166:169], v[178:181], v[116:119]
	v_mfma_f32_16x16x32_bf16 v[124:127], v[158:161], v[186:189], v[124:127]
	v_mfma_f32_16x16x32_bf16 v[140:143], v[162:165], v[182:185], v[140:143]
	v_mfma_f32_16x16x32_bf16 v[150:153], v[84:87], v[190:193], v[150:153]
	v_mfma_f32_16x16x32_bf16 v[154:157], v[162:165], v[190:193], v[154:157]
	v_mfma_f32_16x16x32_bf16 v[76:79], v[158:161], v[216:219], v[76:79]
	v_mfma_f32_16x16x32_bf16 v[80:83], v[166:169], v[216:219], v[80:83]
	v_mfma_f32_16x16x32_bf16 v[170:173], v[158:161], v[178:181], v[170:173]
	v_mfma_f32_16x16x32_bf16 v[140:143], v[166:169], v[186:189], v[140:143]
	v_mfma_f32_16x16x32_bf16 v[150:153], v[158:161], v[194:197], v[150:153]
	v_mfma_f32_16x16x32_bf16 v[154:157], v[166:169], v[194:197], v[154:157]
	s_setprio 0
	s_barrier
	ds_read_b128 v[84:87], v68
	ds_read_b128 v[158:161], v68 offset:1024
	ds_read_b128 v[162:165], v68 offset:2048
	ds_read_b128 v[166:169], v68 offset:3072
	s_add_u32 s16, s74, 0x40600
	s_addc_u32 s17, s75, 0
	s_mov_b32 m0, s90
	v_lshl_add_u64 v[70:71], s[16:17], 0, v[134:135]
	ds_read_b128 v[174:177], v146 offset:32768
	ds_read_b128 v[178:181], v146 offset:33792
	ds_read_b128 v[182:185], v146 offset:34816
	ds_read_b128 v[186:189], v146 offset:35840
	ds_read_b128 v[190:193], v146 offset:36864
	ds_read_b128 v[194:197], v146 offset:37888
	ds_read_b128 v[212:215], v146 offset:38912
	ds_read_b128 v[216:219], v146 offset:39936
	global_load_lds_dwordx4 v[70:71], off
	v_lshl_add_u64 v[70:71], s[16:17], 0, v[130:131]
	s_mov_b32 m0, s91
	s_nop 0
	global_load_lds_dwordx4 v[70:71], off
	s_waitcnt vmcnt(6)
	s_waitcnt lgkmcnt(0)
	s_barrier
	s_setprio 1
	s_waitcnt lgkmcnt(0)
	v_mfma_f32_16x16x32_bf16 v[120:123], v[84:87], v[174:177], v[120:123]
	v_mfma_f32_16x16x32_bf16 v[88:91], v[162:165], v[174:177], v[88:91]
	v_mfma_f32_16x16x32_bf16 v[92:95], v[84:87], v[182:185], v[92:95]
	v_mfma_f32_16x16x32_bf16 v[96:99], v[162:165], v[182:185], v[96:99]
	v_mfma_f32_16x16x32_bf16 v[100:103], v[84:87], v[190:193], v[100:103]
	v_mfma_f32_16x16x32_bf16 v[104:107], v[162:165], v[190:193], v[104:107]
	v_mfma_f32_16x16x32_bf16 v[108:111], v[84:87], v[212:215], v[108:111]
	v_mfma_f32_16x16x32_bf16 v[112:115], v[162:165], v[212:215], v[112:115]
	v_mfma_f32_16x16x32_bf16 v[120:123], v[158:161], v[178:181], v[120:123]
	v_mfma_f32_16x16x32_bf16 v[88:91], v[166:169], v[178:181], v[88:91]
	v_mfma_f32_16x16x32_bf16 v[92:95], v[158:161], v[186:189], v[92:95]
	v_mfma_f32_16x16x32_bf16 v[96:99], v[166:169], v[186:189], v[96:99]
	v_mfma_f32_16x16x32_bf16 v[100:103], v[158:161], v[194:197], v[100:103]
	v_mfma_f32_16x16x32_bf16 v[104:107], v[166:169], v[194:197], v[104:107]
	v_mfma_f32_16x16x32_bf16 v[108:111], v[158:161], v[216:219], v[108:111]
	v_mfma_f32_16x16x32_bf16 v[112:115], v[166:169], v[216:219], v[112:115]
	s_setprio 0
	s_barrier
; #define PG8_STAGE(bufoff, gbase, voff) do { _Pragma("unroll") for (int _i = 0; _i < 2; ++_i) \
;         __builtin_amdgcn_global_load_lds((const unsigned*)((const char*)(gbase) + (voff)[_i]), (PG8_LAS unsigned*)(lds + (bufoff) + ldsw + _i * 8192), 16, 0, 0); } while (0)
; #define PG8_LDA(dst, b, h) do { _Pragma("unroll") for (int m = 0; m < 4; ++m) _Pragma("unroll") for (int k = 0; k < 2; ++k) dst[m][k] = *(const PG8_LAS bf16x8*)(lds + PG8_SA(b, h) + aoff + m * 2048 + k * 1024); } while (0)
; #define PG8_LDB(dst, b, h) do { _Pragma("unroll") for (int n = 0; n < 2; ++n) _Pragma("unroll") for (int k = 0; k < 2; ++k) dst[n][k] = *(const PG8_LAS bf16x8*)(lds + PG8_SB(b, h) + boff + n * 2048 + k * 1024); } while (0)
; #define PG8_WAIT_V(n) asm volatile("s_waitcnt vmcnt(" #n ")" ::: "memory")
; #define PG8_WAIT_L(n) asm volatile("s_waitcnt lgkmcnt(" #n ")" ::: "memory")
; #define PG8_BAR __builtin_amdgcn_s_barrier()
; #define PG8_SCHED __builtin_amdgcn_sched_barrier(0)
; #define PG8_MMA2(ai) PG8_MMA(ai, 0, At, B0)
; #define PG8_MMA2(ai) PG8_MMA(ai, 1, At, B1)
; #define PG8_MMA2(ai) do { PG8_MMA(ai, 0, At, B0); PG8_MMA(ai, 1, At, B1); } while (0)
;     ...
;             PG8_LDB(B0, 0, 0); PG8_LDB(B1, 0, 1); PG8_SCHED; PG8_LDA(At, 0, 0); PG8_STAGE(PG8_SA(1, 1), a1 + hstep, voffA);
;             PG8_WAIT_V(8); PG8_WAIT_L(0); PG8_BAR; PG8_MMA2(0); PG8_BAR; PG8_SCHED;
;             PG8_LDA(At, 0, 1); PG8_STAGE(PG8_SB(0, 0), b2, voffB); PG8_STAGE(PG8_SB(0, 1), b2 + hstep, voffB); PG8_STAGE(PG8_SA(0, 0), a2, voffA);
;             PG8_WAIT_V(8); PG8_WAIT_L(0); PG8_BAR; PG8_MMA2(1); PG8_BAR; PG8_SCHED;
;             PG8_LDB(B0, 1, 0); PG8_LDB(B1, 1, 1); PG8_SCHED; PG8_LDA(At, 1, 0); PG8_STAGE(PG8_SA(0, 1), a2 + hstep, voffA);
;             PG8_WAIT_V(8); PG8_WAIT_L(0); PG8_BAR; PG8_MMA2(0); PG8_BAR; PG8_SCHED;
;             PG8_LDA(At, 1, 1); PG8_STAGE(PG8_SB(1, 0), b3, voffB); PG8_STAGE(PG8_SB(1, 1), b3 + hstep, voffB); PG8_STAGE(PG8_SA(1, 0), a3, voffA);
;             PG8_WAIT_V(8); PG8_WAIT_L(0); PG8_BAR; PG8_MMA2(1); PG8_BAR; PG8_SCHED;
	s_mov_b32 m0, s9
	v_lshl_add_u64 v[70:71], v[56:57], 0, s[58:59]
	s_add_u32 s16, s76, 0x40680
	ds_read_b128 v[174:177], v146 offset:49152
	ds_read_b128 v[178:181], v146 offset:50176
	ds_read_b128 v[182:185], v146 offset:51200
	ds_read_b128 v[186:189], v146 offset:52224
	ds_read_b128 v[190:193], v146 offset:53248
	ds_read_b128 v[194:197], v146 offset:54272
	ds_read_b128 v[212:215], v146 offset:55296
	ds_read_b128 v[216:219], v146 offset:56320
	v_lshl_add_u64 v[70:71], v[58:59], 0, s[58:59]
	s_mov_b32 m0, s82
	s_addc_u32 s17, s77, 0
	v_lshl_add_u64 v[70:71], s[16:17], 0, v[132:133]
	s_mov_b32 m0, s7
	s_nop 0
	global_load_lds_dwordx4 v[70:71], off
	v_lshl_add_u64 v[70:71], s[16:17], 0, v[128:129]
	s_mov_b32 m0, s8
	s_nop 0
	global_load_lds_dwordx4 v[70:71], off
	v_lshl_add_u64 v[70:71], v[60:61], 0, s[58:59]
	s_mov_b32 m0, s92
	s_nop 0
	global_load_lds_dwordx4 v[70:71], off
	v_lshl_add_u64 v[70:71], v[62:63], 0, s[58:59]
	s_mov_b32 m0, s93
	s_nop 0
	global_load_lds_dwordx4 v[70:71], off
	s_waitcnt vmcnt(6)
	s_waitcnt lgkmcnt(0)
	s_barrier
	s_setprio 1
	s_waitcnt lgkmcnt(0)
	v_mfma_f32_16x16x32_bf16 v[116:119], v[162:165], v[174:177], v[116:119]
	v_mfma_f32_16x16x32_bf16 v[124:127], v[84:87], v[182:185], v[124:127]
	v_mfma_f32_16x16x32_bf16 v[76:79], v[84:87], v[212:215], v[76:79]
	v_mfma_f32_16x16x32_bf16 v[80:83], v[162:165], v[212:215], v[80:83]
	v_mfma_f32_16x16x32_bf16 v[170:173], v[84:87], v[174:177], v[170:173]
	v_mfma_f32_16x16x32_bf16 v[116:119], v[166:169], v[178:181], v[116:119]
	v_mfma_f32_16x16x32_bf16 v[124:127], v[158:161], v[186:189], v[124:127]
	v_mfma_f32_16x16x32_bf16 v[140:143], v[162:165], v[182:185], v[140:143]
	v_mfma_f32_16x16x32_bf16 v[150:153], v[84:87], v[190:193], v[150:153]
	v_mfma_f32_16x16x32_bf16 v[154:157], v[162:165], v[190:193], v[154:157]
	v_mfma_f32_16x16x32_bf16 v[76:79], v[158:161], v[216:219], v[76:79]
	v_mfma_f32_16x16x32_bf16 v[80:83], v[166:169], v[216:219], v[80:83]
	v_mfma_f32_16x16x32_bf16 v[170:173], v[158:161], v[178:181], v[170:173]
	v_mfma_f32_16x16x32_bf16 v[140:143], v[166:169], v[186:189], v[140:143]
	v_mfma_f32_16x16x32_bf16 v[150:153], v[158:161], v[194:197], v[150:153]
	v_mfma_f32_16x16x32_bf16 v[154:157], v[166:169], v[194:197], v[154:157]
	s_setprio 0
	s_barrier
	ds_read_b128 v[84:87], v149
	ds_read_b128 v[158:161], v149 offset:1024
	ds_read_b128 v[162:165], v149 offset:2048
	ds_read_b128 v[166:169], v149 offset:3072
	s_add_u32 s16, s74, 0x40680
	s_addc_u32 s17, s75, 0
	s_mov_b32 m0, s73
	v_lshl_add_u64 v[70:71], s[16:17], 0, v[134:135]
	ds_read_b128 v[174:177], v146
	ds_read_b128 v[178:181], v146 offset:1024
	ds_read_b128 v[182:185], v146 offset:2048
	ds_read_b128 v[186:189], v146 offset:3072
	ds_read_b128 v[190:193], v146 offset:4096
	ds_read_b128 v[194:197], v146 offset:5120
	ds_read_b128 v[212:215], v146 offset:6144
	ds_read_b128 v[216:219], v146 offset:7168
	global_load_lds_dwordx4 v[70:71], off
	v_lshl_add_u64 v[70:71], s[16:17], 0, v[130:131]
	s_mov_b32 m0, s65
	s_nop 0
	global_load_lds_dwordx4 v[70:71], off
	s_waitcnt vmcnt(6)
	s_waitcnt lgkmcnt(0)
	s_barrier
	s_setprio 1
	s_waitcnt lgkmcnt(0)
	v_mfma_f32_16x16x32_bf16 v[120:123], v[84:87], v[174:177], v[120:123]
	v_mfma_f32_16x16x32_bf16 v[88:91], v[162:165], v[174:177], v[88:91]
	v_mfma_f32_16x16x32_bf16 v[92:95], v[84:87], v[182:185], v[92:95]
	v_mfma_f32_16x16x32_bf16 v[96:99], v[162:165], v[182:185], v[96:99]
	v_mfma_f32_16x16x32_bf16 v[100:103], v[84:87], v[190:193], v[100:103]
	v_mfma_f32_16x16x32_bf16 v[104:107], v[162:165], v[190:193], v[104:107]
	v_mfma_f32_16x16x32_bf16 v[108:111], v[84:87], v[212:215], v[108:111]
	v_mfma_f32_16x16x32_bf16 v[112:115], v[162:165], v[212:215], v[112:115]
	v_mfma_f32_16x16x32_bf16 v[120:123], v[158:161], v[178:181], v[120:123]
	v_mfma_f32_16x16x32_bf16 v[88:91], v[166:169], v[178:181], v[88:91]
	v_mfma_f32_16x16x32_bf16 v[92:95], v[158:161], v[186:189], v[92:95]
	v_mfma_f32_16x16x32_bf16 v[96:99], v[166:169], v[186:189], v[96:99]
	v_mfma_f32_16x16x32_bf16 v[100:103], v[158:161], v[194:197], v[100:103]
	v_mfma_f32_16x16x32_bf16 v[104:107], v[166:169], v[194:197], v[104:107]
	v_mfma_f32_16x16x32_bf16 v[108:111], v[158:161], v[216:219], v[108:111]
	v_mfma_f32_16x16x32_bf16 v[112:115], v[166:169], v[216:219], v[112:115]
	s_setprio 0
	s_barrier
	s_mov_b32 m0, s67
	v_lshl_add_u64 v[70:71], v[56:57], 0, s[60:61]
	s_add_u32 s16, s76, 0x40700
	ds_read_b128 v[174:177], v146 offset:16384
	ds_read_b128 v[178:181], v146 offset:17408
	ds_read_b128 v[182:185], v146 offset:18432
	ds_read_b128 v[186:189], v146 offset:19456
	ds_read_b128 v[190:193], v146 offset:20480
	ds_read_b128 v[194:197], v146 offset:21504
	ds_read_b128 v[212:215], v146 offset:22528
	ds_read_b128 v[216:219], v146 offset:23552
	v_lshl_add_u64 v[70:71], v[58:59], 0, s[60:61]
	s_mov_b32 m0, s6
	s_addc_u32 s17, s77, 0
	v_lshl_add_u64 v[70:71], s[16:17], 0, v[132:133]
	s_mov_b32 m0, vcc_lo
	s_nop 0
	global_load_lds_dwordx4 v[70:71], off
	v_lshl_add_u64 v[70:71], s[16:17], 0, v[128:129]
	s_mov_b32 m0, vcc_hi
	s_nop 0
	global_load_lds_dwordx4 v[70:71], off
	v_lshl_add_u64 v[70:71], v[60:61], 0, s[60:61]
	s_mov_b32 m0, s83
	s_nop 0
	global_load_lds_dwordx4 v[70:71], off
	v_lshl_add_u64 v[70:71], v[62:63], 0, s[60:61]
	s_mov_b32 m0, s89
	s_nop 0
	global_load_lds_dwordx4 v[70:71], off
	s_waitcnt vmcnt(6)
	s_waitcnt lgkmcnt(0)
	s_barrier
; #define PG8_STAGE(bufoff, gbase, voff) do { _Pragma("unroll") for (int _i = 0; _i < 2; ++_i) \
;         __builtin_amdgcn_global_load_lds((const unsigned*)((const char*)(gbase) + (voff)[_i]), (PG8_LAS unsigned*)(lds + (bufoff) + ldsw + _i * 8192), 16, 0, 0); } while (0)
; #define PG8_LDA(dst, b, h) do { _Pragma("unroll") for (int m = 0; m < 4; ++m) _Pragma("unroll") for (int k = 0; k < 2; ++k) dst[m][k] = *(const PG8_LAS bf16x8*)(lds + PG8_SA(b, h) + aoff + m * 2048 + k * 1024); } while (0)
; #define PG8_LDB(dst, b, h) do { _Pragma("unroll") for (int n = 0; n < 2; ++n) _Pragma("unroll") for (int k = 0; k < 2; ++k) dst[n][k] = *(const PG8_LAS bf16x8*)(lds + PG8_SB(b, h) + boff + n * 2048 + k * 1024); } while (0)
; #define PG8_WAIT_V(n) asm volatile("s_waitcnt vmcnt(" #n ")" ::: "memory")
; #define PG8_WAIT_L(n) asm volatile("s_waitcnt lgkmcnt(" #n ")" ::: "memory")
; #define PG8_BAR __builtin_amdgcn_s_barrier()
; #define PG8_SCHED __builtin_amdgcn_sched_barrier(0)
; #define PG8_MMA2(ai) PG8_MMA(ai, 0, At, B0)
; #define PG8_MMA2(ai) PG8_MMA(ai, 1, At, B1)
; #define PG8_MMA2(ai) do { PG8_MMA(ai, 0, At, B0); PG8_MMA(ai, 1, At, B1); } while (0)
;     ...
;             PG8_LDB(B0, 0, 0); PG8_LDB(B1, 0, 1); PG8_SCHED; PG8_LDA(At, 0, 0); PG8_STAGE(PG8_SA(1, 1), a1 + hstep, voffA);
;             PG8_WAIT_V(8); PG8_WAIT_L(0); PG8_BAR; PG8_MMA2(0); PG8_BAR; PG8_SCHED;
;             PG8_LDA(At, 0, 1); PG8_STAGE(PG8_SB(0, 0), b2, voffB); PG8_STAGE(PG8_SB(0, 1), b2 + hstep, voffB); PG8_STAGE(PG8_SA(0, 0), a2, voffA);
;             PG8_WAIT_V(8); PG8_WAIT_L(0); PG8_BAR; PG8_MMA2(1); PG8_BAR; PG8_SCHED;
;             PG8_LDB(B0, 1, 0); PG8_LDB(B1, 1, 1); PG8_SCHED; PG8_LDA(At, 1, 0); PG8_STAGE(PG8_SA(0, 1), a2 + hstep, voffA);
;             PG8_WAIT_V(8); PG8_WAIT_L(0); PG8_BAR; PG8_MMA2(0); PG8_BAR; PG8_SCHED;
;             PG8_LDA(At, 1, 1); PG8_STAGE(PG8_SB(1, 0), b3, voffB); PG8_STAGE(PG8_SB(1, 1), b3 + hstep, voffB); PG8_STAGE(PG8_SA(1, 0), a3, voffA);
;             PG8_WAIT_V(8); PG8_WAIT_L(0); PG8_BAR; PG8_MMA2(1); PG8_BAR; PG8_SCHED;
	s_setprio 1
	s_waitcnt lgkmcnt(0)
	v_mfma_f32_16x16x32_bf16 v[116:119], v[162:165], v[174:177], v[116:119]
	v_mfma_f32_16x16x32_bf16 v[124:127], v[84:87], v[182:185], v[124:127]
	v_mfma_f32_16x16x32_bf16 v[76:79], v[84:87], v[212:215], v[76:79]
	v_mfma_f32_16x16x32_bf16 v[80:83], v[162:165], v[212:215], v[80:83]
	v_mfma_f32_16x16x32_bf16 v[170:173], v[84:87], v[174:177], v[170:173]
	v_mfma_f32_16x16x32_bf16 v[116:119], v[166:169], v[178:181], v[116:119]
	v_mfma_f32_16x16x32_bf16 v[124:127], v[158:161], v[186:189], v[124:127]
	v_mfma_f32_16x16x32_bf16 v[140:143], v[162:165], v[182:185], v[140:143]
	v_mfma_f32_16x16x32_bf16 v[150:153], v[84:87], v[190:193], v[150:153]
	v_mfma_f32_16x16x32_bf16 v[154:157], v[162:165], v[190:193], v[154:157]
	v_mfma_f32_16x16x32_bf16 v[76:79], v[158:161], v[216:219], v[76:79]
	v_mfma_f32_16x16x32_bf16 v[80:83], v[166:169], v[216:219], v[80:83]
	v_mfma_f32_16x16x32_bf16 v[170:173], v[158:161], v[178:181], v[170:173]
	v_mfma_f32_16x16x32_bf16 v[140:143], v[166:169], v[186:189], v[140:143]
	v_mfma_f32_16x16x32_bf16 v[150:153], v[158:161], v[194:197], v[150:153]
	v_mfma_f32_16x16x32_bf16 v[154:157], v[166:169], v[194:197], v[154:157]
	s_setprio 0
	s_barrier
	ds_read_b128 v[84:87], v68
	ds_read_b128 v[158:161], v68 offset:1024
	ds_read_b128 v[162:165], v68 offset:2048
	ds_read_b128 v[166:169], v68 offset:3072
	s_add_u32 s16, s74, 0x40700
	s_addc_u32 s17, s75, 0
	s_mov_b32 m0, s90
	v_lshl_add_u64 v[70:71], s[16:17], 0, v[134:135]
	ds_read_b128 v[174:177], v146 offset:32768
	ds_read_b128 v[178:181], v146 offset:33792
	ds_read_b128 v[182:185], v146 offset:34816
	ds_read_b128 v[186:189], v146 offset:35840
	ds_read_b128 v[190:193], v146 offset:36864
	ds_read_b128 v[194:197], v146 offset:37888
	ds_read_b128 v[212:215], v146 offset:38912
	ds_read_b128 v[216:219], v146 offset:39936
	global_load_lds_dwordx4 v[70:71], off
	v_lshl_add_u64 v[70:71], s[16:17], 0, v[130:131]
	s_mov_b32 m0, s91
	s_nop 0
	global_load_lds_dwordx4 v[70:71], off
	s_waitcnt vmcnt(6)
	s_waitcnt lgkmcnt(0)
	s_barrier
	s_setprio 1
	s_waitcnt lgkmcnt(0)
	v_mfma_f32_16x16x32_bf16 v[120:123], v[84:87], v[174:177], v[120:123]
	v_mfma_f32_16x16x32_bf16 v[88:91], v[162:165], v[174:177], v[88:91]
	v_mfma_f32_16x16x32_bf16 v[92:95], v[84:87], v[182:185], v[92:95]
	v_mfma_f32_16x16x32_bf16 v[96:99], v[162:165], v[182:185], v[96:99]
	v_mfma_f32_16x16x32_bf16 v[100:103], v[84:87], v[190:193], v[100:103]
	v_mfma_f32_16x16x32_bf16 v[104:107], v[162:165], v[190:193], v[104:107]
	v_mfma_f32_16x16x32_bf16 v[108:111], v[84:87], v[212:215], v[108:111]
	v_mfma_f32_16x16x32_bf16 v[112:115], v[162:165], v[212:215], v[112:115]
	v_mfma_f32_16x16x32_bf16 v[120:123], v[158:161], v[178:181], v[120:123]
	v_mfma_f32_16x16x32_bf16 v[88:91], v[166:169], v[178:181], v[88:91]
	v_mfma_f32_16x16x32_bf16 v[92:95], v[158:161], v[186:189], v[92:95]
	v_mfma_f32_16x16x32_bf16 v[96:99], v[166:169], v[186:189], v[96:99]
	v_mfma_f32_16x16x32_bf16 v[100:103], v[158:161], v[194:197], v[100:103]
	v_mfma_f32_16x16x32_bf16 v[104:107], v[166:169], v[194:197], v[104:107]
	v_mfma_f32_16x16x32_bf16 v[108:111], v[158:161], v[216:219], v[108:111]
	v_mfma_f32_16x16x32_bf16 v[112:115], v[166:169], v[216:219], v[112:115]
	s_setprio 0
	s_barrier
	s_mov_b32 m0, s9
	v_lshl_add_u64 v[56:57], v[56:57], 0, s[62:63]
	s_add_u32 s16, s76, 0x40780
	ds_read_b128 v[174:177], v146 offset:49152
	ds_read_b128 v[178:181], v146 offset:50176
	ds_read_b128 v[182:185], v146 offset:51200
	ds_read_b128 v[186:189], v146 offset:52224
	ds_read_b128 v[190:193], v146 offset:53248
	ds_read_b128 v[194:197], v146 offset:54272
	ds_read_b128 v[212:215], v146 offset:55296
	ds_read_b128 v[216:219], v146 offset:56320
	v_lshl_add_u64 v[56:57], v[58:59], 0, s[62:63]
	s_mov_b32 m0, s82
	s_addc_u32 s17, s77, 0
	v_lshl_add_u64 v[56:57], s[16:17], 0, v[132:133]
	s_mov_b32 m0, s7
	s_nop 0
	global_load_lds_dwordx4 v[56:57], off
	v_lshl_add_u64 v[56:57], s[16:17], 0, v[128:129]
	s_mov_b32 m0, s8
	s_nop 0
	global_load_lds_dwordx4 v[56:57], off
	v_lshl_add_u64 v[56:57], v[60:61], 0, s[62:63]
	s_mov_b32 m0, s92
	s_nop 0
	global_load_lds_dwordx4 v[56:57], off
	v_lshl_add_u64 v[56:57], v[62:63], 0, s[62:63]
	s_mov_b32 m0, s93
	s_nop 0
	global_load_lds_dwordx4 v[56:57], off
	s_waitcnt vmcnt(6)
	s_waitcnt lgkmcnt(0)
	s_barrier
	s_setprio 1
	s_waitcnt lgkmcnt(0)
	v_mfma_f32_16x16x32_bf16 v[56:59], v[84:87], v[174:177], v[170:173]
	v_mfma_f32_16x16x32_bf16 v[60:63], v[162:165], v[174:177], v[116:119]
	v_mfma_f32_16x16x32_bf16 v[116:119], v[84:87], v[182:185], v[124:127]
	v_mfma_f32_16x16x32_bf16 v[124:127], v[162:165], v[182:185], v[140:143]
	v_mfma_f32_16x16x32_bf16 v[76:79], v[84:87], v[212:215], v[76:79]
	v_mfma_f32_16x16x32_bf16 v[80:83], v[162:165], v[212:215], v[80:83]
	v_mfma_f32_16x16x32_bf16 v[56:59], v[158:161], v[178:181], v[56:59]
	v_mfma_f32_16x16x32_bf16 v[60:63], v[166:169], v[178:181], v[60:63]
	v_mfma_f32_16x16x32_bf16 v[116:119], v[158:161], v[186:189], v[116:119]
	v_mfma_f32_16x16x32_bf16 v[124:127], v[166:169], v[186:189], v[124:127]
	v_mfma_f32_16x16x32_bf16 v[140:143], v[84:87], v[190:193], v[150:153]
	v_mfma_f32_16x16x32_bf16 v[150:153], v[162:165], v[190:193], v[154:157]
	v_mfma_f32_16x16x32_bf16 v[76:79], v[158:161], v[216:219], v[76:79]
	v_mfma_f32_16x16x32_bf16 v[80:83], v[166:169], v[216:219], v[80:83]
	v_mfma_f32_16x16x32_bf16 v[140:143], v[158:161], v[194:197], v[140:143]
	v_mfma_f32_16x16x32_bf16 v[150:153], v[166:169], v[194:197], v[150:153]
	s_setprio 0
	s_barrier
; #define PG8_STAGE(bufoff, gbase, voff) do { _Pragma("unroll") for (int _i = 0; _i < 2; ++_i) \
;         __builtin_amdgcn_global_load_lds((const unsigned*)((const char*)(gbase) + (voff)[_i]), (PG8_LAS unsigned*)(lds + (bufoff) + ldsw + _i * 8192), 16, 0, 0); } while (0)
; #define PG8_LDA(dst, b, h) do { _Pragma("unroll") for (int m = 0; m < 4; ++m) _Pragma("unroll") for (int k = 0; k < 2; ++k) dst[m][k] = *(const PG8_LAS bf16x8*)(lds + PG8_SA(b, h) + aoff + m * 2048 + k * 1024); } while (0)
; #define PG8_LDB(dst, b, h) do { _Pragma("unroll") for (int n = 0; n < 2; ++n) _Pragma("unroll") for (int k = 0; k < 2; ++k) dst[n][k] = *(const PG8_LAS bf16x8*)(lds + PG8_SB(b, h) + boff + n * 2048 + k * 1024); } while (0)
; #define PG8_WAIT_V(n) asm volatile("s_waitcnt vmcnt(" #n ")" ::: "memory")
; #define PG8_WAIT_L(n) asm volatile("s_waitcnt lgkmcnt(" #n ")" ::: "memory")
; #define PG8_BAR __builtin_amdgcn_s_barrier()
; #define PG8_SCHED __builtin_amdgcn_sched_barrier(0)
; #define PG8_MMA2(ai) PG8_MMA(ai, 0, At, B0)
; #define PG8_MMA2(ai) PG8_MMA(ai, 1, At, B1)
; #define PG8_MMA2(ai) do { PG8_MMA(ai, 0, At, B0); PG8_MMA(ai, 1, At, B1); } while (0)
;     ...
;             const char* a2 = last ? nA : cA + (size_t)(t + 2) * kstep; const char* b2 = last ? nB : cB + (size_t)(t + 2) * kstep;
;             const char* a3 = a2 + kstep; const char* b3 = b2 + kstep;
;             if (last && has_next) S.a_ready(nxt);
;             if constexpr (SP2) {
;             PG8_LDB(B0, 0, 0); PG8_LDB(B1, 0, 1); PG8_SCHED; PG8_LDA(At, 0, 0); PG8_STAGE(PG8_SA(1, 1), a1 + hstep, voffA);
;             PG8_WAIT_V(8); PG8_WAIT_L(0); PG8_BAR; PG8_MMA2(0); PG8_BAR; PG8_SCHED;
;             PG8_LDA(At, 0, 1); PG8_STAGE(PG8_SB(0, 0), b2, voffB); PG8_STAGE(PG8_SB(0, 1), b2 + hstep, voffB); PG8_STAGE(PG8_SA(0, 0), a2, voffA);
;             PG8_WAIT_V(8); PG8_WAIT_L(0); PG8_BAR; PG8_MMA2(1); PG8_BAR; PG8_SCHED;
;             PG8_LDB(B0, 1, 0); PG8_LDB(B1, 1, 1); PG8_SCHED; PG8_LDA(At, 1, 0); PG8_STAGE(PG8_SA(0, 1), a2 + hstep, voffA);
;             PG8_WAIT_V(8); PG8_WAIT_L(0); PG8_BAR; PG8_MMA2(0); PG8_BAR; PG8_SCHED;
;             PG8_LDA(At, 1, 1); PG8_STAGE(PG8_SB(1, 0), b3, voffB); PG8_STAGE(PG8_SB(1, 1), b3 + hstep, voffB); PG8_STAGE(PG8_SA(1, 0), a3, voffA);
;             PG8_WAIT_V(8); PG8_WAIT_L(0); PG8_BAR; PG8_MMA2(1); PG8_BAR; PG8_SCHED;
	ds_read_b128 v[84:87], v149
	ds_read_b128 v[154:157], v149 offset:1024
	ds_read_b128 v[158:161], v149 offset:2048
	ds_read_b128 v[162:165], v149 offset:3072
	s_add_u32 s16, s74, 0x40780
	s_addc_u32 s17, s75, 0
	s_mov_b32 m0, s73
	v_lshl_add_u64 v[70:71], s[16:17], 0, v[134:135]
	ds_read_b128 v[166:169], v146
	ds_read_b128 v[170:173], v146 offset:1024
	ds_read_b128 v[174:177], v146 offset:2048
	ds_read_b128 v[178:181], v146 offset:3072
	ds_read_b128 v[182:185], v146 offset:4096
	ds_read_b128 v[186:189], v146 offset:5120
	ds_read_b128 v[190:193], v146 offset:6144
	ds_read_b128 v[194:197], v146 offset:7168
	global_load_lds_dwordx4 v[70:71], off
	v_lshl_add_u64 v[70:71], s[16:17], 0, v[130:131]
	s_mov_b32 m0, s65
	s_nop 0
	global_load_lds_dwordx4 v[70:71], off
	s_waitcnt vmcnt(6)
	s_waitcnt lgkmcnt(0)
	s_barrier
	s_setprio 1
	s_waitcnt lgkmcnt(0)
	v_mfma_f32_16x16x32_bf16 v[120:123], v[84:87], v[166:169], v[120:123]
	v_mfma_f32_16x16x32_bf16 v[88:91], v[158:161], v[166:169], v[88:91]
	v_mfma_f32_16x16x32_bf16 v[92:95], v[84:87], v[174:177], v[92:95]
	v_mfma_f32_16x16x32_bf16 v[96:99], v[158:161], v[174:177], v[96:99]
	v_mfma_f32_16x16x32_bf16 v[100:103], v[84:87], v[182:185], v[100:103]
	v_mfma_f32_16x16x32_bf16 v[104:107], v[158:161], v[182:185], v[104:107]
	v_mfma_f32_16x16x32_bf16 v[108:111], v[84:87], v[190:193], v[108:111]
	v_mfma_f32_16x16x32_bf16 v[120:123], v[154:157], v[170:173], v[120:123]
	v_mfma_f32_16x16x32_bf16 v[88:91], v[162:165], v[170:173], v[88:91]
	v_mfma_f32_16x16x32_bf16 v[92:95], v[154:157], v[178:181], v[92:95]
	v_mfma_f32_16x16x32_bf16 v[96:99], v[162:165], v[178:181], v[96:99]
	v_mfma_f32_16x16x32_bf16 v[100:103], v[154:157], v[186:189], v[100:103]
	v_mfma_f32_16x16x32_bf16 v[104:107], v[162:165], v[186:189], v[104:107]
	v_mfma_f32_16x16x32_bf16 v[166:169], v[154:157], v[194:197], v[108:111]
	v_mfma_f32_16x16x32_bf16 v[108:111], v[158:161], v[190:193], v[112:115]
	v_mfma_f32_16x16x32_bf16 v[170:173], v[162:165], v[194:197], v[108:111]
	s_setprio 0
	s_barrier
	s_mov_b32 m0, s67
	v_lshl_add_u64 v[198:199], s[78:79], 0, v[132:133]
	s_add_u32 s16, s78, 0x40000
	s_nop 1
	ds_read_b128 v[108:111], v146 offset:16384
	ds_read_b128 v[112:115], v146 offset:17408
	ds_read_b128 v[174:177], v146 offset:18432
	ds_read_b128 v[178:181], v146 offset:19456
	ds_read_b128 v[182:185], v146 offset:20480
	ds_read_b128 v[186:189], v146 offset:21504
	ds_read_b128 v[190:193], v146 offset:22528
	ds_read_b128 v[194:197], v146 offset:23552
	global_load_lds_dwordx4 v[198:199], off
	v_lshl_add_u64 v[224:225], s[78:79], 0, v[128:129]
	s_mov_b32 m0, s6
	s_addc_u32 s17, s79, 0
	global_load_lds_dwordx4 v[224:225], off
	v_lshl_add_u64 v[70:71], s[16:17], 0, v[132:133]
	s_mov_b32 m0, vcc_lo
	v_lshl_add_u64 v[226:227], s[80:81], 0, v[134:135]
	v_lshl_add_u64 v[70:71], s[16:17], 0, v[128:129]
	s_mov_b32 m0, vcc_hi
	v_lshl_add_u64 v[228:229], s[80:81], 0, v[130:131]
	s_mov_b32 m0, s83
	s_nop 0
	global_load_lds_dwordx4 v[226:227], off
	s_mov_b32 m0, s89
	s_nop 0
	global_load_lds_dwordx4 v[228:229], off
	s_waitcnt vmcnt(6)
	s_waitcnt lgkmcnt(0)
	s_barrier
	s_setprio 1
	s_waitcnt lgkmcnt(0)
	v_mfma_f32_16x16x32_bf16 v[56:59], v[84:87], v[108:111], v[56:59]
	v_mfma_f32_16x16x32_bf16 v[60:63], v[158:161], v[108:111], v[60:63]
	v_mfma_f32_16x16x32_bf16 v[108:111], v[84:87], v[174:177], v[116:119]
	v_mfma_f32_16x16x32_bf16 v[212:215], v[154:157], v[178:181], v[108:111]
	v_mfma_f32_16x16x32_bf16 v[108:111], v[158:161], v[174:177], v[124:127]
	v_mfma_f32_16x16x32_bf16 v[174:177], v[162:165], v[178:181], v[108:111]
	v_mfma_f32_16x16x32_bf16 v[108:111], v[84:87], v[182:185], v[140:143]
	v_mfma_f32_16x16x32_bf16 v[76:79], v[84:87], v[190:193], v[76:79]
	v_mfma_f32_16x16x32_bf16 v[56:59], v[154:157], v[112:115], v[56:59]
	v_mfma_f32_16x16x32_bf16 v[60:63], v[162:165], v[112:115], v[60:63]
	v_mfma_f32_16x16x32_bf16 v[140:143], v[154:157], v[186:189], v[108:111]
	v_mfma_f32_16x16x32_bf16 v[108:111], v[158:161], v[182:185], v[150:153]
	v_mfma_f32_16x16x32_bf16 v[154:157], v[154:157], v[194:197], v[76:79]
	v_mfma_f32_16x16x32_bf16 v[76:79], v[158:161], v[190:193], v[80:83]
	v_mfma_f32_16x16x32_bf16 v[150:153], v[162:165], v[186:189], v[108:111]
	v_mfma_f32_16x16x32_bf16 v[158:161], v[162:165], v[194:197], v[76:79]
	s_setprio 0
	s_barrier
; #define PG8_STAGE(bufoff, gbase, voff) do { _Pragma("unroll") for (int _i = 0; _i < 2; ++_i) \
;         __builtin_amdgcn_global_load_lds((const unsigned*)((const char*)(gbase) + (voff)[_i]), (PG8_LAS unsigned*)(lds + (bufoff) + ldsw + _i * 8192), 16, 0, 0); } while (0)
; #define PG8_LDA(dst, b, h) do { _Pragma("unroll") for (int m = 0; m < 4; ++m) _Pragma("unroll") for (int k = 0; k < 2; ++k) dst[m][k] = *(const PG8_LAS bf16x8*)(lds + PG8_SA(b, h) + aoff + m * 2048 + k * 1024); } while (0)
; #define PG8_LDB(dst, b, h) do { _Pragma("unroll") for (int n = 0; n < 2; ++n) _Pragma("unroll") for (int k = 0; k < 2; ++k) dst[n][k] = *(const PG8_LAS bf16x8*)(lds + PG8_SB(b, h) + boff + n * 2048 + k * 1024); } while (0)
; #define PG8_WAIT_V(n) asm volatile("s_waitcnt vmcnt(" #n ")" ::: "memory")
; #define PG8_WAIT_L(n) asm volatile("s_waitcnt lgkmcnt(" #n ")" ::: "memory")
; #define PG8_BAR __builtin_amdgcn_s_barrier()
; #define PG8_SCHED __builtin_amdgcn_sched_barrier(0)
; #define PG8_MMA2(ai) PG8_MMA(ai, 0, At, B0)
; #define PG8_MMA2(ai) PG8_MMA(ai, 1, At, B1)
; #define PG8_MMA2(ai) do { PG8_MMA(ai, 0, At, B0); PG8_MMA(ai, 1, At, B1); } while (0)
;     ...
;             PG8_LDB(B0, 0, 0); PG8_LDB(B1, 0, 1); PG8_SCHED; PG8_LDA(At, 0, 0); PG8_STAGE(PG8_SA(1, 1), a1 + hstep, voffA);
;             PG8_WAIT_V(8); PG8_WAIT_L(0); PG8_BAR; PG8_MMA2(0); PG8_BAR; PG8_SCHED;
;             PG8_LDA(At, 0, 1); PG8_STAGE(PG8_SB(0, 0), b2, voffB); PG8_STAGE(PG8_SB(0, 1), b2 + hstep, voffB); PG8_STAGE(PG8_SA(0, 0), a2, voffA);
;             PG8_WAIT_V(8); PG8_WAIT_L(0); PG8_BAR; PG8_MMA2(1); PG8_BAR; PG8_SCHED;
;             PG8_LDB(B0, 1, 0); PG8_LDB(B1, 1, 1); PG8_SCHED; PG8_LDA(At, 1, 0); PG8_STAGE(PG8_SA(0, 1), a2 + hstep, voffA);
;             PG8_WAIT_V(8); PG8_WAIT_L(0); PG8_BAR; PG8_MMA2(0); PG8_BAR; PG8_SCHED;
;             PG8_LDA(At, 1, 1); PG8_STAGE(PG8_SB(1, 0), b3, voffB); PG8_STAGE(PG8_SB(1, 1), b3 + hstep, voffB); PG8_STAGE(PG8_SA(1, 0), a3, voffA);
;             PG8_WAIT_V(8); PG8_WAIT_L(0); PG8_BAR; PG8_MMA2(1); PG8_BAR; PG8_SCHED;
	ds_read_b128 v[162:165], v68
	ds_read_b128 v[178:181], v68 offset:1024
	ds_read_b128 v[182:185], v68 offset:2048
	ds_read_b128 v[186:189], v68 offset:3072
	s_add_u32 s16, s80, 0x40000
	s_addc_u32 s17, s81, 0
	s_mov_b32 m0, s90
	v_lshl_add_u64 v[108:109], s[16:17], 0, v[134:135]
	ds_read_b128 v[68:71], v146 offset:32768
	ds_read_b128 v[76:79], v146 offset:33792
	ds_read_b128 v[80:83], v146 offset:34816
	ds_read_b128 v[84:87], v146 offset:35840
	ds_read_b128 v[190:193], v146 offset:36864
	ds_read_b128 v[194:197], v146 offset:37888
	ds_read_b128 v[216:219], v146 offset:38912
	ds_read_b128 v[220:223], v146 offset:39936
	global_load_lds_dwordx4 v[108:109], off
	v_lshl_add_u64 v[108:109], s[16:17], 0, v[130:131]
	s_mov_b32 m0, s91
	s_nop 0
	global_load_lds_dwordx4 v[108:109], off
	s_waitcnt vmcnt(6)
	s_waitcnt lgkmcnt(0)
	s_barrier
	s_setprio 1
	s_waitcnt lgkmcnt(0)
	v_mfma_f32_16x16x32_bf16 v[108:111], v[162:165], v[68:71], v[120:123]
	v_mfma_f32_16x16x32_bf16 v[68:71], v[182:185], v[68:71], v[88:91]
	v_mfma_f32_16x16x32_bf16 v[120:123], v[186:189], v[76:79], v[68:71]
	v_mfma_f32_16x16x32_bf16 v[68:71], v[162:165], v[80:83], v[92:95]
	v_mfma_f32_16x16x32_bf16 v[116:119], v[178:181], v[84:87], v[68:71]
	v_mfma_f32_16x16x32_bf16 v[68:71], v[182:185], v[80:83], v[96:99]
	v_mfma_f32_16x16x32_bf16 v[112:115], v[186:189], v[84:87], v[68:71]
	v_mfma_f32_16x16x32_bf16 v[68:71], v[162:165], v[190:193], v[100:103]
	v_mfma_f32_16x16x32_bf16 v[124:127], v[178:181], v[76:79], v[108:111]
	v_mfma_f32_16x16x32_bf16 v[108:111], v[178:181], v[194:197], v[68:71]
	v_mfma_f32_16x16x32_bf16 v[68:71], v[182:185], v[190:193], v[104:107]
	v_mfma_f32_16x16x32_bf16 v[104:107], v[186:189], v[194:197], v[68:71]
	v_mfma_f32_16x16x32_bf16 v[68:71], v[162:165], v[216:219], v[166:169]
	v_mfma_f32_16x16x32_bf16 v[100:103], v[178:181], v[220:223], v[68:71]
	v_mfma_f32_16x16x32_bf16 v[68:71], v[182:185], v[216:219], v[170:173]
	v_mfma_f32_16x16x32_bf16 v[96:99], v[186:189], v[220:223], v[68:71]
	s_setprio 0
	s_barrier
	s_mov_b32 m0, s9
	v_lshl_add_u64 v[84:85], v[198:199], 0, s[20:21]
	s_add_u32 s16, s78, 0x40080
	s_nop 1
	ds_read_b128 v[68:71], v146 offset:49152
	ds_read_b128 v[76:79], v146 offset:50176
	ds_read_b128 v[80:83], v146 offset:51200
	ds_read_b128 v[166:169], v146 offset:52224
	ds_read_b128 v[170:173], v146 offset:53248
	ds_read_b128 v[190:193], v146 offset:54272
	ds_read_b128 v[194:197], v146 offset:55296
	ds_read_b128 v[216:219], v146 offset:56320
	global_load_lds_dwordx4 v[84:85], off
	v_lshl_add_u64 v[84:85], v[224:225], 0, s[20:21]
	s_mov_b32 m0, s82
	s_addc_u32 s17, s79, 0
	global_load_lds_dwordx4 v[84:85], off
	v_lshl_add_u64 v[84:85], s[16:17], 0, v[132:133]
	s_mov_b32 m0, s7
	s_nop 0
	v_lshl_add_u64 v[84:85], s[16:17], 0, v[128:129]
	s_mov_b32 m0, s8
	s_nop 0
	v_lshl_add_u64 v[84:85], v[226:227], 0, s[20:21]
	s_mov_b32 m0, s92
	s_nop 0
	global_load_lds_dwordx4 v[84:85], off
	v_lshl_add_u64 v[84:85], v[228:229], 0, s[20:21]
	s_mov_b32 m0, s93
	s_nop 0
	global_load_lds_dwordx4 v[84:85], off
	s_waitcnt vmcnt(6)
	s_waitcnt lgkmcnt(0)
	s_barrier
	s_setprio 1
	s_waitcnt lgkmcnt(0)
	v_mfma_f32_16x16x32_bf16 v[56:59], v[162:165], v[68:71], v[56:59]
	v_mfma_f32_16x16x32_bf16 v[92:95], v[178:181], v[76:79], v[56:59]
	v_mfma_f32_16x16x32_bf16 v[56:59], v[182:185], v[68:71], v[60:63]
	v_mfma_f32_16x16x32_bf16 v[88:91], v[186:189], v[76:79], v[56:59]
	v_mfma_f32_16x16x32_bf16 v[56:59], v[162:165], v[80:83], v[212:215]
	v_mfma_f32_16x16x32_bf16 v[84:87], v[178:181], v[166:169], v[56:59]
	v_mfma_f32_16x16x32_bf16 v[56:59], v[182:185], v[80:83], v[174:177]
	v_mfma_f32_16x16x32_bf16 v[80:83], v[186:189], v[166:169], v[56:59]
	v_mfma_f32_16x16x32_bf16 v[56:59], v[162:165], v[170:173], v[140:143]
	v_mfma_f32_16x16x32_bf16 v[76:79], v[178:181], v[190:193], v[56:59]
	v_mfma_f32_16x16x32_bf16 v[56:59], v[182:185], v[170:173], v[150:153]
	v_mfma_f32_16x16x32_bf16 v[68:71], v[186:189], v[190:193], v[56:59]
	v_mfma_f32_16x16x32_bf16 v[56:59], v[162:165], v[194:197], v[154:157]
	v_mfma_f32_16x16x32_bf16 v[60:63], v[178:181], v[216:219], v[56:59]
	v_mfma_f32_16x16x32_bf16 v[56:59], v[182:185], v[194:197], v[158:161]
	v_mfma_f32_16x16x32_bf16 v[56:59], v[186:189], v[216:219], v[56:59]
	s_setprio 0
	s_barrier
	s_andn2_b64 vcc, exec, s[22:23]
	s_cbranch_vccnz .LBB0_1050
	s_barrier

; __device__ __forceinline__ unsigned cvt_pk_bf16(float lo, float hi) { unsigned r; asm volatile("v_cvt_pk_bf16_f32 %0, %1, %2" : "=v"(r) : "v"(lo), "v"(hi)); return r; }
; __device__ __forceinline__ float fast_sigmoid(float x) { return __builtin_amdgcn_rcpf(1.0f + __builtin_amdgcn_exp2f(-1.4426950408889634f * x)); }
; __device__ __forceinline__ float silu_f(float x) { return x * fast_sigmoid(x); }
;     __device__ __forceinline__ void operator()(const f32x4 (&acc)[2][2][4][2], const Unit& u, int wr, int wc, int fr, int fq) const {
;     ...
;         for (int ai = 0; ai < 2; ++ai)
; #pragma unroll
;             for (int m = 0; m < 4; ++m) {
;                 bf16_t* p = O + (size_t)(row0 + ai * HALF + m * 16) * DFF_ + col0;
;                 const f32x4 a0 = acc[ai][0][m][0], a1 = acc[ai][0][m][1], b0 = acc[ai][1][m][0], b1 = acc[ai][1][m][1];
;                 float h[8];
; #pragma unroll
;                 for (int e = 0; e < 4; ++e) { h[e] = silu_f(a0[e]) * b0[e]; h[4 + e] = silu_f(a1[e]) * b1[e]; }
;                 u32x4 w; w.x = cvt_pk_bf16(h[0], h[1]); w.y = cvt_pk_bf16(h[2], h[3]); w.z = cvt_pk_bf16(h[4], h[5]); w.w = cvt_pk_bf16(h[6], h[7]);
;                 *(u32x4*)p = w;
.LBB0_1266:
	s_andn2_b64 vcc, exec, s[12:13]
	s_mov_b64 s[12:13], -1
	v_mov_b32_e32 v160, 0xbfb8aa3b
	v_mov_b32_e32 v161, 0xbfb8aa3b
	v_mov_b32_e32 v162, 1.0
	v_mov_b32_e32 v163, 1.0
	v_lshl_or_b32 v164, s6, 7, v148
	v_lshl_add_u32 v166, s40, 8, v146
	v_mov_b64_e32 v[168:169], s[16:17]
	v_ashrrev_i32_e32 v165, 31, v164
	v_mad_i64_i32 v[170:171], s[6:7], v166, s62, v[168:169]
	v_lshlrev_b64 v[164:165], 1, v[164:165]
	v_lshl_add_u64 v[170:171], v[170:171], 0, v[164:165]
	v_pk_mul_f32 v[152:153], v[124:125], v[160:161]
	v_pk_mul_f32 v[154:155], v[126:127], v[160:161]
	v_pk_mul_f32 v[156:157], v[120:121], v[160:161]
	v_pk_mul_f32 v[158:159], v[122:123], v[160:161]
	v_exp_f32_e32 v152, v152
	v_exp_f32_e32 v153, v153
	v_exp_f32_e32 v154, v154
	v_exp_f32_e32 v155, v155
	v_exp_f32_e32 v156, v156
	v_exp_f32_e32 v157, v157
	v_exp_f32_e32 v158, v158
	v_exp_f32_e32 v159, v159
	v_pk_add_f32 v[152:153], v[152:153], v[162:163]
	v_pk_add_f32 v[154:155], v[154:155], v[162:163]
	v_pk_add_f32 v[156:157], v[156:157], v[162:163]
	v_pk_add_f32 v[158:159], v[158:159], v[162:163]
	v_rcp_f32_e32 v152, v152
	v_rcp_f32_e32 v153, v153
	v_rcp_f32_e32 v154, v154
	v_rcp_f32_e32 v155, v155
	v_rcp_f32_e32 v156, v156
	v_rcp_f32_e32 v157, v157
	v_rcp_f32_e32 v158, v158
	v_rcp_f32_e32 v159, v159
	v_pk_mul_f32 v[152:153], v[124:125], v[152:153]
	v_pk_mul_f32 v[154:155], v[126:127], v[154:155]
	v_pk_mul_f32 v[156:157], v[120:121], v[156:157]
	v_pk_mul_f32 v[158:159], v[122:123], v[158:159]
	v_pk_mul_f32 v[152:153], v[152:153], v[116:117]
	v_pk_mul_f32 v[154:155], v[154:155], v[118:119]
	v_pk_mul_f32 v[156:157], v[156:157], v[112:113]
	v_pk_mul_f32 v[158:159], v[158:159], v[114:115]
	v_cvt_pk_bf16_f32 v194, v152, v153
	v_cvt_pk_bf16_f32 v195, v154, v155
	v_cvt_pk_bf16_f32 v196, v156, v157
	v_cvt_pk_bf16_f32 v197, v158, v159
	global_store_dwordx4 v[170:171], v[194:197], off
	v_pk_mul_f32 v[152:153], v[108:109], v[160:161]
	v_pk_mul_f32 v[154:155], v[110:111], v[160:161]
	v_pk_mul_f32 v[156:157], v[104:105], v[160:161]
	v_pk_mul_f32 v[158:159], v[106:107], v[160:161]
	v_exp_f32_e32 v152, v152
	v_exp_f32_e32 v153, v153
	v_exp_f32_e32 v154, v154
	v_exp_f32_e32 v155, v155
	v_exp_f32_e32 v156, v156
	v_exp_f32_e32 v157, v157
	v_exp_f32_e32 v158, v158
	v_exp_f32_e32 v159, v159
	v_pk_add_f32 v[152:153], v[152:153], v[162:163]
	v_pk_add_f32 v[154:155], v[154:155], v[162:163]
	v_pk_add_f32 v[156:157], v[156:157], v[162:163]
	v_pk_add_f32 v[158:159], v[158:159], v[162:163]
	v_rcp_f32_e32 v152, v152
	v_rcp_f32_e32 v153, v153
	v_rcp_f32_e32 v154, v154
	v_rcp_f32_e32 v155, v155
	v_rcp_f32_e32 v156, v156
	v_rcp_f32_e32 v157, v157
	v_rcp_f32_e32 v158, v158
	v_rcp_f32_e32 v159, v159
	s_mov_b64 s[6:7], 0x16000
	v_lshl_add_u64 v[188:189], v[170:171], 0, s[6:7]
	v_pk_mul_f32 v[152:153], v[108:109], v[152:153]
	v_pk_mul_f32 v[154:155], v[110:111], v[154:155]
	v_pk_mul_f32 v[156:157], v[104:105], v[156:157]
	v_pk_mul_f32 v[158:159], v[106:107], v[158:159]
	v_pk_mul_f32 v[152:153], v[152:153], v[100:101]
	v_pk_mul_f32 v[154:155], v[154:155], v[102:103]
	v_pk_mul_f32 v[156:157], v[156:157], v[96:97]
	v_pk_mul_f32 v[158:159], v[158:159], v[98:99]
	v_cvt_pk_bf16_f32 v222, v152, v153
	v_cvt_pk_bf16_f32 v223, v154, v155
	v_cvt_pk_bf16_f32 v224, v156, v157
	v_cvt_pk_bf16_f32 v225, v158, v159
	global_store_dwordx4 v[188:189], v[222:225], off
	v_pk_mul_f32 v[152:153], v[92:93], v[160:161]
	v_pk_mul_f32 v[154:155], v[94:95], v[160:161]
	v_pk_mul_f32 v[156:157], v[88:89], v[160:161]
	v_pk_mul_f32 v[158:159], v[90:91], v[160:161]
	v_exp_f32_e32 v152, v152
	v_exp_f32_e32 v153, v153
	v_exp_f32_e32 v154, v154
	v_exp_f32_e32 v155, v155
	v_exp_f32_e32 v156, v156
	v_exp_f32_e32 v157, v157
	v_exp_f32_e32 v158, v158
	v_exp_f32_e32 v159, v159
	v_pk_add_f32 v[152:153], v[152:153], v[162:163]
	v_pk_add_f32 v[154:155], v[154:155], v[162:163]
	v_pk_add_f32 v[156:157], v[156:157], v[162:163]
	v_pk_add_f32 v[158:159], v[158:159], v[162:163]
	v_rcp_f32_e32 v152, v152
	v_rcp_f32_e32 v153, v153
	v_rcp_f32_e32 v154, v154
	v_rcp_f32_e32 v155, v155
	v_rcp_f32_e32 v156, v156
	v_rcp_f32_e32 v157, v157
	v_rcp_f32_e32 v158, v158
	v_rcp_f32_e32 v159, v159
	s_mov_b64 s[6:7], 0x2c000
	v_lshl_add_u64 v[190:191], v[170:171], 0, s[6:7]
	v_pk_mul_f32 v[152:153], v[92:93], v[152:153]
	v_pk_mul_f32 v[154:155], v[94:95], v[154:155]
	v_pk_mul_f32 v[156:157], v[88:89], v[156:157]
	v_pk_mul_f32 v[158:159], v[90:91], v[158:159]
	v_pk_mul_f32 v[152:153], v[152:153], v[84:85]
	v_pk_mul_f32 v[154:155], v[154:155], v[86:87]
	v_pk_mul_f32 v[156:157], v[156:157], v[80:81]
	v_pk_mul_f32 v[158:159], v[158:159], v[82:83]
	v_cvt_pk_bf16_f32 v226, v152, v153
	v_cvt_pk_bf16_f32 v227, v154, v155
	v_cvt_pk_bf16_f32 v228, v156, v157
	v_cvt_pk_bf16_f32 v229, v158, v159
	global_store_dwordx4 v[190:191], v[226:229], off
	v_pk_mul_f32 v[152:153], v[76:77], v[160:161]
	v_pk_mul_f32 v[154:155], v[78:79], v[160:161]
	v_pk_mul_f32 v[156:157], v[72:73], v[160:161]
	v_pk_mul_f32 v[158:159], v[74:75], v[160:161]
	v_exp_f32_e32 v152, v152
	v_exp_f32_e32 v153, v153
	v_exp_f32_e32 v154, v154
	v_exp_f32_e32 v155, v155
	v_exp_f32_e32 v156, v156
	v_exp_f32_e32 v157, v157
	v_exp_f32_e32 v158, v158
	v_exp_f32_e32 v159, v159
	v_pk_add_f32 v[152:153], v[152:153], v[162:163]
	v_pk_add_f32 v[154:155], v[154:155], v[162:163]
	v_pk_add_f32 v[156:157], v[156:157], v[162:163]
	v_pk_add_f32 v[158:159], v[158:159], v[162:163]
	v_rcp_f32_e32 v152, v152
	v_rcp_f32_e32 v153, v153
	v_rcp_f32_e32 v154, v154
	v_rcp_f32_e32 v155, v155
	v_rcp_f32_e32 v156, v156
	v_rcp_f32_e32 v157, v157
	v_rcp_f32_e32 v158, v158
	v_rcp_f32_e32 v159, v159
	s_mov_b64 s[6:7], 0x42000
	v_lshl_add_u64 v[192:193], v[170:171], 0, s[6:7]
; __device__ __forceinline__ unsigned cvt_pk_bf16(float lo, float hi) { unsigned r; asm volatile("v_cvt_pk_bf16_f32 %0, %1, %2" : "=v"(r) : "v"(lo), "v"(hi)); return r; }
; __device__ __forceinline__ float fast_sigmoid(float x) { return __builtin_amdgcn_rcpf(1.0f + __builtin_amdgcn_exp2f(-1.4426950408889634f * x)); }
; __device__ __forceinline__ float silu_f(float x) { return x * fast_sigmoid(x); }
;     __device__ __forceinline__ void operator()(const f32x4 (&acc)[2][2][4][2], const Unit& u, int wr, int wc, int fr, int fq) const {
;         const int row0 = u.pm * BM + wr * 64 + fr, col0 = u.pn * HALF + wc * 32 + 8 * fq;
; #pragma unroll
;         for (int ai = 0; ai < 2; ++ai)
; #pragma unroll
;             for (int m = 0; m < 4; ++m) {
;                 bf16_t* p = O + (size_t)(row0 + ai * HALF + m * 16) * DFF_ + col0;
;                 const f32x4 a0 = acc[ai][0][m][0], a1 = acc[ai][0][m][1], b0 = acc[ai][1][m][0], b1 = acc[ai][1][m][1];
;                 float h[8];
; #pragma unroll
;                 for (int e = 0; e < 4; ++e) { h[e] = silu_f(a0[e]) * b0[e]; h[4 + e] = silu_f(a1[e]) * b1[e]; }
;                 u32x4 w; w.x = cvt_pk_bf16(h[0], h[1]); w.y = cvt_pk_bf16(h[2], h[3]); w.z = cvt_pk_bf16(h[4], h[5]); w.w = cvt_pk_bf16(h[6], h[7]);
;                 *(u32x4*)p = w;
;             }
	v_pk_mul_f32 v[152:153], v[76:77], v[152:153]
	v_pk_mul_f32 v[154:155], v[78:79], v[154:155]
	v_pk_mul_f32 v[156:157], v[72:73], v[156:157]
	v_pk_mul_f32 v[158:159], v[74:75], v[158:159]
	v_pk_mul_f32 v[152:153], v[152:153], v[68:69]
	v_pk_mul_f32 v[154:155], v[154:155], v[70:71]
	v_pk_mul_f32 v[156:157], v[156:157], v[64:65]
	v_pk_mul_f32 v[158:159], v[158:159], v[66:67]
	v_cvt_pk_bf16_f32 v230, v152, v153
	v_cvt_pk_bf16_f32 v231, v154, v155
	v_cvt_pk_bf16_f32 v232, v156, v157
	v_cvt_pk_bf16_f32 v233, v158, v159
	global_store_dwordx4 v[192:193], v[230:233], off
	v_pk_mul_f32 v[152:153], v[60:61], v[160:161]
	v_pk_mul_f32 v[154:155], v[62:63], v[160:161]
	v_pk_mul_f32 v[156:157], v[56:57], v[160:161]
	v_pk_mul_f32 v[158:159], v[58:59], v[160:161]
	v_exp_f32_e32 v152, v152
	v_exp_f32_e32 v153, v153
	v_exp_f32_e32 v154, v154
	v_exp_f32_e32 v155, v155
	v_exp_f32_e32 v156, v156
	v_exp_f32_e32 v157, v157
	v_exp_f32_e32 v158, v158
	v_exp_f32_e32 v159, v159
	v_pk_add_f32 v[152:153], v[152:153], v[162:163]
	v_pk_add_f32 v[154:155], v[154:155], v[162:163]
	v_pk_add_f32 v[156:157], v[156:157], v[162:163]
	v_pk_add_f32 v[158:159], v[158:159], v[162:163]
	v_rcp_f32_e32 v152, v152
	v_rcp_f32_e32 v153, v153
	v_rcp_f32_e32 v154, v154
	v_rcp_f32_e32 v155, v155
	v_rcp_f32_e32 v156, v156
	v_rcp_f32_e32 v157, v157
	v_rcp_f32_e32 v158, v158
	v_rcp_f32_e32 v159, v159
	s_mov_b64 s[6:7], 0xb0000
	v_lshl_add_u64 v[186:187], v[170:171], 0, s[6:7]
	v_pk_mul_f32 v[152:153], v[60:61], v[152:153]
	v_pk_mul_f32 v[154:155], v[62:63], v[154:155]
	v_pk_mul_f32 v[156:157], v[56:57], v[156:157]
	v_pk_mul_f32 v[158:159], v[58:59], v[158:159]
	v_pk_mul_f32 v[152:153], v[152:153], v[52:53]
	v_pk_mul_f32 v[154:155], v[154:155], v[54:55]
	v_pk_mul_f32 v[156:157], v[156:157], v[48:49]
	v_pk_mul_f32 v[158:159], v[158:159], v[50:51]
	v_cvt_pk_bf16_f32 v194, v152, v153
	v_cvt_pk_bf16_f32 v195, v154, v155
	v_cvt_pk_bf16_f32 v196, v156, v157
	v_cvt_pk_bf16_f32 v197, v158, v159
	global_store_dwordx4 v[186:187], v[194:197], off
	v_pk_mul_f32 v[152:153], v[44:45], v[160:161]
	v_pk_mul_f32 v[154:155], v[46:47], v[160:161]
	v_pk_mul_f32 v[156:157], v[40:41], v[160:161]
	v_pk_mul_f32 v[158:159], v[42:43], v[160:161]
	v_exp_f32_e32 v152, v152
	v_exp_f32_e32 v153, v153
	v_exp_f32_e32 v154, v154
	v_exp_f32_e32 v155, v155
	v_exp_f32_e32 v156, v156
	v_exp_f32_e32 v157, v157
	v_exp_f32_e32 v158, v158
	v_exp_f32_e32 v159, v159
	v_pk_add_f32 v[152:153], v[152:153], v[162:163]
	v_pk_add_f32 v[154:155], v[154:155], v[162:163]
	v_pk_add_f32 v[156:157], v[156:157], v[162:163]
	v_pk_add_f32 v[158:159], v[158:159], v[162:163]
	v_rcp_f32_e32 v152, v152
	v_rcp_f32_e32 v153, v153
	v_rcp_f32_e32 v154, v154
	v_rcp_f32_e32 v155, v155
	v_rcp_f32_e32 v156, v156
	v_rcp_f32_e32 v157, v157
	v_rcp_f32_e32 v158, v158
	v_rcp_f32_e32 v159, v159
	s_mov_b64 s[6:7], 0xc6000
	v_lshl_add_u64 v[188:189], v[170:171], 0, s[6:7]
	v_pk_mul_f32 v[152:153], v[44:45], v[152:153]
	v_pk_mul_f32 v[154:155], v[46:47], v[154:155]
	v_pk_mul_f32 v[156:157], v[40:41], v[156:157]
	v_pk_mul_f32 v[158:159], v[42:43], v[158:159]
	v_pk_mul_f32 v[152:153], v[152:153], v[36:37]
	v_pk_mul_f32 v[154:155], v[154:155], v[38:39]
	v_pk_mul_f32 v[156:157], v[156:157], v[32:33]
	v_pk_mul_f32 v[158:159], v[158:159], v[34:35]
	v_cvt_pk_bf16_f32 v222, v152, v153
	v_cvt_pk_bf16_f32 v223, v154, v155
	v_cvt_pk_bf16_f32 v224, v156, v157
	v_cvt_pk_bf16_f32 v225, v158, v159
	global_store_dwordx4 v[188:189], v[222:225], off
	v_pk_mul_f32 v[152:153], v[28:29], v[160:161]
	v_pk_mul_f32 v[154:155], v[30:31], v[160:161]
	v_pk_mul_f32 v[156:157], v[24:25], v[160:161]
	v_pk_mul_f32 v[158:159], v[26:27], v[160:161]
	v_exp_f32_e32 v152, v152
	v_exp_f32_e32 v153, v153
	v_exp_f32_e32 v154, v154
	v_exp_f32_e32 v155, v155
	v_exp_f32_e32 v156, v156
	v_exp_f32_e32 v157, v157
	v_exp_f32_e32 v158, v158
	v_exp_f32_e32 v159, v159
	v_pk_add_f32 v[152:153], v[152:153], v[162:163]
	v_pk_add_f32 v[154:155], v[154:155], v[162:163]
	v_pk_add_f32 v[156:157], v[156:157], v[162:163]
	v_pk_add_f32 v[158:159], v[158:159], v[162:163]
	v_rcp_f32_e32 v152, v152
	v_rcp_f32_e32 v153, v153
	v_rcp_f32_e32 v154, v154
	v_rcp_f32_e32 v155, v155
	v_rcp_f32_e32 v156, v156
	v_rcp_f32_e32 v157, v157
	v_rcp_f32_e32 v158, v158
	v_rcp_f32_e32 v159, v159
	s_mov_b64 s[6:7], 0xdc000
	v_lshl_add_u64 v[190:191], v[170:171], 0, s[6:7]
	v_pk_mul_f32 v[152:153], v[28:29], v[152:153]
	v_pk_mul_f32 v[154:155], v[30:31], v[154:155]
	v_pk_mul_f32 v[156:157], v[24:25], v[156:157]
	v_pk_mul_f32 v[158:159], v[26:27], v[158:159]
	v_pk_mul_f32 v[152:153], v[152:153], v[20:21]
	v_pk_mul_f32 v[154:155], v[154:155], v[22:23]
	v_pk_mul_f32 v[156:157], v[156:157], v[16:17]
	v_pk_mul_f32 v[158:159], v[158:159], v[18:19]
	v_cvt_pk_bf16_f32 v226, v152, v153
	v_cvt_pk_bf16_f32 v227, v154, v155
	v_cvt_pk_bf16_f32 v228, v156, v157
	v_cvt_pk_bf16_f32 v229, v158, v159
	global_store_dwordx4 v[190:191], v[226:229], off
	v_pk_mul_f32 v[152:153], v[12:13], v[160:161]
	v_pk_mul_f32 v[154:155], v[14:15], v[160:161]
	v_pk_mul_f32 v[156:157], v[8:9], v[160:161]
	v_pk_mul_f32 v[158:159], v[10:11], v[160:161]
	v_exp_f32_e32 v152, v152
	v_exp_f32_e32 v153, v153
	v_exp_f32_e32 v154, v154
	v_exp_f32_e32 v155, v155
	v_exp_f32_e32 v156, v156
	v_exp_f32_e32 v157, v157
	v_exp_f32_e32 v158, v158
	v_exp_f32_e32 v159, v159
	v_pk_add_f32 v[152:153], v[152:153], v[162:163]
	v_pk_add_f32 v[154:155], v[154:155], v[162:163]
	v_pk_add_f32 v[156:157], v[156:157], v[162:163]
	v_pk_add_f32 v[158:159], v[158:159], v[162:163]
	v_rcp_f32_e32 v152, v152
	v_rcp_f32_e32 v153, v153
	v_rcp_f32_e32 v154, v154
	v_rcp_f32_e32 v155, v155
	v_rcp_f32_e32 v156, v156
	v_rcp_f32_e32 v157, v157
	v_rcp_f32_e32 v158, v158
	v_rcp_f32_e32 v159, v159
	s_mov_b64 s[6:7], 0xf2000
	v_lshl_add_u64 v[192:193], v[170:171], 0, s[6:7]
	v_pk_mul_f32 v[152:153], v[12:13], v[152:153]
	v_pk_mul_f32 v[154:155], v[14:15], v[154:155]
	v_pk_mul_f32 v[156:157], v[8:9], v[156:157]
	v_pk_mul_f32 v[158:159], v[10:11], v[158:159]
	v_pk_mul_f32 v[152:153], v[152:153], v[4:5]
	v_pk_mul_f32 v[154:155], v[154:155], v[6:7]
	v_pk_mul_f32 v[156:157], v[156:157], v[0:1]
	v_pk_mul_f32 v[158:159], v[158:159], v[2:3]
	v_cvt_pk_bf16_f32 v230, v152, v153
	v_cvt_pk_bf16_f32 v231, v154, v155
	v_cvt_pk_bf16_f32 v232, v156, v157
	v_cvt_pk_bf16_f32 v233, v158, v159
	global_store_dwordx4 v[192:193], v[230:233], off
	s_cbranch_vccnz .LBB0_1255
	s_andn2_b64 vcc, exec, s[14:15]
	s_cbranch_vccnz .LBB0_1254
	s_barrier
	s_branch .LBB0_1254

; __device__ __forceinline__ unsigned cvt_pk_bf16(float lo, float hi) { unsigned r; asm volatile("v_cvt_pk_bf16_f32 %0, %1, %2" : "=v"(r) : "v"(lo), "v"(hi)); return r; }
; __device__ __forceinline__ float fast_sigmoid(float x) { return __builtin_amdgcn_rcpf(1.0f + __builtin_amdgcn_exp2f(-1.4426950408889634f * x)); }
; __device__ __forceinline__ float silu_f(float x) { return x * fast_sigmoid(x); }
;     __device__ __forceinline__ void operator()(const f32x4 (&acc)[2][2][4][2], const Unit& u, int wr, int wc, int fr, int fq) const {
;         const int row0 = u.pm * BM + wr * 64 + fr, col0 = u.pn * HALF + wc * 32 + 8 * fq;
; #pragma unroll
;         for (int ai = 0; ai < 2; ++ai)
; #pragma unroll
;             for (int m = 0; m < 4; ++m) {
;                 bf16_t* p = O + (size_t)(row0 + ai * HALF + m * 16) * DFF_ + col0;
;                 const f32x4 a0 = acc[ai][0][m][0], a1 = acc[ai][0][m][1], b0 = acc[ai][1][m][0], b1 = acc[ai][1][m][1];
;                 float h[8];
; #pragma unroll
;                 for (int e = 0; e < 4; ++e) { h[e] = silu_f(a0[e]) * b0[e]; h[4 + e] = silu_f(a1[e]) * b1[e]; }
;                 u32x4 w; w.x = cvt_pk_bf16(h[0], h[1]); w.y = cvt_pk_bf16(h[2], h[3]); w.z = cvt_pk_bf16(h[4], h[5]); w.w = cvt_pk_bf16(h[6], h[7]);
;                 *(u32x4*)p = w;
;             }
.LBB0_1486:
	s_andn2_b64 vcc, exec, s[10:11]
	s_mov_b64 s[10:11], -1
	v_mov_b32_e32 v160, 0xbfb8aa3b
	v_mov_b32_e32 v161, 0xbfb8aa3b
	v_mov_b32_e32 v162, 1.0
	v_mov_b32_e32 v163, 1.0
	v_lshl_or_b32 v164, s6, 7, v148
	v_lshl_add_u32 v166, s38, 8, v146
	v_mov_b64_e32 v[168:169], s[14:15]
	v_ashrrev_i32_e32 v165, 31, v164
	v_mad_i64_i32 v[170:171], s[6:7], v166, s60, v[168:169]
	v_lshlrev_b64 v[164:165], 1, v[164:165]
	v_lshl_add_u64 v[170:171], v[170:171], 0, v[164:165]
	v_pk_mul_f32 v[152:153], v[124:125], v[160:161]
	v_pk_mul_f32 v[154:155], v[126:127], v[160:161]
	v_pk_mul_f32 v[156:157], v[120:121], v[160:161]
	v_pk_mul_f32 v[158:159], v[122:123], v[160:161]
	v_exp_f32_e32 v152, v152
	v_exp_f32_e32 v153, v153
	v_exp_f32_e32 v154, v154
	v_exp_f32_e32 v155, v155
	v_exp_f32_e32 v156, v156
	v_exp_f32_e32 v157, v157
	v_exp_f32_e32 v158, v158
	v_exp_f32_e32 v159, v159
	v_pk_add_f32 v[152:153], v[152:153], v[162:163]
	v_pk_add_f32 v[154:155], v[154:155], v[162:163]
	v_pk_add_f32 v[156:157], v[156:157], v[162:163]
	v_pk_add_f32 v[158:159], v[158:159], v[162:163]
	v_rcp_f32_e32 v152, v152
	v_rcp_f32_e32 v153, v153
	v_rcp_f32_e32 v154, v154
	v_rcp_f32_e32 v155, v155
	v_rcp_f32_e32 v156, v156
	v_rcp_f32_e32 v157, v157
	v_rcp_f32_e32 v158, v158
	v_rcp_f32_e32 v159, v159
	v_pk_mul_f32 v[152:153], v[124:125], v[152:153]
	v_pk_mul_f32 v[154:155], v[126:127], v[154:155]
	v_pk_mul_f32 v[156:157], v[120:121], v[156:157]
	v_pk_mul_f32 v[158:159], v[122:123], v[158:159]
	v_pk_mul_f32 v[152:153], v[152:153], v[116:117]
	v_pk_mul_f32 v[154:155], v[154:155], v[118:119]
	v_pk_mul_f32 v[156:157], v[156:157], v[112:113]
	v_pk_mul_f32 v[158:159], v[158:159], v[114:115]
	v_cvt_pk_bf16_f32 v194, v152, v153
	v_cvt_pk_bf16_f32 v195, v154, v155
	v_cvt_pk_bf16_f32 v196, v156, v157
	v_cvt_pk_bf16_f32 v197, v158, v159
	global_store_dwordx4 v[170:171], v[194:197], off
	v_pk_mul_f32 v[152:153], v[108:109], v[160:161]
	v_pk_mul_f32 v[154:155], v[110:111], v[160:161]
	v_pk_mul_f32 v[156:157], v[104:105], v[160:161]
	v_pk_mul_f32 v[158:159], v[106:107], v[160:161]
	v_exp_f32_e32 v152, v152
	v_exp_f32_e32 v153, v153
	v_exp_f32_e32 v154, v154
	v_exp_f32_e32 v155, v155
	v_exp_f32_e32 v156, v156
	v_exp_f32_e32 v157, v157
	v_exp_f32_e32 v158, v158
	v_exp_f32_e32 v159, v159
	v_pk_add_f32 v[152:153], v[152:153], v[162:163]
	v_pk_add_f32 v[154:155], v[154:155], v[162:163]
	v_pk_add_f32 v[156:157], v[156:157], v[162:163]
	v_pk_add_f32 v[158:159], v[158:159], v[162:163]
	v_rcp_f32_e32 v152, v152
	v_rcp_f32_e32 v153, v153
	v_rcp_f32_e32 v154, v154
	v_rcp_f32_e32 v155, v155
	v_rcp_f32_e32 v156, v156
	v_rcp_f32_e32 v157, v157
	v_rcp_f32_e32 v158, v158
	v_rcp_f32_e32 v159, v159
	s_mov_b64 s[6:7], 0x16000
	v_lshl_add_u64 v[188:189], v[170:171], 0, s[6:7]
	v_pk_mul_f32 v[152:153], v[108:109], v[152:153]
	v_pk_mul_f32 v[154:155], v[110:111], v[154:155]
	v_pk_mul_f32 v[156:157], v[104:105], v[156:157]
	v_pk_mul_f32 v[158:159], v[106:107], v[158:159]
	v_pk_mul_f32 v[152:153], v[152:153], v[100:101]
	v_pk_mul_f32 v[154:155], v[154:155], v[102:103]
	v_pk_mul_f32 v[156:157], v[156:157], v[96:97]
	v_pk_mul_f32 v[158:159], v[158:159], v[98:99]
	v_cvt_pk_bf16_f32 v222, v152, v153
	v_cvt_pk_bf16_f32 v223, v154, v155
	v_cvt_pk_bf16_f32 v224, v156, v157
	v_cvt_pk_bf16_f32 v225, v158, v159
	global_store_dwordx4 v[188:189], v[222:225], off
	v_pk_mul_f32 v[152:153], v[92:93], v[160:161]
	v_pk_mul_f32 v[154:155], v[94:95], v[160:161]
	v_pk_mul_f32 v[156:157], v[88:89], v[160:161]
	v_pk_mul_f32 v[158:159], v[90:91], v[160:161]
	v_exp_f32_e32 v152, v152
	v_exp_f32_e32 v153, v153
	v_exp_f32_e32 v154, v154
	v_exp_f32_e32 v155, v155
	v_exp_f32_e32 v156, v156
	v_exp_f32_e32 v157, v157
	v_exp_f32_e32 v158, v158
	v_exp_f32_e32 v159, v159
	v_pk_add_f32 v[152:153], v[152:153], v[162:163]
	v_pk_add_f32 v[154:155], v[154:155], v[162:163]
	v_pk_add_f32 v[156:157], v[156:157], v[162:163]
	v_pk_add_f32 v[158:159], v[158:159], v[162:163]
	v_rcp_f32_e32 v152, v152
	v_rcp_f32_e32 v153, v153
	v_rcp_f32_e32 v154, v154
	v_rcp_f32_e32 v155, v155
	v_rcp_f32_e32 v156, v156
	v_rcp_f32_e32 v157, v157
	v_rcp_f32_e32 v158, v158
	v_rcp_f32_e32 v159, v159
	s_mov_b64 s[6:7], 0x2c000
	v_lshl_add_u64 v[190:191], v[170:171], 0, s[6:7]
	v_pk_mul_f32 v[152:153], v[92:93], v[152:153]
	v_pk_mul_f32 v[154:155], v[94:95], v[154:155]
	v_pk_mul_f32 v[156:157], v[88:89], v[156:157]
	v_pk_mul_f32 v[158:159], v[90:91], v[158:159]
	v_pk_mul_f32 v[152:153], v[152:153], v[84:85]
	v_pk_mul_f32 v[154:155], v[154:155], v[86:87]
	v_pk_mul_f32 v[156:157], v[156:157], v[80:81]
	v_pk_mul_f32 v[158:159], v[158:159], v[82:83]
	v_cvt_pk_bf16_f32 v226, v152, v153
	v_cvt_pk_bf16_f32 v227, v154, v155
	v_cvt_pk_bf16_f32 v228, v156, v157
	v_cvt_pk_bf16_f32 v229, v158, v159
	global_store_dwordx4 v[190:191], v[226:229], off
	v_pk_mul_f32 v[152:153], v[76:77], v[160:161]
	v_pk_mul_f32 v[154:155], v[78:79], v[160:161]
	v_pk_mul_f32 v[156:157], v[72:73], v[160:161]
	v_pk_mul_f32 v[158:159], v[74:75], v[160:161]
	v_exp_f32_e32 v152, v152
	v_exp_f32_e32 v153, v153
	v_exp_f32_e32 v154, v154
	v_exp_f32_e32 v155, v155
	v_exp_f32_e32 v156, v156
	v_exp_f32_e32 v157, v157
	v_exp_f32_e32 v158, v158
	v_exp_f32_e32 v159, v159
	v_pk_add_f32 v[152:153], v[152:153], v[162:163]
	v_pk_add_f32 v[154:155], v[154:155], v[162:163]
	v_pk_add_f32 v[156:157], v[156:157], v[162:163]
	v_pk_add_f32 v[158:159], v[158:159], v[162:163]
	v_rcp_f32_e32 v152, v152
	v_rcp_f32_e32 v153, v153
	v_rcp_f32_e32 v154, v154
	v_rcp_f32_e32 v155, v155
	v_rcp_f32_e32 v156, v156
	v_rcp_f32_e32 v157, v157
	v_rcp_f32_e32 v158, v158
	v_rcp_f32_e32 v159, v159
	s_mov_b64 s[6:7], 0x42000
	v_lshl_add_u64 v[192:193], v[170:171], 0, s[6:7]
; __device__ __forceinline__ unsigned cvt_pk_bf16(float lo, float hi) { unsigned r; asm volatile("v_cvt_pk_bf16_f32 %0, %1, %2" : "=v"(r) : "v"(lo), "v"(hi)); return r; }
; __device__ __forceinline__ float fast_sigmoid(float x) { return __builtin_amdgcn_rcpf(1.0f + __builtin_amdgcn_exp2f(-1.4426950408889634f * x)); }
; __device__ __forceinline__ float silu_f(float x) { return x * fast_sigmoid(x); }
;     __device__ __forceinline__ void operator()(const f32x4 (&acc)[2][2][4][2], const Unit& u, int wr, int wc, int fr, int fq) const {
;         const int row0 = u.pm * BM + wr * 64 + fr, col0 = u.pn * HALF + wc * 32 + 8 * fq;
; #pragma unroll
;         for (int ai = 0; ai < 2; ++ai)
; #pragma unroll
;             for (int m = 0; m < 4; ++m) {
;                 bf16_t* p = O + (size_t)(row0 + ai * HALF + m * 16) * DFF_ + col0;
;                 const f32x4 a0 = acc[ai][0][m][0], a1 = acc[ai][0][m][1], b0 = acc[ai][1][m][0], b1 = acc[ai][1][m][1];
;                 float h[8];
; #pragma unroll
;                 for (int e = 0; e < 4; ++e) { h[e] = silu_f(a0[e]) * b0[e]; h[4 + e] = silu_f(a1[e]) * b1[e]; }
;                 u32x4 w; w.x = cvt_pk_bf16(h[0], h[1]); w.y = cvt_pk_bf16(h[2], h[3]); w.z = cvt_pk_bf16(h[4], h[5]); w.w = cvt_pk_bf16(h[6], h[7]);
;                 *(u32x4*)p = w;
;             }
	v_pk_mul_f32 v[152:153], v[76:77], v[152:153]
	v_pk_mul_f32 v[154:155], v[78:79], v[154:155]
	v_pk_mul_f32 v[156:157], v[72:73], v[156:157]
	v_pk_mul_f32 v[158:159], v[74:75], v[158:159]
	v_pk_mul_f32 v[152:153], v[152:153], v[68:69]
	v_pk_mul_f32 v[154:155], v[154:155], v[70:71]
	v_pk_mul_f32 v[156:157], v[156:157], v[64:65]
	v_pk_mul_f32 v[158:159], v[158:159], v[66:67]
	v_cvt_pk_bf16_f32 v230, v152, v153
	v_cvt_pk_bf16_f32 v231, v154, v155
	v_cvt_pk_bf16_f32 v232, v156, v157
	v_cvt_pk_bf16_f32 v233, v158, v159
	global_store_dwordx4 v[192:193], v[230:233], off
	v_pk_mul_f32 v[152:153], v[60:61], v[160:161]
	v_pk_mul_f32 v[154:155], v[62:63], v[160:161]
	v_pk_mul_f32 v[156:157], v[56:57], v[160:161]
	v_pk_mul_f32 v[158:159], v[58:59], v[160:161]
	v_exp_f32_e32 v152, v152
	v_exp_f32_e32 v153, v153
	v_exp_f32_e32 v154, v154
	v_exp_f32_e32 v155, v155
	v_exp_f32_e32 v156, v156
	v_exp_f32_e32 v157, v157
	v_exp_f32_e32 v158, v158
	v_exp_f32_e32 v159, v159
	v_pk_add_f32 v[152:153], v[152:153], v[162:163]
	v_pk_add_f32 v[154:155], v[154:155], v[162:163]
	v_pk_add_f32 v[156:157], v[156:157], v[162:163]
	v_pk_add_f32 v[158:159], v[158:159], v[162:163]
	v_rcp_f32_e32 v152, v152
	v_rcp_f32_e32 v153, v153
	v_rcp_f32_e32 v154, v154
	v_rcp_f32_e32 v155, v155
	v_rcp_f32_e32 v156, v156
	v_rcp_f32_e32 v157, v157
	v_rcp_f32_e32 v158, v158
	v_rcp_f32_e32 v159, v159
	s_mov_b64 s[6:7], 0xb0000
	v_lshl_add_u64 v[186:187], v[170:171], 0, s[6:7]
	v_pk_mul_f32 v[152:153], v[60:61], v[152:153]
	v_pk_mul_f32 v[154:155], v[62:63], v[154:155]
	v_pk_mul_f32 v[156:157], v[56:57], v[156:157]
	v_pk_mul_f32 v[158:159], v[58:59], v[158:159]
	v_pk_mul_f32 v[152:153], v[152:153], v[52:53]
	v_pk_mul_f32 v[154:155], v[154:155], v[54:55]
	v_pk_mul_f32 v[156:157], v[156:157], v[48:49]
	v_pk_mul_f32 v[158:159], v[158:159], v[50:51]
	v_cvt_pk_bf16_f32 v194, v152, v153
	v_cvt_pk_bf16_f32 v195, v154, v155
	v_cvt_pk_bf16_f32 v196, v156, v157
	v_cvt_pk_bf16_f32 v197, v158, v159
	global_store_dwordx4 v[186:187], v[194:197], off
	v_pk_mul_f32 v[152:153], v[44:45], v[160:161]
	v_pk_mul_f32 v[154:155], v[46:47], v[160:161]
	v_pk_mul_f32 v[156:157], v[40:41], v[160:161]
	v_pk_mul_f32 v[158:159], v[42:43], v[160:161]
	v_exp_f32_e32 v152, v152
	v_exp_f32_e32 v153, v153
	v_exp_f32_e32 v154, v154
	v_exp_f32_e32 v155, v155
	v_exp_f32_e32 v156, v156
	v_exp_f32_e32 v157, v157
	v_exp_f32_e32 v158, v158
	v_exp_f32_e32 v159, v159
	v_pk_add_f32 v[152:153], v[152:153], v[162:163]
	v_pk_add_f32 v[154:155], v[154:155], v[162:163]
	v_pk_add_f32 v[156:157], v[156:157], v[162:163]
	v_pk_add_f32 v[158:159], v[158:159], v[162:163]
	v_rcp_f32_e32 v152, v152
	v_rcp_f32_e32 v153, v153
	v_rcp_f32_e32 v154, v154
	v_rcp_f32_e32 v155, v155
	v_rcp_f32_e32 v156, v156
	v_rcp_f32_e32 v157, v157
	v_rcp_f32_e32 v158, v158
	v_rcp_f32_e32 v159, v159
	s_mov_b64 s[6:7], 0xc6000
	v_lshl_add_u64 v[188:189], v[170:171], 0, s[6:7]
	v_pk_mul_f32 v[152:153], v[44:45], v[152:153]
	v_pk_mul_f32 v[154:155], v[46:47], v[154:155]
	v_pk_mul_f32 v[156:157], v[40:41], v[156:157]
	v_pk_mul_f32 v[158:159], v[42:43], v[158:159]
	v_pk_mul_f32 v[152:153], v[152:153], v[36:37]
	v_pk_mul_f32 v[154:155], v[154:155], v[38:39]
	v_pk_mul_f32 v[156:157], v[156:157], v[32:33]
	v_pk_mul_f32 v[158:159], v[158:159], v[34:35]
	v_cvt_pk_bf16_f32 v222, v152, v153
	v_cvt_pk_bf16_f32 v223, v154, v155
	v_cvt_pk_bf16_f32 v224, v156, v157
	v_cvt_pk_bf16_f32 v225, v158, v159
	global_store_dwordx4 v[188:189], v[222:225], off
	v_pk_mul_f32 v[152:153], v[28:29], v[160:161]
	v_pk_mul_f32 v[154:155], v[30:31], v[160:161]
	v_pk_mul_f32 v[156:157], v[24:25], v[160:161]
	v_pk_mul_f32 v[158:159], v[26:27], v[160:161]
	v_exp_f32_e32 v152, v152
	v_exp_f32_e32 v153, v153
	v_exp_f32_e32 v154, v154
	v_exp_f32_e32 v155, v155
	v_exp_f32_e32 v156, v156
	v_exp_f32_e32 v157, v157
	v_exp_f32_e32 v158, v158
	v_exp_f32_e32 v159, v159
	v_pk_add_f32 v[152:153], v[152:153], v[162:163]
	v_pk_add_f32 v[154:155], v[154:155], v[162:163]
	v_pk_add_f32 v[156:157], v[156:157], v[162:163]
	v_pk_add_f32 v[158:159], v[158:159], v[162:163]
	v_rcp_f32_e32 v152, v152
	v_rcp_f32_e32 v153, v153
	v_rcp_f32_e32 v154, v154
	v_rcp_f32_e32 v155, v155
	v_rcp_f32_e32 v156, v156
	v_rcp_f32_e32 v157, v157
	v_rcp_f32_e32 v158, v158
	v_rcp_f32_e32 v159, v159
	s_mov_b64 s[6:7], 0xdc000
	v_lshl_add_u64 v[190:191], v[170:171], 0, s[6:7]
	v_pk_mul_f32 v[152:153], v[28:29], v[152:153]
	v_pk_mul_f32 v[154:155], v[30:31], v[154:155]
	v_pk_mul_f32 v[156:157], v[24:25], v[156:157]
	v_pk_mul_f32 v[158:159], v[26:27], v[158:159]
	v_pk_mul_f32 v[152:153], v[152:153], v[20:21]
	v_pk_mul_f32 v[154:155], v[154:155], v[22:23]
	v_pk_mul_f32 v[156:157], v[156:157], v[16:17]
	v_pk_mul_f32 v[158:159], v[158:159], v[18:19]
	v_cvt_pk_bf16_f32 v226, v152, v153
	v_cvt_pk_bf16_f32 v227, v154, v155
	v_cvt_pk_bf16_f32 v228, v156, v157
	v_cvt_pk_bf16_f32 v229, v158, v159
	global_store_dwordx4 v[190:191], v[226:229], off
	v_pk_mul_f32 v[152:153], v[12:13], v[160:161]
	v_pk_mul_f32 v[154:155], v[14:15], v[160:161]
	v_pk_mul_f32 v[156:157], v[8:9], v[160:161]
	v_pk_mul_f32 v[158:159], v[10:11], v[160:161]
	v_exp_f32_e32 v152, v152
	v_exp_f32_e32 v153, v153
	v_exp_f32_e32 v154, v154
	v_exp_f32_e32 v155, v155
	v_exp_f32_e32 v156, v156
	v_exp_f32_e32 v157, v157
	v_exp_f32_e32 v158, v158
	v_exp_f32_e32 v159, v159
	v_pk_add_f32 v[152:153], v[152:153], v[162:163]
	v_pk_add_f32 v[154:155], v[154:155], v[162:163]
	v_pk_add_f32 v[156:157], v[156:157], v[162:163]
	v_pk_add_f32 v[158:159], v[158:159], v[162:163]
	v_rcp_f32_e32 v152, v152
	v_rcp_f32_e32 v153, v153
	v_rcp_f32_e32 v154, v154
	v_rcp_f32_e32 v155, v155
	v_rcp_f32_e32 v156, v156
	v_rcp_f32_e32 v157, v157
	v_rcp_f32_e32 v158, v158
	v_rcp_f32_e32 v159, v159
	s_mov_b64 s[6:7], 0xf2000
	v_lshl_add_u64 v[192:193], v[170:171], 0, s[6:7]
	v_pk_mul_f32 v[152:153], v[12:13], v[152:153]
	v_pk_mul_f32 v[154:155], v[14:15], v[154:155]
	v_pk_mul_f32 v[156:157], v[8:9], v[156:157]
	v_pk_mul_f32 v[158:159], v[10:11], v[158:159]
	v_pk_mul_f32 v[152:153], v[152:153], v[4:5]
	v_pk_mul_f32 v[154:155], v[154:155], v[6:7]
	v_pk_mul_f32 v[156:157], v[156:157], v[0:1]
	v_pk_mul_f32 v[158:159], v[158:159], v[2:3]
	v_cvt_pk_bf16_f32 v230, v152, v153
	v_cvt_pk_bf16_f32 v231, v154, v155
	v_cvt_pk_bf16_f32 v232, v156, v157
	v_cvt_pk_bf16_f32 v233, v158, v159
	global_store_dwordx4 v[192:193], v[230:233], off
	s_cbranch_vccnz .LBB0_1475
	s_andn2_b64 vcc, exec, s[12:13]
	s_cbranch_vccnz .LBB0_1474
	s_barrier
	s_branch .LBB0_1474

; #define PG8_STAGE(bufoff, gbase, voff) do { _Pragma("unroll") for (int _i = 0; _i < 2; ++_i) \
;         __builtin_amdgcn_global_load_lds((const unsigned*)((const char*)(gbase) + (voff)[_i]), (PG8_LAS unsigned*)(lds + (bufoff) + ldsw + _i * 8192), 16, 0, 0); } while (0)
; #define PG8_LDA(dst, b, h) do { _Pragma("unroll") for (int m = 0; m < 4; ++m) _Pragma("unroll") for (int k = 0; k < 2; ++k) dst[m][k] = *(const PG8_LAS bf16x8*)(lds + PG8_SA(b, h) + aoff + m * 2048 + k * 1024); } while (0)
; #define PG8_LDB(dst, b, h) do { _Pragma("unroll") for (int n = 0; n < 2; ++n) _Pragma("unroll") for (int k = 0; k < 2; ++k) dst[n][k] = *(const PG8_LAS bf16x8*)(lds + PG8_SB(b, h) + boff + n * 2048 + k * 1024); } while (0)
; #define PG8_BAR __builtin_amdgcn_s_barrier()
;     ...
;         const bool has_next = S.next(ui + 1, nxt);
;         const char* nA = has_next ? (const char*)g.A + (size_t)nxt.pm * tstep : cA; const char* nB = has_next ? (const char*)g.Bt + (size_t)nxt.pn * tstep : cB;
;         if constexpr (SP2 && ZSPLIT > 0) {
;     ...
;         for (int t = 0; t < ZSPLIT; t += 2) {
;             const bool last = (t == nt - 2);
;             const char* a1 = cA + (size_t)(t + 1) * kstep;
;             const char* a2 = last ? nA : cA + (size_t)(t + 2) * kstep; const char* b2 = last ? nB : cB + (size_t)(t + 2) * kstep;
;             const char* a3 = a2 + kstep; const char* b3 = b2 + kstep;
;             if (last && has_next) S.a_ready(nxt);
;             if constexpr (SP2) {
;             PG8_LDB(B0, 0, 0); PG8_LDB(B1, 0, 1); PG8_SCHED; PG8_LDA(At, 0, 0); PG8_STAGE(PG8_SA(1, 1), a1 + hstep, voffA);
;             PG8_WAIT_V(8); PG8_WAIT_L(0); PG8_BAR; PG8_MMA2(0); PG8_BAR; PG8_SCHED;
;             PG8_LDA(At, 0, 1); PG8_STAGE(PG8_SB(0, 0), b2, voffB); PG8_STAGE(PG8_SB(0, 1), b2 + hstep, voffB); PG8_STAGE(PG8_SA(0, 0), a2, voffA);
;             PG8_WAIT_V(8); PG8_WAIT_L(0); PG8_BAR; PG8_MMA2(1); PG8_BAR; PG8_SCHED;
;             PG8_LDB(B0, 1, 0); PG8_LDB(B1, 1, 1); PG8_SCHED; PG8_LDA(At, 1, 0); PG8_STAGE(PG8_SA(0, 1), a2 + hstep, voffA);
;             PG8_WAIT_V(8); PG8_WAIT_L(0); PG8_BAR; PG8_MMA2(0); PG8_BAR; PG8_SCHED;
;             PG8_LDA(At, 1, 1); PG8_STAGE(PG8_SB(1, 0), b3, voffB); PG8_STAGE(PG8_SB(1, 1), b3 + hstep, voffB); PG8_STAGE(PG8_SA(1, 0), a3, voffA);
;             PG8_WAIT_V(8); PG8_WAIT_L(0); PG8_BAR; PG8_MMA2(1); PG8_BAR; PG8_SCHED;
.LBB0_2259:
	s_ashr_i32 s61, s60, 31
	ds_read_b128 v[0:3], v148
	ds_read_b128 v[4:7], v148 offset:1024
	ds_read_b128 v[8:11], v148 offset:2048
	ds_read_b128 v[12:15], v148 offset:3072
	s_lshl_b64 s[34:35], s[60:61], 19
	s_add_u32 s62, s29, s34
	s_addc_u32 s63, s76, s35
	s_ashr_i32 s59, s58, 31
	s_lshl_b64 s[34:35], s[58:59], 19
	s_add_u32 s64, s77, s34
	s_addc_u32 s65, s78, s35
	s_add_u32 s34, s68, 0x40080
	s_addc_u32 s35, s69, 0
	s_add_i32 s95, s67, 0xc000
	v_lshl_add_u64 v[48:49], s[34:35], 0, v[134:135]
	s_mov_b32 m0, s95
	s_add_i32 s59, s67, 0xe000
	ds_read_b128 v[16:19], v146
	ds_read_b128 v[20:23], v146 offset:1024
	ds_read_b128 v[24:27], v146 offset:2048
	ds_read_b128 v[28:31], v146 offset:3072
	ds_read_b128 v[32:35], v146 offset:4096
	ds_read_b128 v[36:39], v146 offset:5120
	ds_read_b128 v[40:43], v146 offset:6144
	ds_read_b128 v[44:47], v146 offset:7168
	global_load_lds_dwordx4 v[48:49], off
	v_lshl_add_u64 v[48:49], s[34:35], 0, v[130:131]
	s_mov_b32 m0, s59
	s_nop 0
	global_load_lds_dwordx4 v[48:49], off
	s_waitcnt vmcnt(6)
	s_waitcnt lgkmcnt(0)
	s_barrier
	s_setprio 1
	s_waitcnt lgkmcnt(0)
	v_mfma_f32_16x16x32_bf16 v[48:51], v[0:3], v[16:19], 0
	v_mfma_f32_16x16x32_bf16 v[16:19], v[8:11], v[16:19], 0
	v_mfma_f32_16x16x32_bf16 v[48:51], v[4:7], v[20:23], v[48:51]
	v_mfma_f32_16x16x32_bf16 v[16:19], v[12:15], v[20:23], v[16:19]
	v_mfma_f32_16x16x32_bf16 v[20:23], v[0:3], v[24:27], 0
	v_mfma_f32_16x16x32_bf16 v[24:27], v[8:11], v[24:27], 0
	v_mfma_f32_16x16x32_bf16 v[20:23], v[4:7], v[28:31], v[20:23]
	v_mfma_f32_16x16x32_bf16 v[24:27], v[12:15], v[28:31], v[24:27]
	v_mfma_f32_16x16x32_bf16 v[28:31], v[0:3], v[32:35], 0
	v_mfma_f32_16x16x32_bf16 v[32:35], v[8:11], v[32:35], 0
	v_mfma_f32_16x16x32_bf16 v[28:31], v[4:7], v[36:39], v[28:31]
	v_mfma_f32_16x16x32_bf16 v[32:35], v[12:15], v[36:39], v[32:35]
	v_mfma_f32_16x16x32_bf16 v[36:39], v[0:3], v[40:43], 0
	v_mfma_f32_16x16x32_bf16 v[40:43], v[8:11], v[40:43], 0
	v_mfma_f32_16x16x32_bf16 v[36:39], v[4:7], v[44:47], v[36:39]
	v_mfma_f32_16x16x32_bf16 v[40:43], v[12:15], v[44:47], v[40:43]
	s_setprio 0
	s_barrier
	v_lshl_add_u64 v[56:57], s[70:71], 0, v[132:133]
	s_add_i32 s93, s3, s79
	v_lshl_add_u64 v[58:59], v[56:57], 0, s[22:23]
	s_mov_b32 m0, s93
	s_add_i32 s61, s93, 0x2000
	ds_read_b128 v[44:47], v146 offset:16384
	ds_read_b128 v[52:55], v146 offset:17408
	ds_read_b128 v[64:67], v146 offset:18432
	ds_read_b128 v[68:71], v146 offset:19456
	ds_read_b128 v[72:75], v146 offset:20480
	ds_read_b128 v[76:79], v146 offset:21504
	ds_read_b128 v[80:83], v146 offset:22528
	ds_read_b128 v[84:87], v146 offset:23552
	global_load_lds_dwordx4 v[58:59], off
	v_lshl_add_u64 v[58:59], s[70:71], 0, v[128:129]
	s_add_u32 s34, s70, 0x40100
	v_lshl_add_u64 v[60:61], v[58:59], 0, s[22:23]
	s_mov_b32 m0, s61
	s_addc_u32 s35, s71, 0
	s_add_i32 s91, s89, s79
	global_load_lds_dwordx4 v[60:61], off
	v_lshl_add_u64 v[60:61], s[34:35], 0, v[132:133]
	s_mov_b32 m0, s91
	s_add_i32 s92, s91, 0x2000
	v_lshl_add_u64 v[60:61], s[34:35], 0, v[128:129]
	s_mov_b32 m0, s92
	s_nop 0
	v_lshl_add_u64 v[60:61], s[68:69], 0, v[134:135]
	v_lshl_add_u64 v[62:63], v[60:61], 0, s[22:23]
	s_mov_b32 m0, s67
	s_nop 0
	global_load_lds_dwordx4 v[62:63], off
	v_lshl_add_u64 v[62:63], s[68:69], 0, v[130:131]
	v_lshl_add_u64 v[88:89], v[62:63], 0, s[22:23]
	s_mov_b32 m0, s81
	s_nop 0
	global_load_lds_dwordx4 v[88:89], off
	s_waitcnt vmcnt(6)
	s_waitcnt lgkmcnt(0)
	s_barrier
	s_setprio 1
	s_waitcnt lgkmcnt(0)
	v_mfma_f32_16x16x32_bf16 v[88:91], v[0:3], v[44:47], 0
	v_mfma_f32_16x16x32_bf16 v[44:47], v[8:11], v[44:47], 0
	v_mfma_f32_16x16x32_bf16 v[88:91], v[4:7], v[52:55], v[88:91]
	v_mfma_f32_16x16x32_bf16 v[44:47], v[12:15], v[52:55], v[44:47]
	v_mfma_f32_16x16x32_bf16 v[52:55], v[0:3], v[64:67], 0
	v_mfma_f32_16x16x32_bf16 v[64:67], v[8:11], v[64:67], 0
	v_mfma_f32_16x16x32_bf16 v[52:55], v[4:7], v[68:71], v[52:55]
	v_mfma_f32_16x16x32_bf16 v[64:67], v[12:15], v[68:71], v[64:67]
	v_mfma_f32_16x16x32_bf16 v[68:71], v[0:3], v[72:75], 0
	v_mfma_f32_16x16x32_bf16 v[0:3], v[0:3], v[80:83], 0
	v_mfma_f32_16x16x32_bf16 v[68:71], v[4:7], v[76:79], v[68:71]
	v_mfma_f32_16x16x32_bf16 v[72:75], v[8:11], v[72:75], 0
	v_mfma_f32_16x16x32_bf16 v[2:5], v[4:7], v[84:87], v[0:3]
	v_mfma_f32_16x16x32_bf16 v[6:9], v[8:11], v[80:83], 0
	v_mfma_f32_16x16x32_bf16 v[72:75], v[12:15], v[76:79], v[72:75]
	v_mfma_f32_16x16x32_bf16 v[6:9], v[12:15], v[84:87], v[6:9]
	s_setprio 0
	s_barrier
	s_add_i32 s97, 0, 0x18000
	v_add_u32_e32 v0, s97, v145
	ds_read_b128 v[10:13], v0
	ds_read_b128 v[76:79], v0 offset:1024
	ds_read_b128 v[80:83], v0 offset:2048
	ds_read_b128 v[84:87], v0 offset:3072
	s_add_u32 s34, s68, 0x40100
	s_addc_u32 s35, s69, 0
	s_mov_b32 m0, s83
	v_lshl_add_u64 v[14:15], s[34:35], 0, v[134:135]
	ds_read_b128 v[92:95], v146 offset:32768
	ds_read_b128 v[96:99], v146 offset:33792
	ds_read_b128 v[100:103], v146 offset:34816
	ds_read_b128 v[104:107], v146 offset:35840
	ds_read_b128 v[108:111], v146 offset:36864
	ds_read_b128 v[112:115], v146 offset:37888
	ds_read_b128 v[116:119], v146 offset:38912
	ds_read_b128 v[120:123], v146 offset:39936
	global_load_lds_dwordx4 v[14:15], off
	v_lshl_add_u64 v[14:15], s[34:35], 0, v[130:131]
	s_mov_b32 m0, s84
	s_nop 0
	global_load_lds_dwordx4 v[14:15], off
	s_waitcnt vmcnt(6)
	s_waitcnt lgkmcnt(0)
	s_barrier
; #define PG8_STAGE(bufoff, gbase, voff) do { _Pragma("unroll") for (int _i = 0; _i < 2; ++_i) \
;         __builtin_amdgcn_global_load_lds((const unsigned*)((const char*)(gbase) + (voff)[_i]), (PG8_LAS unsigned*)(lds + (bufoff) + ldsw + _i * 8192), 16, 0, 0); } while (0)
; #define PG8_LDA(dst, b, h) do { _Pragma("unroll") for (int m = 0; m < 4; ++m) _Pragma("unroll") for (int k = 0; k < 2; ++k) dst[m][k] = *(const PG8_LAS bf16x8*)(lds + PG8_SA(b, h) + aoff + m * 2048 + k * 1024); } while (0)
; #define PG8_LDB(dst, b, h) do { _Pragma("unroll") for (int n = 0; n < 2; ++n) _Pragma("unroll") for (int k = 0; k < 2; ++k) dst[n][k] = *(const PG8_LAS bf16x8*)(lds + PG8_SB(b, h) + boff + n * 2048 + k * 1024); } while (0)
; #define PG8_WAIT_V(n) asm volatile("s_waitcnt vmcnt(" #n ")" ::: "memory")
; #define PG8_WAIT_L(n) asm volatile("s_waitcnt lgkmcnt(" #n ")" ::: "memory")
; #define PG8_BAR __builtin_amdgcn_s_barrier()
; #define PG8_SCHED __builtin_amdgcn_sched_barrier(0)
; #define PG8_MMA2(ai) PG8_MMA(ai, 0, At, B0)
; #define PG8_MMA2(ai) PG8_MMA(ai, 1, At, B1)
; #define PG8_MMA2(ai) do { PG8_MMA(ai, 0, At, B0); PG8_MMA(ai, 1, At, B1); } while (0)
;     ...
;             PG8_LDB(B0, 0, 0); PG8_LDB(B1, 0, 1); PG8_SCHED; PG8_LDA(At, 0, 0); PG8_STAGE(PG8_SA(1, 1), a1 + hstep, voffA);
;             PG8_WAIT_V(8); PG8_WAIT_L(0); PG8_BAR; PG8_MMA2(0); PG8_BAR; PG8_SCHED;
;             PG8_LDA(At, 0, 1); PG8_STAGE(PG8_SB(0, 0), b2, voffB); PG8_STAGE(PG8_SB(0, 1), b2 + hstep, voffB); PG8_STAGE(PG8_SA(0, 0), a2, voffA);
;             PG8_WAIT_V(8); PG8_WAIT_L(0); PG8_BAR; PG8_MMA2(1); PG8_BAR; PG8_SCHED;
;             PG8_LDB(B0, 1, 0); PG8_LDB(B1, 1, 1); PG8_SCHED; PG8_LDA(At, 1, 0); PG8_STAGE(PG8_SA(0, 1), a2 + hstep, voffA);
;             PG8_WAIT_V(8); PG8_WAIT_L(0); PG8_BAR; PG8_MMA2(0); PG8_BAR; PG8_SCHED;
;             PG8_LDA(At, 1, 1); PG8_STAGE(PG8_SB(1, 0), b3, voffB); PG8_STAGE(PG8_SB(1, 1), b3 + hstep, voffB); PG8_STAGE(PG8_SA(1, 0), a3, voffA);
;             PG8_WAIT_V(8); PG8_WAIT_L(0); PG8_BAR; PG8_MMA2(1); PG8_BAR; PG8_SCHED;
	s_setprio 1
	s_waitcnt lgkmcnt(0)
	v_mfma_f32_16x16x32_bf16 v[48:51], v[10:13], v[92:95], v[48:51]
	v_mfma_f32_16x16x32_bf16 v[14:17], v[80:83], v[92:95], v[16:19]
	v_mfma_f32_16x16x32_bf16 v[18:21], v[10:13], v[100:103], v[20:23]
	v_mfma_f32_16x16x32_bf16 v[22:25], v[80:83], v[100:103], v[24:27]
	v_mfma_f32_16x16x32_bf16 v[26:29], v[10:13], v[108:111], v[28:31]
	v_mfma_f32_16x16x32_bf16 v[30:33], v[80:83], v[108:111], v[32:35]
	v_mfma_f32_16x16x32_bf16 v[34:37], v[10:13], v[116:119], v[36:39]
	v_mfma_f32_16x16x32_bf16 v[38:41], v[80:83], v[116:119], v[40:43]
	v_mfma_f32_16x16x32_bf16 v[48:51], v[76:79], v[96:99], v[48:51]
	v_mfma_f32_16x16x32_bf16 v[14:17], v[84:87], v[96:99], v[14:17]
	v_mfma_f32_16x16x32_bf16 v[18:21], v[76:79], v[104:107], v[18:21]
	v_mfma_f32_16x16x32_bf16 v[22:25], v[84:87], v[104:107], v[22:25]
	v_mfma_f32_16x16x32_bf16 v[26:29], v[76:79], v[112:115], v[26:29]
	v_mfma_f32_16x16x32_bf16 v[30:33], v[84:87], v[112:115], v[30:33]
	v_mfma_f32_16x16x32_bf16 v[34:37], v[76:79], v[120:123], v[34:37]
	v_mfma_f32_16x16x32_bf16 v[38:41], v[84:87], v[120:123], v[38:41]
	s_setprio 0
	s_barrier
	s_add_i32 s97, s97, s79
	s_add_i32 s82, s97, 0x2000
	s_add_u32 s72, s70, 0x40180
	v_lshl_add_u64 v[42:43], v[56:57], 0, s[26:27]
	s_mov_b32 m0, s97
	s_addc_u32 s73, s71, 0
	s_add_i32 s34, 0, 0x1c000
	ds_read_b128 v[92:95], v146 offset:49152
	ds_read_b128 v[96:99], v146 offset:50176
	ds_read_b128 v[100:103], v146 offset:51200
	ds_read_b128 v[104:107], v146 offset:52224
	ds_read_b128 v[108:111], v146 offset:53248
	ds_read_b128 v[112:115], v146 offset:54272
	ds_read_b128 v[116:119], v146 offset:55296
	ds_read_b128 v[120:123], v146 offset:56320
	global_load_lds_dwordx4 v[42:43], off
	v_lshl_add_u64 v[42:43], v[58:59], 0, s[26:27]
	s_mov_b32 m0, s82
	s_add_i32 s94, s34, s79
	global_load_lds_dwordx4 v[42:43], off
	v_lshl_add_u64 v[42:43], s[72:73], 0, v[132:133]
	s_mov_b32 m0, s94
	s_add_i32 s96, s94, 0x2000
	v_lshl_add_u64 v[42:43], s[72:73], 0, v[128:129]
	s_mov_b32 m0, s96
	s_nop 0
	v_lshl_add_u64 v[42:43], v[60:61], 0, s[26:27]
	s_mov_b32 m0, s85
	s_nop 0
	global_load_lds_dwordx4 v[42:43], off
	v_lshl_add_u64 v[42:43], v[62:63], 0, s[26:27]
	s_mov_b32 m0, s86
	s_nop 0
	global_load_lds_dwordx4 v[42:43], off
	s_waitcnt vmcnt(6)
	s_waitcnt lgkmcnt(0)
	s_barrier
	s_setprio 1
	s_waitcnt lgkmcnt(0)
	v_mfma_f32_16x16x32_bf16 v[88:91], v[10:13], v[92:95], v[88:91]
	v_mfma_f32_16x16x32_bf16 v[42:45], v[80:83], v[92:95], v[44:47]
	v_mfma_f32_16x16x32_bf16 v[52:55], v[10:13], v[100:103], v[52:55]
	v_mfma_f32_16x16x32_bf16 v[64:67], v[80:83], v[100:103], v[64:67]
	v_mfma_f32_16x16x32_bf16 v[68:71], v[10:13], v[108:111], v[68:71]
	v_mfma_f32_16x16x32_bf16 v[72:75], v[80:83], v[108:111], v[72:75]
	v_mfma_f32_16x16x32_bf16 v[2:5], v[10:13], v[116:119], v[2:5]
	v_mfma_f32_16x16x32_bf16 v[6:9], v[80:83], v[116:119], v[6:9]
	v_mfma_f32_16x16x32_bf16 v[88:91], v[76:79], v[96:99], v[88:91]
	v_mfma_f32_16x16x32_bf16 v[42:45], v[84:87], v[96:99], v[42:45]
	v_mfma_f32_16x16x32_bf16 v[52:55], v[76:79], v[104:107], v[52:55]
	v_mfma_f32_16x16x32_bf16 v[64:67], v[84:87], v[104:107], v[64:67]
	v_mfma_f32_16x16x32_bf16 v[68:71], v[76:79], v[112:115], v[68:71]
	v_mfma_f32_16x16x32_bf16 v[72:75], v[84:87], v[112:115], v[72:75]
	v_mfma_f32_16x16x32_bf16 v[2:5], v[76:79], v[120:123], v[2:5]
	v_mfma_f32_16x16x32_bf16 v[6:9], v[84:87], v[120:123], v[6:9]
	s_setprio 0
	s_barrier
	ds_read_b128 v[10:13], v148
	ds_read_b128 v[76:79], v148 offset:1024
	ds_read_b128 v[80:83], v148 offset:2048
	ds_read_b128 v[84:87], v148 offset:3072
	s_add_u32 s72, s68, 0x40180
	s_addc_u32 s73, s69, 0
	s_mov_b32 m0, s95
	v_lshl_add_u64 v[46:47], s[72:73], 0, v[134:135]
	ds_read_b128 v[92:95], v146
	ds_read_b128 v[96:99], v146 offset:1024
	ds_read_b128 v[100:103], v146 offset:2048
	ds_read_b128 v[104:107], v146 offset:3072
	ds_read_b128 v[108:111], v146 offset:4096
	ds_read_b128 v[112:115], v146 offset:5120
	ds_read_b128 v[116:119], v146 offset:6144
	ds_read_b128 v[120:123], v146 offset:7168
	global_load_lds_dwordx4 v[46:47], off
	v_lshl_add_u64 v[46:47], s[72:73], 0, v[130:131]
	s_mov_b32 m0, s59
	s_nop 0
	global_load_lds_dwordx4 v[46:47], off
	s_waitcnt vmcnt(6)
	s_waitcnt lgkmcnt(0)
	s_barrier
	s_setprio 1
	s_waitcnt lgkmcnt(0)
	v_mfma_f32_16x16x32_bf16 v[46:49], v[10:13], v[92:95], v[48:51]
	v_mfma_f32_16x16x32_bf16 v[14:17], v[80:83], v[92:95], v[14:17]
	v_mfma_f32_16x16x32_bf16 v[18:21], v[10:13], v[100:103], v[18:21]
	v_mfma_f32_16x16x32_bf16 v[22:25], v[80:83], v[100:103], v[22:25]
	v_mfma_f32_16x16x32_bf16 v[26:29], v[10:13], v[108:111], v[26:29]
	v_mfma_f32_16x16x32_bf16 v[30:33], v[80:83], v[108:111], v[30:33]
	v_mfma_f32_16x16x32_bf16 v[34:37], v[10:13], v[116:119], v[34:37]
	v_mfma_f32_16x16x32_bf16 v[38:41], v[80:83], v[116:119], v[38:41]
	v_mfma_f32_16x16x32_bf16 v[46:49], v[76:79], v[96:99], v[46:49]
	v_mfma_f32_16x16x32_bf16 v[14:17], v[84:87], v[96:99], v[14:17]
	v_mfma_f32_16x16x32_bf16 v[18:21], v[76:79], v[104:107], v[18:21]
	v_mfma_f32_16x16x32_bf16 v[22:25], v[84:87], v[104:107], v[22:25]
	v_mfma_f32_16x16x32_bf16 v[26:29], v[76:79], v[112:115], v[26:29]
	v_mfma_f32_16x16x32_bf16 v[30:33], v[84:87], v[112:115], v[30:33]
	v_mfma_f32_16x16x32_bf16 v[34:37], v[76:79], v[120:123], v[34:37]
	v_mfma_f32_16x16x32_bf16 v[38:41], v[84:87], v[120:123], v[38:41]
	s_setprio 0
	s_barrier
; #define PG8_STAGE(bufoff, gbase, voff) do { _Pragma("unroll") for (int _i = 0; _i < 2; ++_i) \
;         __builtin_amdgcn_global_load_lds((const unsigned*)((const char*)(gbase) + (voff)[_i]), (PG8_LAS unsigned*)(lds + (bufoff) + ldsw + _i * 8192), 16, 0, 0); } while (0)
; #define PG8_LDA(dst, b, h) do { _Pragma("unroll") for (int m = 0; m < 4; ++m) _Pragma("unroll") for (int k = 0; k < 2; ++k) dst[m][k] = *(const PG8_LAS bf16x8*)(lds + PG8_SA(b, h) + aoff + m * 2048 + k * 1024); } while (0)
; #define PG8_LDB(dst, b, h) do { _Pragma("unroll") for (int n = 0; n < 2; ++n) _Pragma("unroll") for (int k = 0; k < 2; ++k) dst[n][k] = *(const PG8_LAS bf16x8*)(lds + PG8_SB(b, h) + boff + n * 2048 + k * 1024); } while (0)
; #define PG8_WAIT_V(n) asm volatile("s_waitcnt vmcnt(" #n ")" ::: "memory")
; #define PG8_WAIT_L(n) asm volatile("s_waitcnt lgkmcnt(" #n ")" ::: "memory")
; #define PG8_BAR __builtin_amdgcn_s_barrier()
; #define PG8_SCHED __builtin_amdgcn_sched_barrier(0)
; #define PG8_MMA2(ai) PG8_MMA(ai, 0, At, B0)
; #define PG8_MMA2(ai) PG8_MMA(ai, 1, At, B1)
; #define PG8_MMA2(ai) do { PG8_MMA(ai, 0, At, B0); PG8_MMA(ai, 1, At, B1); } while (0)
;     ...
;             PG8_LDB(B0, 0, 0); PG8_LDB(B1, 0, 1); PG8_SCHED; PG8_LDA(At, 0, 0); PG8_STAGE(PG8_SA(1, 1), a1 + hstep, voffA);
;             PG8_WAIT_V(8); PG8_WAIT_L(0); PG8_BAR; PG8_MMA2(0); PG8_BAR; PG8_SCHED;
;             PG8_LDA(At, 0, 1); PG8_STAGE(PG8_SB(0, 0), b2, voffB); PG8_STAGE(PG8_SB(0, 1), b2 + hstep, voffB); PG8_STAGE(PG8_SA(0, 0), a2, voffA);
;             PG8_WAIT_V(8); PG8_WAIT_L(0); PG8_BAR; PG8_MMA2(1); PG8_BAR; PG8_SCHED;
;             PG8_LDB(B0, 1, 0); PG8_LDB(B1, 1, 1); PG8_SCHED; PG8_LDA(At, 1, 0); PG8_STAGE(PG8_SA(0, 1), a2 + hstep, voffA);
;             PG8_WAIT_V(8); PG8_WAIT_L(0); PG8_BAR; PG8_MMA2(0); PG8_BAR; PG8_SCHED;
;             PG8_LDA(At, 1, 1); PG8_STAGE(PG8_SB(1, 0), b3, voffB); PG8_STAGE(PG8_SB(1, 1), b3 + hstep, voffB); PG8_STAGE(PG8_SA(1, 0), a3, voffA);
;             PG8_WAIT_V(8); PG8_WAIT_L(0); PG8_BAR; PG8_MMA2(1); PG8_BAR; PG8_SCHED;
	s_mov_b32 m0, s93
	v_lshl_add_u64 v[50:51], v[56:57], 0, s[36:37]
	s_add_u32 s72, s70, 0x40200
	ds_read_b128 v[92:95], v146 offset:16384
	ds_read_b128 v[96:99], v146 offset:17408
	ds_read_b128 v[100:103], v146 offset:18432
	ds_read_b128 v[104:107], v146 offset:19456
	ds_read_b128 v[108:111], v146 offset:20480
	ds_read_b128 v[112:115], v146 offset:21504
	ds_read_b128 v[116:119], v146 offset:22528
	ds_read_b128 v[120:123], v146 offset:23552
	global_load_lds_dwordx4 v[50:51], off
	v_lshl_add_u64 v[50:51], v[58:59], 0, s[36:37]
	s_mov_b32 m0, s61
	s_addc_u32 s73, s71, 0
	global_load_lds_dwordx4 v[50:51], off
	v_lshl_add_u64 v[50:51], s[72:73], 0, v[132:133]
	s_mov_b32 m0, s91
	s_nop 0
	v_lshl_add_u64 v[50:51], s[72:73], 0, v[128:129]
	s_mov_b32 m0, s92
	s_nop 0
	v_lshl_add_u64 v[50:51], v[60:61], 0, s[36:37]
	s_mov_b32 m0, s67
	s_nop 0
	global_load_lds_dwordx4 v[50:51], off
	v_lshl_add_u64 v[50:51], v[62:63], 0, s[36:37]
	s_mov_b32 m0, s81
	s_nop 0
	global_load_lds_dwordx4 v[50:51], off
	s_waitcnt vmcnt(6)
	s_waitcnt lgkmcnt(0)
	s_barrier
	s_setprio 1
	s_waitcnt lgkmcnt(0)
	v_mfma_f32_16x16x32_bf16 v[88:91], v[10:13], v[92:95], v[88:91]
	v_mfma_f32_16x16x32_bf16 v[42:45], v[80:83], v[92:95], v[42:45]
	v_mfma_f32_16x16x32_bf16 v[50:53], v[10:13], v[100:103], v[52:55]
	v_mfma_f32_16x16x32_bf16 v[64:67], v[80:83], v[100:103], v[64:67]
	v_mfma_f32_16x16x32_bf16 v[68:71], v[10:13], v[108:111], v[68:71]
	v_mfma_f32_16x16x32_bf16 v[72:75], v[80:83], v[108:111], v[72:75]
	v_mfma_f32_16x16x32_bf16 v[2:5], v[10:13], v[116:119], v[2:5]
	v_mfma_f32_16x16x32_bf16 v[6:9], v[80:83], v[116:119], v[6:9]
	v_mfma_f32_16x16x32_bf16 v[88:91], v[76:79], v[96:99], v[88:91]
	v_mfma_f32_16x16x32_bf16 v[42:45], v[84:87], v[96:99], v[42:45]
	v_mfma_f32_16x16x32_bf16 v[50:53], v[76:79], v[104:107], v[50:53]
	v_mfma_f32_16x16x32_bf16 v[64:67], v[84:87], v[104:107], v[64:67]
	v_mfma_f32_16x16x32_bf16 v[68:71], v[76:79], v[112:115], v[68:71]
	v_mfma_f32_16x16x32_bf16 v[72:75], v[84:87], v[112:115], v[72:75]
	v_mfma_f32_16x16x32_bf16 v[2:5], v[76:79], v[120:123], v[2:5]
	v_mfma_f32_16x16x32_bf16 v[6:9], v[84:87], v[120:123], v[6:9]
	s_setprio 0
	s_barrier
	ds_read_b128 v[10:13], v0
	ds_read_b128 v[76:79], v0 offset:1024
	ds_read_b128 v[80:83], v0 offset:2048
	ds_read_b128 v[84:87], v0 offset:3072
	s_add_u32 s72, s68, 0x40200
	s_addc_u32 s73, s69, 0
	s_mov_b32 m0, s83
	v_lshl_add_u64 v[54:55], s[72:73], 0, v[134:135]
	ds_read_b128 v[92:95], v146 offset:32768
	ds_read_b128 v[96:99], v146 offset:33792
	ds_read_b128 v[100:103], v146 offset:34816
	ds_read_b128 v[104:107], v146 offset:35840
	ds_read_b128 v[108:111], v146 offset:36864
	ds_read_b128 v[112:115], v146 offset:37888
	ds_read_b128 v[116:119], v146 offset:38912
	ds_read_b128 v[120:123], v146 offset:39936
	global_load_lds_dwordx4 v[54:55], off
	v_lshl_add_u64 v[54:55], s[72:73], 0, v[130:131]
	s_mov_b32 m0, s84
	s_nop 0
	global_load_lds_dwordx4 v[54:55], off
	s_waitcnt vmcnt(6)
	s_waitcnt lgkmcnt(0)
	s_barrier
	s_setprio 1
	s_waitcnt lgkmcnt(0)
	v_mfma_f32_16x16x32_bf16 v[46:49], v[10:13], v[92:95], v[46:49]
	v_mfma_f32_16x16x32_bf16 v[14:17], v[80:83], v[92:95], v[14:17]
	v_mfma_f32_16x16x32_bf16 v[18:21], v[10:13], v[100:103], v[18:21]
	v_mfma_f32_16x16x32_bf16 v[22:25], v[80:83], v[100:103], v[22:25]
	v_mfma_f32_16x16x32_bf16 v[26:29], v[10:13], v[108:111], v[26:29]
	v_mfma_f32_16x16x32_bf16 v[30:33], v[80:83], v[108:111], v[30:33]
	v_mfma_f32_16x16x32_bf16 v[34:37], v[10:13], v[116:119], v[34:37]
	v_mfma_f32_16x16x32_bf16 v[38:41], v[80:83], v[116:119], v[38:41]
	v_mfma_f32_16x16x32_bf16 v[46:49], v[76:79], v[96:99], v[46:49]
	v_mfma_f32_16x16x32_bf16 v[14:17], v[84:87], v[96:99], v[14:17]
	v_mfma_f32_16x16x32_bf16 v[18:21], v[76:79], v[104:107], v[18:21]
	v_mfma_f32_16x16x32_bf16 v[22:25], v[84:87], v[104:107], v[22:25]
	v_mfma_f32_16x16x32_bf16 v[26:29], v[76:79], v[112:115], v[26:29]
	v_mfma_f32_16x16x32_bf16 v[30:33], v[84:87], v[112:115], v[30:33]
	v_mfma_f32_16x16x32_bf16 v[34:37], v[76:79], v[120:123], v[34:37]
	v_mfma_f32_16x16x32_bf16 v[38:41], v[84:87], v[120:123], v[38:41]
	s_setprio 0
	s_barrier
	s_mov_b32 m0, s97
	v_lshl_add_u64 v[54:55], v[56:57], 0, s[38:39]
	s_add_u32 s72, s70, 0x40280
	ds_read_b128 v[92:95], v146 offset:49152
	ds_read_b128 v[96:99], v146 offset:50176
	ds_read_b128 v[100:103], v146 offset:51200
	ds_read_b128 v[104:107], v146 offset:52224
	ds_read_b128 v[108:111], v146 offset:53248
	ds_read_b128 v[112:115], v146 offset:54272
	ds_read_b128 v[116:119], v146 offset:55296
	ds_read_b128 v[120:123], v146 offset:56320
	global_load_lds_dwordx4 v[54:55], off
	v_lshl_add_u64 v[54:55], v[58:59], 0, s[38:39]
	s_mov_b32 m0, s82
	s_addc_u32 s73, s71, 0
	global_load_lds_dwordx4 v[54:55], off
	v_lshl_add_u64 v[54:55], s[72:73], 0, v[132:133]
	s_mov_b32 m0, s94
	s_nop 0
	v_lshl_add_u64 v[54:55], s[72:73], 0, v[128:129]
	s_mov_b32 m0, s96
	s_nop 0
	v_lshl_add_u64 v[54:55], v[60:61], 0, s[38:39]
	s_mov_b32 m0, s85
	s_nop 0
	global_load_lds_dwordx4 v[54:55], off
	v_lshl_add_u64 v[54:55], v[62:63], 0, s[38:39]
	s_mov_b32 m0, s86
	s_nop 0
	global_load_lds_dwordx4 v[54:55], off
	s_waitcnt vmcnt(6)
	s_waitcnt lgkmcnt(0)
	s_barrier
; #define PG8_STAGE(bufoff, gbase, voff) do { _Pragma("unroll") for (int _i = 0; _i < 2; ++_i) \
;         __builtin_amdgcn_global_load_lds((const unsigned*)((const char*)(gbase) + (voff)[_i]), (PG8_LAS unsigned*)(lds + (bufoff) + ldsw + _i * 8192), 16, 0, 0); } while (0)
; #define PG8_LDA(dst, b, h) do { _Pragma("unroll") for (int m = 0; m < 4; ++m) _Pragma("unroll") for (int k = 0; k < 2; ++k) dst[m][k] = *(const PG8_LAS bf16x8*)(lds + PG8_SA(b, h) + aoff + m * 2048 + k * 1024); } while (0)
; #define PG8_LDB(dst, b, h) do { _Pragma("unroll") for (int n = 0; n < 2; ++n) _Pragma("unroll") for (int k = 0; k < 2; ++k) dst[n][k] = *(const PG8_LAS bf16x8*)(lds + PG8_SB(b, h) + boff + n * 2048 + k * 1024); } while (0)
; #define PG8_WAIT_V(n) asm volatile("s_waitcnt vmcnt(" #n ")" ::: "memory")
; #define PG8_WAIT_L(n) asm volatile("s_waitcnt lgkmcnt(" #n ")" ::: "memory")
; #define PG8_BAR __builtin_amdgcn_s_barrier()
; #define PG8_SCHED __builtin_amdgcn_sched_barrier(0)
; #define PG8_MMA2(ai) PG8_MMA(ai, 0, At, B0)
; #define PG8_MMA2(ai) PG8_MMA(ai, 1, At, B1)
; #define PG8_MMA2(ai) do { PG8_MMA(ai, 0, At, B0); PG8_MMA(ai, 1, At, B1); } while (0)
;     ...
;             PG8_LDB(B0, 0, 0); PG8_LDB(B1, 0, 1); PG8_SCHED; PG8_LDA(At, 0, 0); PG8_STAGE(PG8_SA(1, 1), a1 + hstep, voffA);
;             PG8_WAIT_V(8); PG8_WAIT_L(0); PG8_BAR; PG8_MMA2(0); PG8_BAR; PG8_SCHED;
;             PG8_LDA(At, 0, 1); PG8_STAGE(PG8_SB(0, 0), b2, voffB); PG8_STAGE(PG8_SB(0, 1), b2 + hstep, voffB); PG8_STAGE(PG8_SA(0, 0), a2, voffA);
;             PG8_WAIT_V(8); PG8_WAIT_L(0); PG8_BAR; PG8_MMA2(1); PG8_BAR; PG8_SCHED;
;             PG8_LDB(B0, 1, 0); PG8_LDB(B1, 1, 1); PG8_SCHED; PG8_LDA(At, 1, 0); PG8_STAGE(PG8_SA(0, 1), a2 + hstep, voffA);
;             PG8_WAIT_V(8); PG8_WAIT_L(0); PG8_BAR; PG8_MMA2(0); PG8_BAR; PG8_SCHED;
;             PG8_LDA(At, 1, 1); PG8_STAGE(PG8_SB(1, 0), b3, voffB); PG8_STAGE(PG8_SB(1, 1), b3 + hstep, voffB); PG8_STAGE(PG8_SA(1, 0), a3, voffA);
;             PG8_WAIT_V(8); PG8_WAIT_L(0); PG8_BAR; PG8_MMA2(1); PG8_BAR; PG8_SCHED;
	s_setprio 1
	s_waitcnt lgkmcnt(0)
	v_mfma_f32_16x16x32_bf16 v[88:91], v[10:13], v[92:95], v[88:91]
	v_mfma_f32_16x16x32_bf16 v[42:45], v[80:83], v[92:95], v[42:45]
	v_mfma_f32_16x16x32_bf16 v[50:53], v[10:13], v[100:103], v[50:53]
	v_mfma_f32_16x16x32_bf16 v[64:67], v[80:83], v[100:103], v[64:67]
	v_mfma_f32_16x16x32_bf16 v[68:71], v[10:13], v[108:111], v[68:71]
	v_mfma_f32_16x16x32_bf16 v[72:75], v[80:83], v[108:111], v[72:75]
	v_mfma_f32_16x16x32_bf16 v[2:5], v[10:13], v[116:119], v[2:5]
	v_mfma_f32_16x16x32_bf16 v[6:9], v[80:83], v[116:119], v[6:9]
	v_mfma_f32_16x16x32_bf16 v[88:91], v[76:79], v[96:99], v[88:91]
	v_mfma_f32_16x16x32_bf16 v[42:45], v[84:87], v[96:99], v[42:45]
	v_mfma_f32_16x16x32_bf16 v[50:53], v[76:79], v[104:107], v[50:53]
	v_mfma_f32_16x16x32_bf16 v[64:67], v[84:87], v[104:107], v[64:67]
	v_mfma_f32_16x16x32_bf16 v[68:71], v[76:79], v[112:115], v[68:71]
	v_mfma_f32_16x16x32_bf16 v[72:75], v[84:87], v[112:115], v[72:75]
	v_mfma_f32_16x16x32_bf16 v[2:5], v[76:79], v[120:123], v[2:5]
	v_mfma_f32_16x16x32_bf16 v[6:9], v[84:87], v[120:123], v[6:9]
	s_setprio 0
	s_barrier
	ds_read_b128 v[10:13], v148
	ds_read_b128 v[76:79], v148 offset:1024
	ds_read_b128 v[80:83], v148 offset:2048
	ds_read_b128 v[84:87], v148 offset:3072
	s_add_u32 s72, s68, 0x40280
	s_addc_u32 s73, s69, 0
	s_mov_b32 m0, s95
	v_lshl_add_u64 v[54:55], s[72:73], 0, v[134:135]
	ds_read_b128 v[92:95], v146
	ds_read_b128 v[96:99], v146 offset:1024
	ds_read_b128 v[100:103], v146 offset:2048
	ds_read_b128 v[104:107], v146 offset:3072
	ds_read_b128 v[108:111], v146 offset:4096
	ds_read_b128 v[112:115], v146 offset:5120
	ds_read_b128 v[116:119], v146 offset:6144
	ds_read_b128 v[120:123], v146 offset:7168
	global_load_lds_dwordx4 v[54:55], off
	v_lshl_add_u64 v[54:55], s[72:73], 0, v[130:131]
	s_mov_b32 m0, s59
	s_nop 0
	global_load_lds_dwordx4 v[54:55], off
	s_waitcnt vmcnt(6)
	s_waitcnt lgkmcnt(0)
	s_barrier
	s_setprio 1
	s_waitcnt lgkmcnt(0)
	v_mfma_f32_16x16x32_bf16 v[46:49], v[10:13], v[92:95], v[46:49]
	v_mfma_f32_16x16x32_bf16 v[14:17], v[80:83], v[92:95], v[14:17]
	v_mfma_f32_16x16x32_bf16 v[18:21], v[10:13], v[100:103], v[18:21]
	v_mfma_f32_16x16x32_bf16 v[22:25], v[80:83], v[100:103], v[22:25]
	v_mfma_f32_16x16x32_bf16 v[26:29], v[10:13], v[108:111], v[26:29]
	v_mfma_f32_16x16x32_bf16 v[30:33], v[80:83], v[108:111], v[30:33]
	v_mfma_f32_16x16x32_bf16 v[34:37], v[10:13], v[116:119], v[34:37]
	v_mfma_f32_16x16x32_bf16 v[38:41], v[80:83], v[116:119], v[38:41]
	v_mfma_f32_16x16x32_bf16 v[46:49], v[76:79], v[96:99], v[46:49]
	v_mfma_f32_16x16x32_bf16 v[14:17], v[84:87], v[96:99], v[14:17]
	v_mfma_f32_16x16x32_bf16 v[18:21], v[76:79], v[104:107], v[18:21]
	v_mfma_f32_16x16x32_bf16 v[22:25], v[84:87], v[104:107], v[22:25]
	v_mfma_f32_16x16x32_bf16 v[26:29], v[76:79], v[112:115], v[26:29]
	v_mfma_f32_16x16x32_bf16 v[30:33], v[84:87], v[112:115], v[30:33]
	v_mfma_f32_16x16x32_bf16 v[34:37], v[76:79], v[120:123], v[34:37]
	v_mfma_f32_16x16x32_bf16 v[38:41], v[84:87], v[120:123], v[38:41]
	s_setprio 0
	s_barrier
	s_mov_b32 m0, s93
	v_lshl_add_u64 v[54:55], v[56:57], 0, s[40:41]
	s_add_u32 s72, s70, 0x40300
	ds_read_b128 v[92:95], v146 offset:16384
	ds_read_b128 v[96:99], v146 offset:17408
	ds_read_b128 v[100:103], v146 offset:18432
	ds_read_b128 v[104:107], v146 offset:19456
	ds_read_b128 v[108:111], v146 offset:20480
	ds_read_b128 v[112:115], v146 offset:21504
	ds_read_b128 v[116:119], v146 offset:22528
	ds_read_b128 v[120:123], v146 offset:23552
	global_load_lds_dwordx4 v[54:55], off
	v_lshl_add_u64 v[54:55], v[58:59], 0, s[40:41]
	s_mov_b32 m0, s61
	s_addc_u32 s73, s71, 0
	global_load_lds_dwordx4 v[54:55], off
	v_lshl_add_u64 v[54:55], s[72:73], 0, v[132:133]
	s_mov_b32 m0, s91
	s_nop 0
	v_lshl_add_u64 v[54:55], s[72:73], 0, v[128:129]
	s_mov_b32 m0, s92
	s_nop 0
	v_lshl_add_u64 v[54:55], v[60:61], 0, s[40:41]
	s_mov_b32 m0, s67
	s_nop 0
	global_load_lds_dwordx4 v[54:55], off
	v_lshl_add_u64 v[54:55], v[62:63], 0, s[40:41]
	s_mov_b32 m0, s81
	s_nop 0
	global_load_lds_dwordx4 v[54:55], off
	s_waitcnt vmcnt(6)
	s_waitcnt lgkmcnt(0)
	s_barrier
	s_setprio 1
	s_waitcnt lgkmcnt(0)
	v_mfma_f32_16x16x32_bf16 v[88:91], v[10:13], v[92:95], v[88:91]
	v_mfma_f32_16x16x32_bf16 v[42:45], v[80:83], v[92:95], v[42:45]
	v_mfma_f32_16x16x32_bf16 v[50:53], v[10:13], v[100:103], v[50:53]
	v_mfma_f32_16x16x32_bf16 v[64:67], v[80:83], v[100:103], v[64:67]
	v_mfma_f32_16x16x32_bf16 v[68:71], v[10:13], v[108:111], v[68:71]
	v_mfma_f32_16x16x32_bf16 v[72:75], v[80:83], v[108:111], v[72:75]
	v_mfma_f32_16x16x32_bf16 v[2:5], v[10:13], v[116:119], v[2:5]
	v_mfma_f32_16x16x32_bf16 v[6:9], v[80:83], v[116:119], v[6:9]
	v_mfma_f32_16x16x32_bf16 v[88:91], v[76:79], v[96:99], v[88:91]
	v_mfma_f32_16x16x32_bf16 v[42:45], v[84:87], v[96:99], v[42:45]
	v_mfma_f32_16x16x32_bf16 v[50:53], v[76:79], v[104:107], v[50:53]
	v_mfma_f32_16x16x32_bf16 v[64:67], v[84:87], v[104:107], v[64:67]
	v_mfma_f32_16x16x32_bf16 v[68:71], v[76:79], v[112:115], v[68:71]
	v_mfma_f32_16x16x32_bf16 v[72:75], v[84:87], v[112:115], v[72:75]
	v_mfma_f32_16x16x32_bf16 v[2:5], v[76:79], v[120:123], v[2:5]
	v_mfma_f32_16x16x32_bf16 v[6:9], v[84:87], v[120:123], v[6:9]
	s_setprio 0
	s_barrier
	ds_read_b128 v[10:13], v0
	ds_read_b128 v[76:79], v0 offset:1024
	ds_read_b128 v[80:83], v0 offset:2048
	ds_read_b128 v[84:87], v0 offset:3072
	s_add_u32 s72, s68, 0x40300
	s_addc_u32 s73, s69, 0
	s_mov_b32 m0, s83
	v_lshl_add_u64 v[54:55], s[72:73], 0, v[134:135]
	ds_read_b128 v[92:95], v146 offset:32768
	ds_read_b128 v[96:99], v146 offset:33792
	ds_read_b128 v[100:103], v146 offset:34816
	ds_read_b128 v[104:107], v146 offset:35840
	ds_read_b128 v[108:111], v146 offset:36864
	ds_read_b128 v[112:115], v146 offset:37888
	ds_read_b128 v[116:119], v146 offset:38912
	ds_read_b128 v[120:123], v146 offset:39936
	global_load_lds_dwordx4 v[54:55], off
	v_lshl_add_u64 v[54:55], s[72:73], 0, v[130:131]
	s_mov_b32 m0, s84
	s_nop 0
	global_load_lds_dwordx4 v[54:55], off
	s_waitcnt vmcnt(6)
	s_waitcnt lgkmcnt(0)
	s_barrier
; #define PG8_STAGE(bufoff, gbase, voff) do { _Pragma("unroll") for (int _i = 0; _i < 2; ++_i) \
;         __builtin_amdgcn_global_load_lds((const unsigned*)((const char*)(gbase) + (voff)[_i]), (PG8_LAS unsigned*)(lds + (bufoff) + ldsw + _i * 8192), 16, 0, 0); } while (0)
; #define PG8_LDA(dst, b, h) do { _Pragma("unroll") for (int m = 0; m < 4; ++m) _Pragma("unroll") for (int k = 0; k < 2; ++k) dst[m][k] = *(const PG8_LAS bf16x8*)(lds + PG8_SA(b, h) + aoff + m * 2048 + k * 1024); } while (0)
; #define PG8_LDB(dst, b, h) do { _Pragma("unroll") for (int n = 0; n < 2; ++n) _Pragma("unroll") for (int k = 0; k < 2; ++k) dst[n][k] = *(const PG8_LAS bf16x8*)(lds + PG8_SB(b, h) + boff + n * 2048 + k * 1024); } while (0)
; #define PG8_WAIT_V(n) asm volatile("s_waitcnt vmcnt(" #n ")" ::: "memory")
; #define PG8_WAIT_L(n) asm volatile("s_waitcnt lgkmcnt(" #n ")" ::: "memory")
; #define PG8_BAR __builtin_amdgcn_s_barrier()
; #define PG8_SCHED __builtin_amdgcn_sched_barrier(0)
; #define PG8_MMA2(ai) PG8_MMA(ai, 0, At, B0)
; #define PG8_MMA2(ai) PG8_MMA(ai, 1, At, B1)
; #define PG8_MMA2(ai) do { PG8_MMA(ai, 0, At, B0); PG8_MMA(ai, 1, At, B1); } while (0)
;     ...
;             PG8_LDB(B0, 0, 0); PG8_LDB(B1, 0, 1); PG8_SCHED; PG8_LDA(At, 0, 0); PG8_STAGE(PG8_SA(1, 1), a1 + hstep, voffA);
;             PG8_WAIT_V(8); PG8_WAIT_L(0); PG8_BAR; PG8_MMA2(0); PG8_BAR; PG8_SCHED;
;             PG8_LDA(At, 0, 1); PG8_STAGE(PG8_SB(0, 0), b2, voffB); PG8_STAGE(PG8_SB(0, 1), b2 + hstep, voffB); PG8_STAGE(PG8_SA(0, 0), a2, voffA);
;             PG8_WAIT_V(8); PG8_WAIT_L(0); PG8_BAR; PG8_MMA2(1); PG8_BAR; PG8_SCHED;
;             PG8_LDB(B0, 1, 0); PG8_LDB(B1, 1, 1); PG8_SCHED; PG8_LDA(At, 1, 0); PG8_STAGE(PG8_SA(0, 1), a2 + hstep, voffA);
;             PG8_WAIT_V(8); PG8_WAIT_L(0); PG8_BAR; PG8_MMA2(0); PG8_BAR; PG8_SCHED;
;             PG8_LDA(At, 1, 1); PG8_STAGE(PG8_SB(1, 0), b3, voffB); PG8_STAGE(PG8_SB(1, 1), b3 + hstep, voffB); PG8_STAGE(PG8_SA(1, 0), a3, voffA);
;             PG8_WAIT_V(8); PG8_WAIT_L(0); PG8_BAR; PG8_MMA2(1); PG8_BAR; PG8_SCHED;
	s_setprio 1
	s_waitcnt lgkmcnt(0)
	v_mfma_f32_16x16x32_bf16 v[46:49], v[10:13], v[92:95], v[46:49]
	v_mfma_f32_16x16x32_bf16 v[14:17], v[80:83], v[92:95], v[14:17]
	v_mfma_f32_16x16x32_bf16 v[18:21], v[10:13], v[100:103], v[18:21]
	v_mfma_f32_16x16x32_bf16 v[22:25], v[80:83], v[100:103], v[22:25]
	v_mfma_f32_16x16x32_bf16 v[26:29], v[10:13], v[108:111], v[26:29]
	v_mfma_f32_16x16x32_bf16 v[30:33], v[80:83], v[108:111], v[30:33]
	v_mfma_f32_16x16x32_bf16 v[34:37], v[10:13], v[116:119], v[34:37]
	v_mfma_f32_16x16x32_bf16 v[38:41], v[80:83], v[116:119], v[38:41]
	v_mfma_f32_16x16x32_bf16 v[46:49], v[76:79], v[96:99], v[46:49]
	v_mfma_f32_16x16x32_bf16 v[14:17], v[84:87], v[96:99], v[14:17]
	v_mfma_f32_16x16x32_bf16 v[18:21], v[76:79], v[104:107], v[18:21]
	v_mfma_f32_16x16x32_bf16 v[22:25], v[84:87], v[104:107], v[22:25]
	v_mfma_f32_16x16x32_bf16 v[26:29], v[76:79], v[112:115], v[26:29]
	v_mfma_f32_16x16x32_bf16 v[30:33], v[84:87], v[112:115], v[30:33]
	v_mfma_f32_16x16x32_bf16 v[34:37], v[76:79], v[120:123], v[34:37]
	v_mfma_f32_16x16x32_bf16 v[38:41], v[84:87], v[120:123], v[38:41]
	s_setprio 0
	s_barrier
	s_mov_b32 m0, s97
	v_lshl_add_u64 v[54:55], v[56:57], 0, s[42:43]
	s_add_u32 s72, s70, 0x40380
	ds_read_b128 v[92:95], v146 offset:49152
	ds_read_b128 v[96:99], v146 offset:50176
	ds_read_b128 v[100:103], v146 offset:51200
	ds_read_b128 v[104:107], v146 offset:52224
	ds_read_b128 v[108:111], v146 offset:53248
	ds_read_b128 v[112:115], v146 offset:54272
	ds_read_b128 v[116:119], v146 offset:55296
	ds_read_b128 v[120:123], v146 offset:56320
	global_load_lds_dwordx4 v[54:55], off
	v_lshl_add_u64 v[54:55], v[58:59], 0, s[42:43]
	s_mov_b32 m0, s82
	s_addc_u32 s73, s71, 0
	global_load_lds_dwordx4 v[54:55], off
	v_lshl_add_u64 v[54:55], s[72:73], 0, v[132:133]
	s_mov_b32 m0, s94
	s_nop 0
	v_lshl_add_u64 v[54:55], s[72:73], 0, v[128:129]
	s_mov_b32 m0, s96
	s_nop 0
	v_lshl_add_u64 v[54:55], v[60:61], 0, s[42:43]
	s_mov_b32 m0, s85
	s_nop 0
	global_load_lds_dwordx4 v[54:55], off
	v_lshl_add_u64 v[54:55], v[62:63], 0, s[42:43]
	s_mov_b32 m0, s86
	s_nop 0
	global_load_lds_dwordx4 v[54:55], off
	s_waitcnt vmcnt(6)
	s_waitcnt lgkmcnt(0)
	s_barrier
	s_setprio 1
	s_waitcnt lgkmcnt(0)
	v_mfma_f32_16x16x32_bf16 v[88:91], v[10:13], v[92:95], v[88:91]
	v_mfma_f32_16x16x32_bf16 v[42:45], v[80:83], v[92:95], v[42:45]
	v_mfma_f32_16x16x32_bf16 v[50:53], v[10:13], v[100:103], v[50:53]
	v_mfma_f32_16x16x32_bf16 v[64:67], v[80:83], v[100:103], v[64:67]
	v_mfma_f32_16x16x32_bf16 v[68:71], v[10:13], v[108:111], v[68:71]
	v_mfma_f32_16x16x32_bf16 v[72:75], v[80:83], v[108:111], v[72:75]
	v_mfma_f32_16x16x32_bf16 v[2:5], v[10:13], v[116:119], v[2:5]
	v_mfma_f32_16x16x32_bf16 v[6:9], v[80:83], v[116:119], v[6:9]
	v_mfma_f32_16x16x32_bf16 v[88:91], v[76:79], v[96:99], v[88:91]
	v_mfma_f32_16x16x32_bf16 v[42:45], v[84:87], v[96:99], v[42:45]
	v_mfma_f32_16x16x32_bf16 v[50:53], v[76:79], v[104:107], v[50:53]
	v_mfma_f32_16x16x32_bf16 v[64:67], v[84:87], v[104:107], v[64:67]
	v_mfma_f32_16x16x32_bf16 v[68:71], v[76:79], v[112:115], v[68:71]
	v_mfma_f32_16x16x32_bf16 v[72:75], v[84:87], v[112:115], v[72:75]
	v_mfma_f32_16x16x32_bf16 v[2:5], v[76:79], v[120:123], v[2:5]
	v_mfma_f32_16x16x32_bf16 v[6:9], v[84:87], v[120:123], v[6:9]
	s_setprio 0
	s_barrier
	ds_read_b128 v[10:13], v148
	ds_read_b128 v[76:79], v148 offset:1024
	ds_read_b128 v[80:83], v148 offset:2048
	ds_read_b128 v[84:87], v148 offset:3072
	s_add_u32 s72, s68, 0x40380
	s_addc_u32 s73, s69, 0
	s_mov_b32 m0, s95
	v_lshl_add_u64 v[54:55], s[72:73], 0, v[134:135]
	ds_read_b128 v[92:95], v146
	ds_read_b128 v[96:99], v146 offset:1024
	ds_read_b128 v[100:103], v146 offset:2048
	ds_read_b128 v[104:107], v146 offset:3072
	ds_read_b128 v[108:111], v146 offset:4096
	ds_read_b128 v[112:115], v146 offset:5120
	ds_read_b128 v[116:119], v146 offset:6144
	ds_read_b128 v[120:123], v146 offset:7168
	global_load_lds_dwordx4 v[54:55], off
	v_lshl_add_u64 v[54:55], s[72:73], 0, v[130:131]
	s_mov_b32 m0, s59
	s_nop 0
	global_load_lds_dwordx4 v[54:55], off
	s_waitcnt vmcnt(6)
	s_waitcnt lgkmcnt(0)
	s_barrier
	s_setprio 1
	s_waitcnt lgkmcnt(0)
	v_mfma_f32_16x16x32_bf16 v[46:49], v[10:13], v[92:95], v[46:49]
	v_mfma_f32_16x16x32_bf16 v[14:17], v[80:83], v[92:95], v[14:17]
	v_mfma_f32_16x16x32_bf16 v[18:21], v[10:13], v[100:103], v[18:21]
	v_mfma_f32_16x16x32_bf16 v[22:25], v[80:83], v[100:103], v[22:25]
	v_mfma_f32_16x16x32_bf16 v[26:29], v[10:13], v[108:111], v[26:29]
	v_mfma_f32_16x16x32_bf16 v[30:33], v[80:83], v[108:111], v[30:33]
	v_mfma_f32_16x16x32_bf16 v[34:37], v[10:13], v[116:119], v[34:37]
	v_mfma_f32_16x16x32_bf16 v[38:41], v[80:83], v[116:119], v[38:41]
	v_mfma_f32_16x16x32_bf16 v[46:49], v[76:79], v[96:99], v[46:49]
	v_mfma_f32_16x16x32_bf16 v[14:17], v[84:87], v[96:99], v[14:17]
	v_mfma_f32_16x16x32_bf16 v[18:21], v[76:79], v[104:107], v[18:21]
	v_mfma_f32_16x16x32_bf16 v[22:25], v[84:87], v[104:107], v[22:25]
	v_mfma_f32_16x16x32_bf16 v[26:29], v[76:79], v[112:115], v[26:29]
	v_mfma_f32_16x16x32_bf16 v[30:33], v[84:87], v[112:115], v[30:33]
	v_mfma_f32_16x16x32_bf16 v[34:37], v[76:79], v[120:123], v[34:37]
	v_mfma_f32_16x16x32_bf16 v[92:95], v[84:87], v[120:123], v[38:41]
	s_setprio 0
	s_barrier
; #define PG8_STAGE(bufoff, gbase, voff) do { _Pragma("unroll") for (int _i = 0; _i < 2; ++_i) \
;         __builtin_amdgcn_global_load_lds((const unsigned*)((const char*)(gbase) + (voff)[_i]), (PG8_LAS unsigned*)(lds + (bufoff) + ldsw + _i * 8192), 16, 0, 0); } while (0)
; #define PG8_LDA(dst, b, h) do { _Pragma("unroll") for (int m = 0; m < 4; ++m) _Pragma("unroll") for (int k = 0; k < 2; ++k) dst[m][k] = *(const PG8_LAS bf16x8*)(lds + PG8_SA(b, h) + aoff + m * 2048 + k * 1024); } while (0)
; #define PG8_LDB(dst, b, h) do { _Pragma("unroll") for (int n = 0; n < 2; ++n) _Pragma("unroll") for (int k = 0; k < 2; ++k) dst[n][k] = *(const PG8_LAS bf16x8*)(lds + PG8_SB(b, h) + boff + n * 2048 + k * 1024); } while (0)
; #define PG8_WAIT_V(n) asm volatile("s_waitcnt vmcnt(" #n ")" ::: "memory")
; #define PG8_WAIT_L(n) asm volatile("s_waitcnt lgkmcnt(" #n ")" ::: "memory")
; #define PG8_BAR __builtin_amdgcn_s_barrier()
; #define PG8_SCHED __builtin_amdgcn_sched_barrier(0)
; #define PG8_MMA2(ai) PG8_MMA(ai, 0, At, B0)
; #define PG8_MMA2(ai) PG8_MMA(ai, 1, At, B1)
; #define PG8_MMA2(ai) do { PG8_MMA(ai, 0, At, B0); PG8_MMA(ai, 1, At, B1); } while (0)
;     ...
;             PG8_LDB(B0, 0, 0); PG8_LDB(B1, 0, 1); PG8_SCHED; PG8_LDA(At, 0, 0); PG8_STAGE(PG8_SA(1, 1), a1 + hstep, voffA);
;             PG8_WAIT_V(8); PG8_WAIT_L(0); PG8_BAR; PG8_MMA2(0); PG8_BAR; PG8_SCHED;
;             PG8_LDA(At, 0, 1); PG8_STAGE(PG8_SB(0, 0), b2, voffB); PG8_STAGE(PG8_SB(0, 1), b2 + hstep, voffB); PG8_STAGE(PG8_SA(0, 0), a2, voffA);
;             PG8_WAIT_V(8); PG8_WAIT_L(0); PG8_BAR; PG8_MMA2(1); PG8_BAR; PG8_SCHED;
;             PG8_LDB(B0, 1, 0); PG8_LDB(B1, 1, 1); PG8_SCHED; PG8_LDA(At, 1, 0); PG8_STAGE(PG8_SA(0, 1), a2 + hstep, voffA);
;             PG8_WAIT_V(8); PG8_WAIT_L(0); PG8_BAR; PG8_MMA2(0); PG8_BAR; PG8_SCHED;
;             PG8_LDA(At, 1, 1); PG8_STAGE(PG8_SB(1, 0), b3, voffB); PG8_STAGE(PG8_SB(1, 1), b3 + hstep, voffB); PG8_STAGE(PG8_SA(1, 0), a3, voffA);
;             PG8_WAIT_V(8); PG8_WAIT_L(0); PG8_BAR; PG8_MMA2(1); PG8_BAR; PG8_SCHED;
	s_mov_b32 m0, s93
	v_lshl_add_u64 v[54:55], v[56:57], 0, s[20:21]
	s_add_u32 s72, s70, 0x40400
	ds_read_b128 v[38:41], v146 offset:16384
	ds_read_b128 v[96:99], v146 offset:17408
	ds_read_b128 v[100:103], v146 offset:18432
	ds_read_b128 v[104:107], v146 offset:19456
	ds_read_b128 v[108:111], v146 offset:20480
	ds_read_b128 v[112:115], v146 offset:21504
	ds_read_b128 v[116:119], v146 offset:22528
	ds_read_b128 v[120:123], v146 offset:23552
	v_lshl_add_u64 v[54:55], v[58:59], 0, s[20:21]
	s_mov_b32 m0, s61
	s_addc_u32 s73, s71, 0
	v_lshl_add_u64 v[54:55], s[72:73], 0, v[132:133]
	s_mov_b32 m0, s91
	s_nop 0
	global_load_lds_dwordx4 v[54:55], off
	v_lshl_add_u64 v[54:55], s[72:73], 0, v[128:129]
	s_mov_b32 m0, s92
	s_nop 0
	global_load_lds_dwordx4 v[54:55], off
	v_lshl_add_u64 v[54:55], v[60:61], 0, s[20:21]
	s_mov_b32 m0, s67
	s_nop 0
	global_load_lds_dwordx4 v[54:55], off
	v_lshl_add_u64 v[54:55], v[62:63], 0, s[20:21]
	s_mov_b32 m0, s81
	s_nop 0
	global_load_lds_dwordx4 v[54:55], off
	s_waitcnt vmcnt(6)
	s_waitcnt lgkmcnt(0)
	s_barrier
	s_setprio 1
	s_waitcnt lgkmcnt(0)
	v_mfma_f32_16x16x32_bf16 v[88:91], v[10:13], v[38:41], v[88:91]
	v_mfma_f32_16x16x32_bf16 v[38:41], v[80:83], v[38:41], v[42:45]
	v_mfma_f32_16x16x32_bf16 v[88:91], v[76:79], v[96:99], v[88:91]
	v_mfma_f32_16x16x32_bf16 v[96:99], v[84:87], v[96:99], v[38:41]
	v_mfma_f32_16x16x32_bf16 v[38:41], v[10:13], v[100:103], v[50:53]
	v_mfma_f32_16x16x32_bf16 v[124:127], v[76:79], v[104:107], v[38:41]
	v_mfma_f32_16x16x32_bf16 v[38:41], v[80:83], v[100:103], v[64:67]
	v_mfma_f32_16x16x32_bf16 v[100:103], v[84:87], v[104:107], v[38:41]
	v_mfma_f32_16x16x32_bf16 v[38:41], v[10:13], v[108:111], v[68:71]
	v_mfma_f32_16x16x32_bf16 v[68:71], v[76:79], v[112:115], v[38:41]
	v_mfma_f32_16x16x32_bf16 v[38:41], v[80:83], v[108:111], v[72:75]
	v_mfma_f32_16x16x32_bf16 v[2:5], v[10:13], v[116:119], v[2:5]
	v_mfma_f32_16x16x32_bf16 v[6:9], v[80:83], v[116:119], v[6:9]
	v_mfma_f32_16x16x32_bf16 v[104:107], v[84:87], v[112:115], v[38:41]
	v_mfma_f32_16x16x32_bf16 v[2:5], v[76:79], v[120:123], v[2:5]
	v_mfma_f32_16x16x32_bf16 v[76:79], v[84:87], v[120:123], v[6:9]
	s_setprio 0
	s_barrier
	ds_read_b128 v[80:83], v0
	ds_read_b128 v[84:87], v0 offset:1024
	ds_read_b128 v[108:111], v0 offset:2048
	ds_read_b128 v[112:115], v0 offset:3072
	s_add_u32 s72, s68, 0x40400
	s_addc_u32 s73, s69, 0
	s_mov_b32 m0, s83
	v_lshl_add_u64 v[0:1], s[72:73], 0, v[134:135]
	ds_read_b128 v[6:9], v146 offset:32768
	ds_read_b128 v[10:13], v146 offset:33792
	ds_read_b128 v[38:41], v146 offset:34816
	ds_read_b128 v[42:45], v146 offset:35840
	ds_read_b128 v[116:119], v146 offset:36864
	ds_read_b128 v[120:123], v146 offset:37888
	ds_read_b128 v[140:143], v146 offset:38912
	ds_read_b128 v[150:153], v146 offset:39936
	global_load_lds_dwordx4 v[0:1], off
	v_lshl_add_u64 v[0:1], s[72:73], 0, v[130:131]
	s_mov_b32 m0, s84
	s_nop 0
	global_load_lds_dwordx4 v[0:1], off
	s_waitcnt vmcnt(6)
	s_waitcnt lgkmcnt(0)
	s_barrier
	s_setprio 1
	s_waitcnt lgkmcnt(0)
	v_mfma_f32_16x16x32_bf16 v[46:49], v[80:83], v[6:9], v[46:49]
	v_mfma_f32_16x16x32_bf16 v[6:9], v[108:111], v[6:9], v[14:17]
	v_mfma_f32_16x16x32_bf16 v[64:67], v[112:115], v[10:13], v[6:9]
	v_mfma_f32_16x16x32_bf16 v[6:9], v[80:83], v[38:41], v[18:21]
	v_mfma_f32_16x16x32_bf16 v[52:55], v[84:87], v[42:45], v[6:9]
	v_mfma_f32_16x16x32_bf16 v[6:9], v[108:111], v[38:41], v[22:25]
	v_mfma_f32_16x16x32_bf16 v[72:75], v[84:87], v[10:13], v[46:49]
	v_mfma_f32_16x16x32_bf16 v[48:51], v[112:115], v[42:45], v[6:9]
	v_mfma_f32_16x16x32_bf16 v[6:9], v[80:83], v[116:119], v[26:29]
	v_mfma_f32_16x16x32_bf16 v[44:47], v[84:87], v[120:123], v[6:9]
	v_mfma_f32_16x16x32_bf16 v[6:9], v[108:111], v[116:119], v[30:33]
	v_mfma_f32_16x16x32_bf16 v[40:43], v[112:115], v[120:123], v[6:9]
	v_mfma_f32_16x16x32_bf16 v[6:9], v[80:83], v[140:143], v[34:37]
	v_mfma_f32_16x16x32_bf16 v[36:39], v[84:87], v[150:153], v[6:9]
	v_mfma_f32_16x16x32_bf16 v[6:9], v[108:111], v[140:143], v[92:95]
	v_mfma_f32_16x16x32_bf16 v[32:35], v[112:115], v[150:153], v[6:9]
	s_setprio 0
	s_barrier
	s_mov_b32 m0, s97
	v_lshl_add_u64 v[0:1], v[56:57], 0, s[44:45]
	s_add_u32 s72, s70, 0x40480
	s_nop 1
	ds_read_b128 v[6:9], v146 offset:49152
	ds_read_b128 v[10:13], v146 offset:50176
	ds_read_b128 v[14:17], v146 offset:51200
	ds_read_b128 v[92:95], v146 offset:52224
	ds_read_b128 v[116:119], v146 offset:53248
	ds_read_b128 v[120:123], v146 offset:54272
	ds_read_b128 v[140:143], v146 offset:55296
	ds_read_b128 v[150:153], v146 offset:56320
	v_lshl_add_u64 v[0:1], v[58:59], 0, s[44:45]
	s_mov_b32 m0, s82
	s_addc_u32 s73, s71, 0
	v_lshl_add_u64 v[0:1], s[72:73], 0, v[132:133]
	s_mov_b32 m0, s94
	s_nop 0
	global_load_lds_dwordx4 v[0:1], off
	v_lshl_add_u64 v[0:1], s[72:73], 0, v[128:129]
	s_mov_b32 m0, s96
	s_nop 0
	global_load_lds_dwordx4 v[0:1], off
	v_lshl_add_u64 v[0:1], v[60:61], 0, s[44:45]
	s_mov_b32 m0, s85
	s_nop 0
	global_load_lds_dwordx4 v[0:1], off
	v_lshl_add_u64 v[0:1], v[62:63], 0, s[44:45]
	s_mov_b32 m0, s86
	s_nop 0
	global_load_lds_dwordx4 v[0:1], off
	s_waitcnt vmcnt(6)
	s_waitcnt lgkmcnt(0)
	s_barrier
; #define PG8_STAGE(bufoff, gbase, voff) do { _Pragma("unroll") for (int _i = 0; _i < 2; ++_i) \
;         __builtin_amdgcn_global_load_lds((const unsigned*)((const char*)(gbase) + (voff)[_i]), (PG8_LAS unsigned*)(lds + (bufoff) + ldsw + _i * 8192), 16, 0, 0); } while (0)
; #define PG8_LDA(dst, b, h) do { _Pragma("unroll") for (int m = 0; m < 4; ++m) _Pragma("unroll") for (int k = 0; k < 2; ++k) dst[m][k] = *(const PG8_LAS bf16x8*)(lds + PG8_SA(b, h) + aoff + m * 2048 + k * 1024); } while (0)
; #define PG8_WAIT_V(n) asm volatile("s_waitcnt vmcnt(" #n ")" ::: "memory")
;     ...
;             PG8_LDB(B0, 0, 0); PG8_LDB(B1, 0, 1); PG8_SCHED; PG8_LDA(At, 0, 0); PG8_STAGE(PG8_SA(1, 1), a1 + hstep, voffA);
;             PG8_WAIT_V(8); PG8_WAIT_L(0); PG8_BAR; PG8_MMA2(0); PG8_BAR; PG8_SCHED;
;             PG8_LDA(At, 0, 1); PG8_STAGE(PG8_SB(0, 0), b2, voffB); PG8_STAGE(PG8_SB(0, 1), b2 + hstep, voffB); PG8_STAGE(PG8_SA(0, 0), a2, voffA);
;             PG8_WAIT_V(8); PG8_WAIT_L(0); PG8_BAR; PG8_MMA2(1); PG8_BAR; PG8_SCHED;
;             PG8_LDB(B0, 1, 0); PG8_LDB(B1, 1, 1); PG8_SCHED; PG8_LDA(At, 1, 0); PG8_STAGE(PG8_SA(0, 1), a2 + hstep, voffA);
;             PG8_WAIT_V(8); PG8_WAIT_L(0); PG8_BAR; PG8_MMA2(0); PG8_BAR; PG8_SCHED;
;             PG8_LDA(At, 1, 1); PG8_STAGE(PG8_SB(1, 0), b3, voffB); PG8_STAGE(PG8_SB(1, 1), b3 + hstep, voffB); PG8_STAGE(PG8_SA(1, 0), a3, voffA);
;             PG8_WAIT_V(8); PG8_WAIT_L(0); PG8_BAR; PG8_MMA2(1); PG8_BAR; PG8_SCHED;
;     ...
;             PG8_LDB(B0, 0, 0); PG8_LDB(B1, 0, 1); PG8_SCHED; PG8_LDA(At, 0, 0); PG8_STAGE(PG8_SA(1, 1), a1 + hstep, voffA);
;             PG8_WAIT_V(8); PG8_WAIT_L(0); PG8_BAR; PG8_MMA2(0); PG8_BAR; PG8_SCHED;
;             PG8_LDA(At, 0, 1); PG8_STAGE(PG8_SB(0, 0), b2, voffB); PG8_STAGE(PG8_SB(0, 1), b2 + hstep, voffB); PG8_STAGE(PG8_SA(0, 0), a2, voffA);
;             PG8_WAIT_V(8); PG8_WAIT_L(0); PG8_BAR; PG8_MMA2(1); PG8_BAR; PG8_SCHED;
;             PG8_LDB(B0, 1, 0); PG8_LDB(B1, 1, 1); PG8_SCHED; PG8_LDA(At, 1, 0); PG8_STAGE(PG8_SA(0, 1), a2 + hstep, voffA);
;             PG8_WAIT_V(8); PG8_WAIT_L(0); PG8_BAR; PG8_MMA2(0); PG8_BAR; PG8_SCHED;
;             PG8_LDA(At, 1, 1); PG8_STAGE(PG8_SB(1, 0), b3, voffB); PG8_STAGE(PG8_SB(1, 1), b3 + hstep, voffB); PG8_STAGE(PG8_SA(1, 0), a3, voffA);
;             PG8_WAIT_V(8); PG8_WAIT_L(0); PG8_BAR; PG8_MMA2(1); PG8_BAR; PG8_SCHED;
	s_setprio 1
	s_waitcnt lgkmcnt(0)
	v_mfma_f32_16x16x32_bf16 v[18:21], v[80:83], v[6:9], v[88:91]
	v_mfma_f32_16x16x32_bf16 v[6:9], v[108:111], v[6:9], v[96:99]
	v_mfma_f32_16x16x32_bf16 v[24:27], v[112:115], v[10:13], v[6:9]
	v_mfma_f32_16x16x32_bf16 v[6:9], v[80:83], v[14:17], v[124:127]
	v_mfma_f32_16x16x32_bf16 v[28:31], v[84:87], v[10:13], v[18:21]
	v_mfma_f32_16x16x32_bf16 v[20:23], v[84:87], v[92:95], v[6:9]
	v_mfma_f32_16x16x32_bf16 v[6:9], v[108:111], v[14:17], v[100:103]
	v_mfma_f32_16x16x32_bf16 v[16:19], v[112:115], v[92:95], v[6:9]
	v_mfma_f32_16x16x32_bf16 v[6:9], v[80:83], v[116:119], v[68:71]
	v_mfma_f32_16x16x32_bf16 v[12:15], v[84:87], v[120:123], v[6:9]
	v_mfma_f32_16x16x32_bf16 v[6:9], v[108:111], v[116:119], v[104:107]
	v_mfma_f32_16x16x32_bf16 v[0:3], v[80:83], v[140:143], v[2:5]
	v_mfma_f32_16x16x32_bf16 v[8:11], v[112:115], v[120:123], v[6:9]
	v_mfma_f32_16x16x32_bf16 v[4:7], v[84:87], v[150:153], v[0:3]
	v_mfma_f32_16x16x32_bf16 v[0:3], v[108:111], v[140:143], v[76:79]
	v_mfma_f32_16x16x32_bf16 v[0:3], v[112:115], v[150:153], v[0:3]
	s_setprio 0
	s_barrier
	ds_read_b128 v[68:71], v149
	ds_read_b128 v[76:79], v149 offset:1024
	ds_read_b128 v[80:83], v149 offset:2048
	ds_read_b128 v[84:87], v149 offset:3072
	s_and_b64 s[72:73], s[6:7], exec
	s_cselect_b32 s75, s63, s69
	s_cselect_b32 s74, s62, s68
	s_cselect_b32 s73, s65, s71
	s_cselect_b32 s72, s64, s70
	s_add_u32 vcc_lo, s68, 0x40480
	s_addc_u32 vcc_hi, s69, 0
	s_mov_b32 m0, s95
	v_lshl_add_u64 v[120:121], vcc, 0, v[134:135]
	ds_read_b128 v[88:91], v146
	ds_read_b128 v[92:95], v146 offset:1024
	ds_read_b128 v[96:99], v146 offset:2048
	ds_read_b128 v[100:103], v146 offset:3072
	ds_read_b128 v[104:107], v146 offset:4096
	ds_read_b128 v[108:111], v146 offset:5120
	ds_read_b128 v[112:115], v146 offset:6144
	ds_read_b128 v[116:119], v146 offset:7168
	global_load_lds_dwordx4 v[120:121], off
	v_lshl_add_u64 v[120:121], vcc, 0, v[130:131]
	s_mov_b32 m0, s59
	s_nop 0
	global_load_lds_dwordx4 v[120:121], off
	s_waitcnt vmcnt(6)
	s_waitcnt lgkmcnt(0)
	s_barrier
	s_setprio 1
	s_waitcnt lgkmcnt(0)
	v_mfma_f32_16x16x32_bf16 v[120:123], v[68:71], v[88:91], 0
	v_mfma_f32_16x16x32_bf16 v[88:91], v[80:83], v[88:91], 0
	v_mfma_f32_16x16x32_bf16 v[120:123], v[76:79], v[92:95], v[120:123]
	v_mfma_f32_16x16x32_bf16 v[88:91], v[84:87], v[92:95], v[88:91]
	v_mfma_f32_16x16x32_bf16 v[92:95], v[68:71], v[96:99], 0
	v_mfma_f32_16x16x32_bf16 v[96:99], v[80:83], v[96:99], 0
	v_mfma_f32_16x16x32_bf16 v[92:95], v[76:79], v[100:103], v[92:95]
	v_mfma_f32_16x16x32_bf16 v[96:99], v[84:87], v[100:103], v[96:99]
	v_mfma_f32_16x16x32_bf16 v[100:103], v[68:71], v[104:107], 0
	v_mfma_f32_16x16x32_bf16 v[104:107], v[80:83], v[104:107], 0
	v_mfma_f32_16x16x32_bf16 v[100:103], v[76:79], v[108:111], v[100:103]
	v_mfma_f32_16x16x32_bf16 v[104:107], v[84:87], v[108:111], v[104:107]
	v_mfma_f32_16x16x32_bf16 v[108:111], v[68:71], v[112:115], 0
	v_mfma_f32_16x16x32_bf16 v[112:115], v[80:83], v[112:115], 0
	v_mfma_f32_16x16x32_bf16 v[108:111], v[76:79], v[116:119], v[108:111]
	v_mfma_f32_16x16x32_bf16 v[112:115], v[84:87], v[116:119], v[112:115]
	s_setprio 0
	s_barrier
	s_mov_b32 m0, s93
	v_lshl_add_u64 v[170:171], v[56:57], 0, s[46:47]
	s_add_u32 vcc_lo, s70, 0x40500
	ds_read_b128 v[116:119], v146 offset:16384
	ds_read_b128 v[124:127], v146 offset:17408
	ds_read_b128 v[140:143], v146 offset:18432
	ds_read_b128 v[150:153], v146 offset:19456
	ds_read_b128 v[154:157], v146 offset:20480
	ds_read_b128 v[158:161], v146 offset:21504
	ds_read_b128 v[162:165], v146 offset:22528
	ds_read_b128 v[166:169], v146 offset:23552
	v_lshl_add_u64 v[170:171], v[58:59], 0, s[46:47]
	s_mov_b32 m0, s61
	s_addc_u32 vcc_hi, s71, 0
	v_lshl_add_u64 v[170:171], vcc, 0, v[132:133]
	s_mov_b32 m0, s91
	s_nop 0
	global_load_lds_dwordx4 v[170:171], off
	v_lshl_add_u64 v[170:171], vcc, 0, v[128:129]
	s_mov_b32 m0, s92
	s_nop 0
	global_load_lds_dwordx4 v[170:171], off
	v_lshl_add_u64 v[170:171], v[60:61], 0, s[46:47]
	s_mov_b32 m0, s67
	s_nop 0
	global_load_lds_dwordx4 v[170:171], off
	v_lshl_add_u64 v[170:171], v[62:63], 0, s[46:47]
	s_mov_b32 m0, s81
	s_nop 0
	global_load_lds_dwordx4 v[170:171], off
	s_waitcnt vmcnt(6)
	s_waitcnt lgkmcnt(0)
	s_barrier
	s_setprio 1
	s_waitcnt lgkmcnt(0)
	v_mfma_f32_16x16x32_bf16 v[170:173], v[68:71], v[116:119], 0
	v_mfma_f32_16x16x32_bf16 v[116:119], v[80:83], v[116:119], 0
	v_mfma_f32_16x16x32_bf16 v[170:173], v[76:79], v[124:127], v[170:173]
	v_mfma_f32_16x16x32_bf16 v[116:119], v[84:87], v[124:127], v[116:119]
	v_mfma_f32_16x16x32_bf16 v[124:127], v[68:71], v[140:143], 0
	v_mfma_f32_16x16x32_bf16 v[140:143], v[80:83], v[140:143], 0
	v_mfma_f32_16x16x32_bf16 v[124:127], v[76:79], v[150:153], v[124:127]
	v_mfma_f32_16x16x32_bf16 v[140:143], v[84:87], v[150:153], v[140:143]
	v_mfma_f32_16x16x32_bf16 v[150:153], v[68:71], v[154:157], 0
	v_mfma_f32_16x16x32_bf16 v[68:71], v[68:71], v[162:165], 0
	v_mfma_f32_16x16x32_bf16 v[150:153], v[76:79], v[158:161], v[150:153]
	v_mfma_f32_16x16x32_bf16 v[76:79], v[76:79], v[166:169], v[68:71]
	v_mfma_f32_16x16x32_bf16 v[68:71], v[80:83], v[162:165], 0
	v_mfma_f32_16x16x32_bf16 v[154:157], v[80:83], v[154:157], 0
	v_mfma_f32_16x16x32_bf16 v[80:83], v[84:87], v[166:169], v[68:71]
	v_mfma_f32_16x16x32_bf16 v[154:157], v[84:87], v[158:161], v[154:157]
	s_setprio 0
	s_barrier
; #define PG8_STAGE(bufoff, gbase, voff) do { _Pragma("unroll") for (int _i = 0; _i < 2; ++_i) \
;         __builtin_amdgcn_global_load_lds((const unsigned*)((const char*)(gbase) + (voff)[_i]), (PG8_LAS unsigned*)(lds + (bufoff) + ldsw + _i * 8192), 16, 0, 0); } while (0)
; #define PG8_LDA(dst, b, h) do { _Pragma("unroll") for (int m = 0; m < 4; ++m) _Pragma("unroll") for (int k = 0; k < 2; ++k) dst[m][k] = *(const PG8_LAS bf16x8*)(lds + PG8_SA(b, h) + aoff + m * 2048 + k * 1024); } while (0)
; #define PG8_LDB(dst, b, h) do { _Pragma("unroll") for (int n = 0; n < 2; ++n) _Pragma("unroll") for (int k = 0; k < 2; ++k) dst[n][k] = *(const PG8_LAS bf16x8*)(lds + PG8_SB(b, h) + boff + n * 2048 + k * 1024); } while (0)
; #define PG8_WAIT_V(n) asm volatile("s_waitcnt vmcnt(" #n ")" ::: "memory")
; #define PG8_WAIT_L(n) asm volatile("s_waitcnt lgkmcnt(" #n ")" ::: "memory")
; #define PG8_BAR __builtin_amdgcn_s_barrier()
; #define PG8_SCHED __builtin_amdgcn_sched_barrier(0)
; #define PG8_MMA2(ai) PG8_MMA(ai, 0, At, B0)
; #define PG8_MMA2(ai) PG8_MMA(ai, 1, At, B1)
; #define PG8_MMA2(ai) do { PG8_MMA(ai, 0, At, B0); PG8_MMA(ai, 1, At, B1); } while (0)
;     ...
;             PG8_LDB(B0, 0, 0); PG8_LDB(B1, 0, 1); PG8_SCHED; PG8_LDA(At, 0, 0); PG8_STAGE(PG8_SA(1, 1), a1 + hstep, voffA);
;             PG8_WAIT_V(8); PG8_WAIT_L(0); PG8_BAR; PG8_MMA2(0); PG8_BAR; PG8_SCHED;
;             PG8_LDA(At, 0, 1); PG8_STAGE(PG8_SB(0, 0), b2, voffB); PG8_STAGE(PG8_SB(0, 1), b2 + hstep, voffB); PG8_STAGE(PG8_SA(0, 0), a2, voffA);
;             PG8_WAIT_V(8); PG8_WAIT_L(0); PG8_BAR; PG8_MMA2(1); PG8_BAR; PG8_SCHED;
;             PG8_LDB(B0, 1, 0); PG8_LDB(B1, 1, 1); PG8_SCHED; PG8_LDA(At, 1, 0); PG8_STAGE(PG8_SA(0, 1), a2 + hstep, voffA);
;             PG8_WAIT_V(8); PG8_WAIT_L(0); PG8_BAR; PG8_MMA2(0); PG8_BAR; PG8_SCHED;
;             PG8_LDA(At, 1, 1); PG8_STAGE(PG8_SB(1, 0), b3, voffB); PG8_STAGE(PG8_SB(1, 1), b3 + hstep, voffB); PG8_STAGE(PG8_SA(1, 0), a3, voffA);
;             PG8_WAIT_V(8); PG8_WAIT_L(0); PG8_BAR; PG8_MMA2(1); PG8_BAR; PG8_SCHED;
	s_nop 2
	v_add_u32_e32 v68, s34, v145
	ds_read_b128 v[84:87], v68
	ds_read_b128 v[158:161], v68 offset:1024
	ds_read_b128 v[162:165], v68 offset:2048
	ds_read_b128 v[166:169], v68 offset:3072
	s_add_u32 s34, s68, 0x40500
	s_addc_u32 s35, s69, 0
	s_mov_b32 m0, s83
	v_lshl_add_u64 v[70:71], s[34:35], 0, v[134:135]
	ds_read_b128 v[174:177], v146 offset:32768
	ds_read_b128 v[178:181], v146 offset:33792
	ds_read_b128 v[182:185], v146 offset:34816
	ds_read_b128 v[186:189], v146 offset:35840
	ds_read_b128 v[190:193], v146 offset:36864
	ds_read_b128 v[194:197], v146 offset:37888
	ds_read_b128 v[198:201], v146 offset:38912
	ds_read_b128 v[208:211], v146 offset:39936
	global_load_lds_dwordx4 v[70:71], off
	v_lshl_add_u64 v[70:71], s[34:35], 0, v[130:131]
	s_mov_b32 m0, s84
	s_nop 0
	global_load_lds_dwordx4 v[70:71], off
	s_waitcnt vmcnt(6)
	s_waitcnt lgkmcnt(0)
	s_barrier
	s_setprio 1
	s_waitcnt lgkmcnt(0)
	v_mfma_f32_16x16x32_bf16 v[120:123], v[84:87], v[174:177], v[120:123]
	v_mfma_f32_16x16x32_bf16 v[88:91], v[162:165], v[174:177], v[88:91]
	v_mfma_f32_16x16x32_bf16 v[92:95], v[84:87], v[182:185], v[92:95]
	v_mfma_f32_16x16x32_bf16 v[96:99], v[162:165], v[182:185], v[96:99]
	v_mfma_f32_16x16x32_bf16 v[100:103], v[84:87], v[190:193], v[100:103]
	v_mfma_f32_16x16x32_bf16 v[104:107], v[162:165], v[190:193], v[104:107]
	v_mfma_f32_16x16x32_bf16 v[108:111], v[84:87], v[198:201], v[108:111]
	v_mfma_f32_16x16x32_bf16 v[112:115], v[162:165], v[198:201], v[112:115]
	v_mfma_f32_16x16x32_bf16 v[120:123], v[158:161], v[178:181], v[120:123]
	v_mfma_f32_16x16x32_bf16 v[88:91], v[166:169], v[178:181], v[88:91]
	v_mfma_f32_16x16x32_bf16 v[92:95], v[158:161], v[186:189], v[92:95]
	v_mfma_f32_16x16x32_bf16 v[96:99], v[166:169], v[186:189], v[96:99]
	v_mfma_f32_16x16x32_bf16 v[100:103], v[158:161], v[194:197], v[100:103]
	v_mfma_f32_16x16x32_bf16 v[104:107], v[166:169], v[194:197], v[104:107]
	v_mfma_f32_16x16x32_bf16 v[108:111], v[158:161], v[208:211], v[108:111]
	v_mfma_f32_16x16x32_bf16 v[112:115], v[166:169], v[208:211], v[112:115]
	s_setprio 0
	s_barrier
	s_mov_b32 m0, s97
	v_lshl_add_u64 v[70:71], v[56:57], 0, s[48:49]
	s_add_u32 s34, s70, 0x40580
	ds_read_b128 v[174:177], v146 offset:49152
	ds_read_b128 v[178:181], v146 offset:50176
	ds_read_b128 v[182:185], v146 offset:51200
	ds_read_b128 v[186:189], v146 offset:52224
	ds_read_b128 v[190:193], v146 offset:53248
	ds_read_b128 v[194:197], v146 offset:54272
	ds_read_b128 v[198:201], v146 offset:55296
	ds_read_b128 v[208:211], v146 offset:56320
	v_lshl_add_u64 v[70:71], v[58:59], 0, s[48:49]
	s_mov_b32 m0, s82
	s_addc_u32 s35, s71, 0
	v_lshl_add_u64 v[70:71], s[34:35], 0, v[132:133]
	s_mov_b32 m0, s94
	s_nop 0
	global_load_lds_dwordx4 v[70:71], off
	v_lshl_add_u64 v[70:71], s[34:35], 0, v[128:129]
	s_mov_b32 m0, s96
	s_nop 0
	global_load_lds_dwordx4 v[70:71], off
	v_lshl_add_u64 v[70:71], v[60:61], 0, s[48:49]
	s_mov_b32 m0, s85
	s_nop 0
	global_load_lds_dwordx4 v[70:71], off
	v_lshl_add_u64 v[70:71], v[62:63], 0, s[48:49]
	s_mov_b32 m0, s86
	s_nop 0
	global_load_lds_dwordx4 v[70:71], off
	s_waitcnt vmcnt(6)
	s_waitcnt lgkmcnt(0)
	s_barrier
	s_setprio 1
	s_waitcnt lgkmcnt(0)
	v_mfma_f32_16x16x32_bf16 v[116:119], v[162:165], v[174:177], v[116:119]
	v_mfma_f32_16x16x32_bf16 v[124:127], v[84:87], v[182:185], v[124:127]
	v_mfma_f32_16x16x32_bf16 v[76:79], v[84:87], v[198:201], v[76:79]
	v_mfma_f32_16x16x32_bf16 v[80:83], v[162:165], v[198:201], v[80:83]
	v_mfma_f32_16x16x32_bf16 v[170:173], v[84:87], v[174:177], v[170:173]
	v_mfma_f32_16x16x32_bf16 v[116:119], v[166:169], v[178:181], v[116:119]
	v_mfma_f32_16x16x32_bf16 v[124:127], v[158:161], v[186:189], v[124:127]
	v_mfma_f32_16x16x32_bf16 v[140:143], v[162:165], v[182:185], v[140:143]
	v_mfma_f32_16x16x32_bf16 v[150:153], v[84:87], v[190:193], v[150:153]
	v_mfma_f32_16x16x32_bf16 v[154:157], v[162:165], v[190:193], v[154:157]
	v_mfma_f32_16x16x32_bf16 v[76:79], v[158:161], v[208:211], v[76:79]
	v_mfma_f32_16x16x32_bf16 v[80:83], v[166:169], v[208:211], v[80:83]
	v_mfma_f32_16x16x32_bf16 v[170:173], v[158:161], v[178:181], v[170:173]
	v_mfma_f32_16x16x32_bf16 v[140:143], v[166:169], v[186:189], v[140:143]
	v_mfma_f32_16x16x32_bf16 v[150:153], v[158:161], v[194:197], v[150:153]
	v_mfma_f32_16x16x32_bf16 v[154:157], v[166:169], v[194:197], v[154:157]
	s_setprio 0
	s_barrier
	ds_read_b128 v[84:87], v149
	ds_read_b128 v[158:161], v149 offset:1024
	ds_read_b128 v[162:165], v149 offset:2048
	ds_read_b128 v[166:169], v149 offset:3072
	s_add_u32 s34, s68, 0x40580
	s_addc_u32 s35, s69, 0
	s_mov_b32 m0, s95
	v_lshl_add_u64 v[70:71], s[34:35], 0, v[134:135]
	ds_read_b128 v[174:177], v146
	ds_read_b128 v[178:181], v146 offset:1024
	ds_read_b128 v[182:185], v146 offset:2048
	ds_read_b128 v[186:189], v146 offset:3072
	ds_read_b128 v[190:193], v146 offset:4096
	ds_read_b128 v[194:197], v146 offset:5120
	ds_read_b128 v[198:201], v146 offset:6144
	ds_read_b128 v[208:211], v146 offset:7168
	global_load_lds_dwordx4 v[70:71], off
	v_lshl_add_u64 v[70:71], s[34:35], 0, v[130:131]
	s_mov_b32 m0, s59
	s_nop 0
	global_load_lds_dwordx4 v[70:71], off
	s_waitcnt vmcnt(6)
	s_waitcnt lgkmcnt(0)
	s_barrier
; #define PG8_STAGE(bufoff, gbase, voff) do { _Pragma("unroll") for (int _i = 0; _i < 2; ++_i) \
;         __builtin_amdgcn_global_load_lds((const unsigned*)((const char*)(gbase) + (voff)[_i]), (PG8_LAS unsigned*)(lds + (bufoff) + ldsw + _i * 8192), 16, 0, 0); } while (0)
; #define PG8_LDA(dst, b, h) do { _Pragma("unroll") for (int m = 0; m < 4; ++m) _Pragma("unroll") for (int k = 0; k < 2; ++k) dst[m][k] = *(const PG8_LAS bf16x8*)(lds + PG8_SA(b, h) + aoff + m * 2048 + k * 1024); } while (0)
; #define PG8_LDB(dst, b, h) do { _Pragma("unroll") for (int n = 0; n < 2; ++n) _Pragma("unroll") for (int k = 0; k < 2; ++k) dst[n][k] = *(const PG8_LAS bf16x8*)(lds + PG8_SB(b, h) + boff + n * 2048 + k * 1024); } while (0)
; #define PG8_WAIT_V(n) asm volatile("s_waitcnt vmcnt(" #n ")" ::: "memory")
; #define PG8_WAIT_L(n) asm volatile("s_waitcnt lgkmcnt(" #n ")" ::: "memory")
; #define PG8_BAR __builtin_amdgcn_s_barrier()
; #define PG8_SCHED __builtin_amdgcn_sched_barrier(0)
; #define PG8_MMA2(ai) PG8_MMA(ai, 0, At, B0)
; #define PG8_MMA2(ai) PG8_MMA(ai, 1, At, B1)
; #define PG8_MMA2(ai) do { PG8_MMA(ai, 0, At, B0); PG8_MMA(ai, 1, At, B1); } while (0)
;     ...
;             PG8_LDB(B0, 0, 0); PG8_LDB(B1, 0, 1); PG8_SCHED; PG8_LDA(At, 0, 0); PG8_STAGE(PG8_SA(1, 1), a1 + hstep, voffA);
;             PG8_WAIT_V(8); PG8_WAIT_L(0); PG8_BAR; PG8_MMA2(0); PG8_BAR; PG8_SCHED;
;             PG8_LDA(At, 0, 1); PG8_STAGE(PG8_SB(0, 0), b2, voffB); PG8_STAGE(PG8_SB(0, 1), b2 + hstep, voffB); PG8_STAGE(PG8_SA(0, 0), a2, voffA);
;             PG8_WAIT_V(8); PG8_WAIT_L(0); PG8_BAR; PG8_MMA2(1); PG8_BAR; PG8_SCHED;
;             PG8_LDB(B0, 1, 0); PG8_LDB(B1, 1, 1); PG8_SCHED; PG8_LDA(At, 1, 0); PG8_STAGE(PG8_SA(0, 1), a2 + hstep, voffA);
;             PG8_WAIT_V(8); PG8_WAIT_L(0); PG8_BAR; PG8_MMA2(0); PG8_BAR; PG8_SCHED;
;             PG8_LDA(At, 1, 1); PG8_STAGE(PG8_SB(1, 0), b3, voffB); PG8_STAGE(PG8_SB(1, 1), b3 + hstep, voffB); PG8_STAGE(PG8_SA(1, 0), a3, voffA);
;             PG8_WAIT_V(8); PG8_WAIT_L(0); PG8_BAR; PG8_MMA2(1); PG8_BAR; PG8_SCHED;
	s_setprio 1
	s_waitcnt lgkmcnt(0)
	v_mfma_f32_16x16x32_bf16 v[120:123], v[84:87], v[174:177], v[120:123]
	v_mfma_f32_16x16x32_bf16 v[88:91], v[162:165], v[174:177], v[88:91]
	v_mfma_f32_16x16x32_bf16 v[92:95], v[84:87], v[182:185], v[92:95]
	v_mfma_f32_16x16x32_bf16 v[96:99], v[162:165], v[182:185], v[96:99]
	v_mfma_f32_16x16x32_bf16 v[100:103], v[84:87], v[190:193], v[100:103]
	v_mfma_f32_16x16x32_bf16 v[104:107], v[162:165], v[190:193], v[104:107]
	v_mfma_f32_16x16x32_bf16 v[108:111], v[84:87], v[198:201], v[108:111]
	v_mfma_f32_16x16x32_bf16 v[112:115], v[162:165], v[198:201], v[112:115]
	v_mfma_f32_16x16x32_bf16 v[120:123], v[158:161], v[178:181], v[120:123]
	v_mfma_f32_16x16x32_bf16 v[88:91], v[166:169], v[178:181], v[88:91]
	v_mfma_f32_16x16x32_bf16 v[92:95], v[158:161], v[186:189], v[92:95]
	v_mfma_f32_16x16x32_bf16 v[96:99], v[166:169], v[186:189], v[96:99]
	v_mfma_f32_16x16x32_bf16 v[100:103], v[158:161], v[194:197], v[100:103]
	v_mfma_f32_16x16x32_bf16 v[104:107], v[166:169], v[194:197], v[104:107]
	v_mfma_f32_16x16x32_bf16 v[108:111], v[158:161], v[208:211], v[108:111]
	v_mfma_f32_16x16x32_bf16 v[112:115], v[166:169], v[208:211], v[112:115]
	s_setprio 0
	s_barrier
	s_mov_b32 m0, s93
	v_lshl_add_u64 v[70:71], v[56:57], 0, s[50:51]
	s_add_u32 s34, s70, 0x40600
	ds_read_b128 v[174:177], v146 offset:16384
	ds_read_b128 v[178:181], v146 offset:17408
	ds_read_b128 v[182:185], v146 offset:18432
	ds_read_b128 v[186:189], v146 offset:19456
	ds_read_b128 v[190:193], v146 offset:20480
	ds_read_b128 v[194:197], v146 offset:21504
	ds_read_b128 v[198:201], v146 offset:22528
	ds_read_b128 v[208:211], v146 offset:23552
	v_lshl_add_u64 v[70:71], v[58:59], 0, s[50:51]
	s_mov_b32 m0, s61
	s_addc_u32 s35, s71, 0
	v_lshl_add_u64 v[70:71], s[34:35], 0, v[132:133]
	s_mov_b32 m0, s91
	s_nop 0
	global_load_lds_dwordx4 v[70:71], off
	v_lshl_add_u64 v[70:71], s[34:35], 0, v[128:129]
	s_mov_b32 m0, s92
	s_nop 0
	global_load_lds_dwordx4 v[70:71], off
	v_lshl_add_u64 v[70:71], v[60:61], 0, s[50:51]
	s_mov_b32 m0, s67
	s_nop 0
	global_load_lds_dwordx4 v[70:71], off
	v_lshl_add_u64 v[70:71], v[62:63], 0, s[50:51]
	s_mov_b32 m0, s81
	s_nop 0
	global_load_lds_dwordx4 v[70:71], off
	s_waitcnt vmcnt(6)
	s_waitcnt lgkmcnt(0)
	s_barrier
	s_setprio 1
	s_waitcnt lgkmcnt(0)
	v_mfma_f32_16x16x32_bf16 v[116:119], v[162:165], v[174:177], v[116:119]
	v_mfma_f32_16x16x32_bf16 v[124:127], v[84:87], v[182:185], v[124:127]
	v_mfma_f32_16x16x32_bf16 v[76:79], v[84:87], v[198:201], v[76:79]
	v_mfma_f32_16x16x32_bf16 v[80:83], v[162:165], v[198:201], v[80:83]
	v_mfma_f32_16x16x32_bf16 v[170:173], v[84:87], v[174:177], v[170:173]
	v_mfma_f32_16x16x32_bf16 v[116:119], v[166:169], v[178:181], v[116:119]
	v_mfma_f32_16x16x32_bf16 v[124:127], v[158:161], v[186:189], v[124:127]
	v_mfma_f32_16x16x32_bf16 v[140:143], v[162:165], v[182:185], v[140:143]
	v_mfma_f32_16x16x32_bf16 v[150:153], v[84:87], v[190:193], v[150:153]
	v_mfma_f32_16x16x32_bf16 v[154:157], v[162:165], v[190:193], v[154:157]
	v_mfma_f32_16x16x32_bf16 v[76:79], v[158:161], v[208:211], v[76:79]
	v_mfma_f32_16x16x32_bf16 v[80:83], v[166:169], v[208:211], v[80:83]
	v_mfma_f32_16x16x32_bf16 v[170:173], v[158:161], v[178:181], v[170:173]
	v_mfma_f32_16x16x32_bf16 v[140:143], v[166:169], v[186:189], v[140:143]
	v_mfma_f32_16x16x32_bf16 v[150:153], v[158:161], v[194:197], v[150:153]
	v_mfma_f32_16x16x32_bf16 v[154:157], v[166:169], v[194:197], v[154:157]
	s_setprio 0
	s_barrier
	ds_read_b128 v[84:87], v68
	ds_read_b128 v[158:161], v68 offset:1024
	ds_read_b128 v[162:165], v68 offset:2048
	ds_read_b128 v[166:169], v68 offset:3072
	s_add_u32 s34, s68, 0x40600
	s_addc_u32 s35, s69, 0
	s_mov_b32 m0, s83
	v_lshl_add_u64 v[70:71], s[34:35], 0, v[134:135]
	ds_read_b128 v[174:177], v146 offset:32768
	ds_read_b128 v[178:181], v146 offset:33792
	ds_read_b128 v[182:185], v146 offset:34816
	ds_read_b128 v[186:189], v146 offset:35840
	ds_read_b128 v[190:193], v146 offset:36864
	ds_read_b128 v[194:197], v146 offset:37888
	ds_read_b128 v[198:201], v146 offset:38912
	ds_read_b128 v[208:211], v146 offset:39936
	global_load_lds_dwordx4 v[70:71], off
	v_lshl_add_u64 v[70:71], s[34:35], 0, v[130:131]
	s_mov_b32 m0, s84
	s_nop 0
	global_load_lds_dwordx4 v[70:71], off
	s_waitcnt vmcnt(6)
	s_waitcnt lgkmcnt(0)
	s_barrier
	s_setprio 1
	s_waitcnt lgkmcnt(0)
	v_mfma_f32_16x16x32_bf16 v[120:123], v[84:87], v[174:177], v[120:123]
	v_mfma_f32_16x16x32_bf16 v[88:91], v[162:165], v[174:177], v[88:91]
	v_mfma_f32_16x16x32_bf16 v[92:95], v[84:87], v[182:185], v[92:95]
	v_mfma_f32_16x16x32_bf16 v[96:99], v[162:165], v[182:185], v[96:99]
	v_mfma_f32_16x16x32_bf16 v[100:103], v[84:87], v[190:193], v[100:103]
	v_mfma_f32_16x16x32_bf16 v[104:107], v[162:165], v[190:193], v[104:107]
	v_mfma_f32_16x16x32_bf16 v[108:111], v[84:87], v[198:201], v[108:111]
	v_mfma_f32_16x16x32_bf16 v[112:115], v[162:165], v[198:201], v[112:115]
	v_mfma_f32_16x16x32_bf16 v[120:123], v[158:161], v[178:181], v[120:123]
	v_mfma_f32_16x16x32_bf16 v[88:91], v[166:169], v[178:181], v[88:91]
	v_mfma_f32_16x16x32_bf16 v[92:95], v[158:161], v[186:189], v[92:95]
	v_mfma_f32_16x16x32_bf16 v[96:99], v[166:169], v[186:189], v[96:99]
	v_mfma_f32_16x16x32_bf16 v[100:103], v[158:161], v[194:197], v[100:103]
	v_mfma_f32_16x16x32_bf16 v[104:107], v[166:169], v[194:197], v[104:107]
	v_mfma_f32_16x16x32_bf16 v[108:111], v[158:161], v[208:211], v[108:111]
	v_mfma_f32_16x16x32_bf16 v[112:115], v[166:169], v[208:211], v[112:115]
	s_setprio 0
	s_barrier
; #define PG8_STAGE(bufoff, gbase, voff) do { _Pragma("unroll") for (int _i = 0; _i < 2; ++_i) \
;         __builtin_amdgcn_global_load_lds((const unsigned*)((const char*)(gbase) + (voff)[_i]), (PG8_LAS unsigned*)(lds + (bufoff) + ldsw + _i * 8192), 16, 0, 0); } while (0)
; #define PG8_LDA(dst, b, h) do { _Pragma("unroll") for (int m = 0; m < 4; ++m) _Pragma("unroll") for (int k = 0; k < 2; ++k) dst[m][k] = *(const PG8_LAS bf16x8*)(lds + PG8_SA(b, h) + aoff + m * 2048 + k * 1024); } while (0)
; #define PG8_LDB(dst, b, h) do { _Pragma("unroll") for (int n = 0; n < 2; ++n) _Pragma("unroll") for (int k = 0; k < 2; ++k) dst[n][k] = *(const PG8_LAS bf16x8*)(lds + PG8_SB(b, h) + boff + n * 2048 + k * 1024); } while (0)
; #define PG8_WAIT_V(n) asm volatile("s_waitcnt vmcnt(" #n ")" ::: "memory")
; #define PG8_WAIT_L(n) asm volatile("s_waitcnt lgkmcnt(" #n ")" ::: "memory")
; #define PG8_BAR __builtin_amdgcn_s_barrier()
; #define PG8_SCHED __builtin_amdgcn_sched_barrier(0)
; #define PG8_MMA2(ai) PG8_MMA(ai, 0, At, B0)
; #define PG8_MMA2(ai) PG8_MMA(ai, 1, At, B1)
; #define PG8_MMA2(ai) do { PG8_MMA(ai, 0, At, B0); PG8_MMA(ai, 1, At, B1); } while (0)
;     ...
;             PG8_LDB(B0, 0, 0); PG8_LDB(B1, 0, 1); PG8_SCHED; PG8_LDA(At, 0, 0); PG8_STAGE(PG8_SA(1, 1), a1 + hstep, voffA);
;             PG8_WAIT_V(8); PG8_WAIT_L(0); PG8_BAR; PG8_MMA2(0); PG8_BAR; PG8_SCHED;
;             PG8_LDA(At, 0, 1); PG8_STAGE(PG8_SB(0, 0), b2, voffB); PG8_STAGE(PG8_SB(0, 1), b2 + hstep, voffB); PG8_STAGE(PG8_SA(0, 0), a2, voffA);
;             PG8_WAIT_V(8); PG8_WAIT_L(0); PG8_BAR; PG8_MMA2(1); PG8_BAR; PG8_SCHED;
;             PG8_LDB(B0, 1, 0); PG8_LDB(B1, 1, 1); PG8_SCHED; PG8_LDA(At, 1, 0); PG8_STAGE(PG8_SA(0, 1), a2 + hstep, voffA);
;             PG8_WAIT_V(8); PG8_WAIT_L(0); PG8_BAR; PG8_MMA2(0); PG8_BAR; PG8_SCHED;
;             PG8_LDA(At, 1, 1); PG8_STAGE(PG8_SB(1, 0), b3, voffB); PG8_STAGE(PG8_SB(1, 1), b3 + hstep, voffB); PG8_STAGE(PG8_SA(1, 0), a3, voffA);
;             PG8_WAIT_V(8); PG8_WAIT_L(0); PG8_BAR; PG8_MMA2(1); PG8_BAR; PG8_SCHED;
	s_mov_b32 m0, s97
	v_lshl_add_u64 v[70:71], v[56:57], 0, s[52:53]
	s_add_u32 s34, s70, 0x40680
	ds_read_b128 v[174:177], v146 offset:49152
	ds_read_b128 v[178:181], v146 offset:50176
	ds_read_b128 v[182:185], v146 offset:51200
	ds_read_b128 v[186:189], v146 offset:52224
	ds_read_b128 v[190:193], v146 offset:53248
	ds_read_b128 v[194:197], v146 offset:54272
	ds_read_b128 v[198:201], v146 offset:55296
	ds_read_b128 v[208:211], v146 offset:56320
	v_lshl_add_u64 v[70:71], v[58:59], 0, s[52:53]
	s_mov_b32 m0, s82
	s_addc_u32 s35, s71, 0
	v_lshl_add_u64 v[70:71], s[34:35], 0, v[132:133]
	s_mov_b32 m0, s94
	s_nop 0
	global_load_lds_dwordx4 v[70:71], off
	v_lshl_add_u64 v[70:71], s[34:35], 0, v[128:129]
	s_mov_b32 m0, s96
	s_nop 0
	global_load_lds_dwordx4 v[70:71], off
	v_lshl_add_u64 v[70:71], v[60:61], 0, s[52:53]
	s_mov_b32 m0, s85
	s_nop 0
	global_load_lds_dwordx4 v[70:71], off
	v_lshl_add_u64 v[70:71], v[62:63], 0, s[52:53]
	s_mov_b32 m0, s86
	s_nop 0
	global_load_lds_dwordx4 v[70:71], off
	s_waitcnt vmcnt(6)
	s_waitcnt lgkmcnt(0)
	s_barrier
	s_setprio 1
	s_waitcnt lgkmcnt(0)
	v_mfma_f32_16x16x32_bf16 v[116:119], v[162:165], v[174:177], v[116:119]
	v_mfma_f32_16x16x32_bf16 v[124:127], v[84:87], v[182:185], v[124:127]
	v_mfma_f32_16x16x32_bf16 v[76:79], v[84:87], v[198:201], v[76:79]
	v_mfma_f32_16x16x32_bf16 v[80:83], v[162:165], v[198:201], v[80:83]
	v_mfma_f32_16x16x32_bf16 v[170:173], v[84:87], v[174:177], v[170:173]
	v_mfma_f32_16x16x32_bf16 v[116:119], v[166:169], v[178:181], v[116:119]
	v_mfma_f32_16x16x32_bf16 v[124:127], v[158:161], v[186:189], v[124:127]
	v_mfma_f32_16x16x32_bf16 v[140:143], v[162:165], v[182:185], v[140:143]
	v_mfma_f32_16x16x32_bf16 v[150:153], v[84:87], v[190:193], v[150:153]
	v_mfma_f32_16x16x32_bf16 v[154:157], v[162:165], v[190:193], v[154:157]
	v_mfma_f32_16x16x32_bf16 v[76:79], v[158:161], v[208:211], v[76:79]
	v_mfma_f32_16x16x32_bf16 v[80:83], v[166:169], v[208:211], v[80:83]
	v_mfma_f32_16x16x32_bf16 v[170:173], v[158:161], v[178:181], v[170:173]
	v_mfma_f32_16x16x32_bf16 v[140:143], v[166:169], v[186:189], v[140:143]
	v_mfma_f32_16x16x32_bf16 v[150:153], v[158:161], v[194:197], v[150:153]
	v_mfma_f32_16x16x32_bf16 v[154:157], v[166:169], v[194:197], v[154:157]
	s_setprio 0
	s_barrier
	ds_read_b128 v[84:87], v149
	ds_read_b128 v[158:161], v149 offset:1024
	ds_read_b128 v[162:165], v149 offset:2048
	ds_read_b128 v[166:169], v149 offset:3072
	s_add_u32 s34, s68, 0x40680
	s_addc_u32 s35, s69, 0
	s_mov_b32 m0, s95
	v_lshl_add_u64 v[70:71], s[34:35], 0, v[134:135]
	ds_read_b128 v[174:177], v146
	ds_read_b128 v[178:181], v146 offset:1024
	ds_read_b128 v[182:185], v146 offset:2048
	ds_read_b128 v[186:189], v146 offset:3072
	ds_read_b128 v[190:193], v146 offset:4096
	ds_read_b128 v[194:197], v146 offset:5120
	ds_read_b128 v[198:201], v146 offset:6144
	ds_read_b128 v[208:211], v146 offset:7168
	global_load_lds_dwordx4 v[70:71], off
	v_lshl_add_u64 v[70:71], s[34:35], 0, v[130:131]
	s_mov_b32 m0, s59
	s_nop 0
	global_load_lds_dwordx4 v[70:71], off
	s_waitcnt vmcnt(6)
	s_waitcnt lgkmcnt(0)
	s_barrier
	s_setprio 1
	s_waitcnt lgkmcnt(0)
	v_mfma_f32_16x16x32_bf16 v[120:123], v[84:87], v[174:177], v[120:123]
	v_mfma_f32_16x16x32_bf16 v[88:91], v[162:165], v[174:177], v[88:91]
	v_mfma_f32_16x16x32_bf16 v[92:95], v[84:87], v[182:185], v[92:95]
	v_mfma_f32_16x16x32_bf16 v[96:99], v[162:165], v[182:185], v[96:99]
	v_mfma_f32_16x16x32_bf16 v[100:103], v[84:87], v[190:193], v[100:103]
	v_mfma_f32_16x16x32_bf16 v[104:107], v[162:165], v[190:193], v[104:107]
	v_mfma_f32_16x16x32_bf16 v[108:111], v[84:87], v[198:201], v[108:111]
	v_mfma_f32_16x16x32_bf16 v[112:115], v[162:165], v[198:201], v[112:115]
	v_mfma_f32_16x16x32_bf16 v[120:123], v[158:161], v[178:181], v[120:123]
	v_mfma_f32_16x16x32_bf16 v[88:91], v[166:169], v[178:181], v[88:91]
	v_mfma_f32_16x16x32_bf16 v[92:95], v[158:161], v[186:189], v[92:95]
	v_mfma_f32_16x16x32_bf16 v[96:99], v[166:169], v[186:189], v[96:99]
	v_mfma_f32_16x16x32_bf16 v[100:103], v[158:161], v[194:197], v[100:103]
	v_mfma_f32_16x16x32_bf16 v[104:107], v[166:169], v[194:197], v[104:107]
	v_mfma_f32_16x16x32_bf16 v[108:111], v[158:161], v[208:211], v[108:111]
	v_mfma_f32_16x16x32_bf16 v[112:115], v[166:169], v[208:211], v[112:115]
	s_setprio 0
	s_barrier
	s_mov_b32 m0, s93
	v_lshl_add_u64 v[70:71], v[56:57], 0, s[54:55]
	s_add_u32 s34, s70, 0x40700
	ds_read_b128 v[174:177], v146 offset:16384
	ds_read_b128 v[178:181], v146 offset:17408
	ds_read_b128 v[182:185], v146 offset:18432
	ds_read_b128 v[186:189], v146 offset:19456
	ds_read_b128 v[190:193], v146 offset:20480
	ds_read_b128 v[194:197], v146 offset:21504
	ds_read_b128 v[198:201], v146 offset:22528
	ds_read_b128 v[208:211], v146 offset:23552
	v_lshl_add_u64 v[70:71], v[58:59], 0, s[54:55]
	s_mov_b32 m0, s61
	s_addc_u32 s35, s71, 0
	v_lshl_add_u64 v[70:71], s[34:35], 0, v[132:133]
	s_mov_b32 m0, s91
	s_nop 0
	global_load_lds_dwordx4 v[70:71], off
	v_lshl_add_u64 v[70:71], s[34:35], 0, v[128:129]
	s_mov_b32 m0, s92
	s_nop 0
	global_load_lds_dwordx4 v[70:71], off
	v_lshl_add_u64 v[70:71], v[60:61], 0, s[54:55]
	s_mov_b32 m0, s67
	s_nop 0
	global_load_lds_dwordx4 v[70:71], off
	v_lshl_add_u64 v[70:71], v[62:63], 0, s[54:55]
	s_mov_b32 m0, s81
	s_nop 0
	global_load_lds_dwordx4 v[70:71], off
	s_waitcnt vmcnt(6)
	s_waitcnt lgkmcnt(0)
	s_barrier
; #define PG8_STAGE(bufoff, gbase, voff) do { _Pragma("unroll") for (int _i = 0; _i < 2; ++_i) \
;         __builtin_amdgcn_global_load_lds((const unsigned*)((const char*)(gbase) + (voff)[_i]), (PG8_LAS unsigned*)(lds + (bufoff) + ldsw + _i * 8192), 16, 0, 0); } while (0)
; #define PG8_LDA(dst, b, h) do { _Pragma("unroll") for (int m = 0; m < 4; ++m) _Pragma("unroll") for (int k = 0; k < 2; ++k) dst[m][k] = *(const PG8_LAS bf16x8*)(lds + PG8_SA(b, h) + aoff + m * 2048 + k * 1024); } while (0)
; #define PG8_LDB(dst, b, h) do { _Pragma("unroll") for (int n = 0; n < 2; ++n) _Pragma("unroll") for (int k = 0; k < 2; ++k) dst[n][k] = *(const PG8_LAS bf16x8*)(lds + PG8_SB(b, h) + boff + n * 2048 + k * 1024); } while (0)
; #define PG8_WAIT_V(n) asm volatile("s_waitcnt vmcnt(" #n ")" ::: "memory")
; #define PG8_WAIT_L(n) asm volatile("s_waitcnt lgkmcnt(" #n ")" ::: "memory")
; #define PG8_BAR __builtin_amdgcn_s_barrier()
; #define PG8_SCHED __builtin_amdgcn_sched_barrier(0)
; #define PG8_MMA2(ai) PG8_MMA(ai, 0, At, B0)
; #define PG8_MMA2(ai) PG8_MMA(ai, 1, At, B1)
; #define PG8_MMA2(ai) do { PG8_MMA(ai, 0, At, B0); PG8_MMA(ai, 1, At, B1); } while (0)
;     ...
;             PG8_LDB(B0, 0, 0); PG8_LDB(B1, 0, 1); PG8_SCHED; PG8_LDA(At, 0, 0); PG8_STAGE(PG8_SA(1, 1), a1 + hstep, voffA);
;             PG8_WAIT_V(8); PG8_WAIT_L(0); PG8_BAR; PG8_MMA2(0); PG8_BAR; PG8_SCHED;
;             PG8_LDA(At, 0, 1); PG8_STAGE(PG8_SB(0, 0), b2, voffB); PG8_STAGE(PG8_SB(0, 1), b2 + hstep, voffB); PG8_STAGE(PG8_SA(0, 0), a2, voffA);
;             PG8_WAIT_V(8); PG8_WAIT_L(0); PG8_BAR; PG8_MMA2(1); PG8_BAR; PG8_SCHED;
;             PG8_LDB(B0, 1, 0); PG8_LDB(B1, 1, 1); PG8_SCHED; PG8_LDA(At, 1, 0); PG8_STAGE(PG8_SA(0, 1), a2 + hstep, voffA);
;             PG8_WAIT_V(8); PG8_WAIT_L(0); PG8_BAR; PG8_MMA2(0); PG8_BAR; PG8_SCHED;
;             PG8_LDA(At, 1, 1); PG8_STAGE(PG8_SB(1, 0), b3, voffB); PG8_STAGE(PG8_SB(1, 1), b3 + hstep, voffB); PG8_STAGE(PG8_SA(1, 0), a3, voffA);
;             PG8_WAIT_V(8); PG8_WAIT_L(0); PG8_BAR; PG8_MMA2(1); PG8_BAR; PG8_SCHED;
	s_setprio 1
	s_waitcnt lgkmcnt(0)
	v_mfma_f32_16x16x32_bf16 v[116:119], v[162:165], v[174:177], v[116:119]
	v_mfma_f32_16x16x32_bf16 v[124:127], v[84:87], v[182:185], v[124:127]
	v_mfma_f32_16x16x32_bf16 v[76:79], v[84:87], v[198:201], v[76:79]
	v_mfma_f32_16x16x32_bf16 v[80:83], v[162:165], v[198:201], v[80:83]
	v_mfma_f32_16x16x32_bf16 v[170:173], v[84:87], v[174:177], v[170:173]
	v_mfma_f32_16x16x32_bf16 v[116:119], v[166:169], v[178:181], v[116:119]
	v_mfma_f32_16x16x32_bf16 v[124:127], v[158:161], v[186:189], v[124:127]
	v_mfma_f32_16x16x32_bf16 v[140:143], v[162:165], v[182:185], v[140:143]
	v_mfma_f32_16x16x32_bf16 v[150:153], v[84:87], v[190:193], v[150:153]
	v_mfma_f32_16x16x32_bf16 v[154:157], v[162:165], v[190:193], v[154:157]
	v_mfma_f32_16x16x32_bf16 v[76:79], v[158:161], v[208:211], v[76:79]
	v_mfma_f32_16x16x32_bf16 v[80:83], v[166:169], v[208:211], v[80:83]
	v_mfma_f32_16x16x32_bf16 v[170:173], v[158:161], v[178:181], v[170:173]
	v_mfma_f32_16x16x32_bf16 v[140:143], v[166:169], v[186:189], v[140:143]
	v_mfma_f32_16x16x32_bf16 v[150:153], v[158:161], v[194:197], v[150:153]
	v_mfma_f32_16x16x32_bf16 v[154:157], v[166:169], v[194:197], v[154:157]
	s_setprio 0
	s_barrier
	ds_read_b128 v[84:87], v68
	ds_read_b128 v[158:161], v68 offset:1024
	ds_read_b128 v[162:165], v68 offset:2048
	ds_read_b128 v[166:169], v68 offset:3072
	s_add_u32 s34, s68, 0x40700
	s_addc_u32 s35, s69, 0
	s_mov_b32 m0, s83
	v_lshl_add_u64 v[70:71], s[34:35], 0, v[134:135]
	ds_read_b128 v[174:177], v146 offset:32768
	ds_read_b128 v[178:181], v146 offset:33792
	ds_read_b128 v[182:185], v146 offset:34816
	ds_read_b128 v[186:189], v146 offset:35840
	ds_read_b128 v[190:193], v146 offset:36864
	ds_read_b128 v[194:197], v146 offset:37888
	ds_read_b128 v[198:201], v146 offset:38912
	ds_read_b128 v[208:211], v146 offset:39936
	global_load_lds_dwordx4 v[70:71], off
	v_lshl_add_u64 v[70:71], s[34:35], 0, v[130:131]
	s_mov_b32 m0, s84
	s_nop 0
	global_load_lds_dwordx4 v[70:71], off
	s_waitcnt vmcnt(6)
	s_waitcnt lgkmcnt(0)
	s_barrier
	s_setprio 1
	s_waitcnt lgkmcnt(0)
	v_mfma_f32_16x16x32_bf16 v[120:123], v[84:87], v[174:177], v[120:123]
	v_mfma_f32_16x16x32_bf16 v[88:91], v[162:165], v[174:177], v[88:91]
	v_mfma_f32_16x16x32_bf16 v[92:95], v[84:87], v[182:185], v[92:95]
	v_mfma_f32_16x16x32_bf16 v[96:99], v[162:165], v[182:185], v[96:99]
	v_mfma_f32_16x16x32_bf16 v[100:103], v[84:87], v[190:193], v[100:103]
	v_mfma_f32_16x16x32_bf16 v[104:107], v[162:165], v[190:193], v[104:107]
	v_mfma_f32_16x16x32_bf16 v[108:111], v[84:87], v[198:201], v[108:111]
	v_mfma_f32_16x16x32_bf16 v[112:115], v[162:165], v[198:201], v[112:115]
	v_mfma_f32_16x16x32_bf16 v[120:123], v[158:161], v[178:181], v[120:123]
	v_mfma_f32_16x16x32_bf16 v[88:91], v[166:169], v[178:181], v[88:91]
	v_mfma_f32_16x16x32_bf16 v[92:95], v[158:161], v[186:189], v[92:95]
	v_mfma_f32_16x16x32_bf16 v[96:99], v[166:169], v[186:189], v[96:99]
	v_mfma_f32_16x16x32_bf16 v[100:103], v[158:161], v[194:197], v[100:103]
	v_mfma_f32_16x16x32_bf16 v[104:107], v[166:169], v[194:197], v[104:107]
	v_mfma_f32_16x16x32_bf16 v[108:111], v[158:161], v[208:211], v[108:111]
	v_mfma_f32_16x16x32_bf16 v[112:115], v[166:169], v[208:211], v[112:115]
	s_setprio 0
	s_barrier
	s_mov_b32 m0, s97
	v_lshl_add_u64 v[56:57], v[56:57], 0, s[56:57]
	s_add_u32 s34, s70, 0x40780
	ds_read_b128 v[174:177], v146 offset:49152
	ds_read_b128 v[178:181], v146 offset:50176
	ds_read_b128 v[182:185], v146 offset:51200
	ds_read_b128 v[186:189], v146 offset:52224
	ds_read_b128 v[190:193], v146 offset:53248
	ds_read_b128 v[194:197], v146 offset:54272
	ds_read_b128 v[198:201], v146 offset:55296
	ds_read_b128 v[208:211], v146 offset:56320
	v_lshl_add_u64 v[56:57], v[58:59], 0, s[56:57]
	s_mov_b32 m0, s82
	s_addc_u32 s35, s71, 0
	v_lshl_add_u64 v[56:57], s[34:35], 0, v[132:133]
	s_mov_b32 m0, s94
	s_nop 0
	global_load_lds_dwordx4 v[56:57], off
	v_lshl_add_u64 v[56:57], s[34:35], 0, v[128:129]
	s_mov_b32 m0, s96
	s_nop 0
	global_load_lds_dwordx4 v[56:57], off
	v_lshl_add_u64 v[56:57], v[60:61], 0, s[56:57]
	s_mov_b32 m0, s85
	s_nop 0
	global_load_lds_dwordx4 v[56:57], off
	v_lshl_add_u64 v[56:57], v[62:63], 0, s[56:57]
	s_mov_b32 m0, s86
	s_nop 0
	global_load_lds_dwordx4 v[56:57], off
	s_waitcnt vmcnt(6)
	s_waitcnt lgkmcnt(0)
	s_barrier
	s_setprio 1
	s_waitcnt lgkmcnt(0)
	v_mfma_f32_16x16x32_bf16 v[56:59], v[84:87], v[174:177], v[170:173]
	v_mfma_f32_16x16x32_bf16 v[60:63], v[162:165], v[174:177], v[116:119]
	v_mfma_f32_16x16x32_bf16 v[116:119], v[84:87], v[182:185], v[124:127]
	v_mfma_f32_16x16x32_bf16 v[124:127], v[162:165], v[182:185], v[140:143]
	v_mfma_f32_16x16x32_bf16 v[76:79], v[84:87], v[198:201], v[76:79]
	v_mfma_f32_16x16x32_bf16 v[80:83], v[162:165], v[198:201], v[80:83]
	v_mfma_f32_16x16x32_bf16 v[56:59], v[158:161], v[178:181], v[56:59]
	v_mfma_f32_16x16x32_bf16 v[60:63], v[166:169], v[178:181], v[60:63]
	v_mfma_f32_16x16x32_bf16 v[116:119], v[158:161], v[186:189], v[116:119]
	v_mfma_f32_16x16x32_bf16 v[124:127], v[166:169], v[186:189], v[124:127]
	v_mfma_f32_16x16x32_bf16 v[140:143], v[84:87], v[190:193], v[150:153]
	v_mfma_f32_16x16x32_bf16 v[150:153], v[162:165], v[190:193], v[154:157]
	v_mfma_f32_16x16x32_bf16 v[76:79], v[158:161], v[208:211], v[76:79]
	v_mfma_f32_16x16x32_bf16 v[80:83], v[166:169], v[208:211], v[80:83]
	v_mfma_f32_16x16x32_bf16 v[140:143], v[158:161], v[194:197], v[140:143]
	v_mfma_f32_16x16x32_bf16 v[150:153], v[166:169], v[194:197], v[150:153]
	s_setprio 0
	s_barrier
; #define PG8_STAGE(bufoff, gbase, voff) do { _Pragma("unroll") for (int _i = 0; _i < 2; ++_i) \
;         __builtin_amdgcn_global_load_lds((const unsigned*)((const char*)(gbase) + (voff)[_i]), (PG8_LAS unsigned*)(lds + (bufoff) + ldsw + _i * 8192), 16, 0, 0); } while (0)
; #define PG8_LDA(dst, b, h) do { _Pragma("unroll") for (int m = 0; m < 4; ++m) _Pragma("unroll") for (int k = 0; k < 2; ++k) dst[m][k] = *(const PG8_LAS bf16x8*)(lds + PG8_SA(b, h) + aoff + m * 2048 + k * 1024); } while (0)
; #define PG8_LDB(dst, b, h) do { _Pragma("unroll") for (int n = 0; n < 2; ++n) _Pragma("unroll") for (int k = 0; k < 2; ++k) dst[n][k] = *(const PG8_LAS bf16x8*)(lds + PG8_SB(b, h) + boff + n * 2048 + k * 1024); } while (0)
; #define PG8_WAIT_V(n) asm volatile("s_waitcnt vmcnt(" #n ")" ::: "memory")
; #define PG8_WAIT_L(n) asm volatile("s_waitcnt lgkmcnt(" #n ")" ::: "memory")
;     ...
;         const char* nA = has_next ? (const char*)g.A + (size_t)nxt.pm * tstep : cA; const char* nB = has_next ? (const char*)g.Bt + (size_t)nxt.pn * tstep : cB;
;     ...
;         for (int t = ZSPLIT; t < nt; t += 2) {
;             const bool last = (t == nt - 2);
;             const char* a1 = cA + (size_t)(t + 1) * kstep;
;             const char* a2 = last ? nA : cA + (size_t)(t + 2) * kstep; const char* b2 = last ? nB : cB + (size_t)(t + 2) * kstep;
;             const char* a3 = a2 + kstep; const char* b3 = b2 + kstep;
;             if (last && has_next) S.a_ready(nxt);
;             if constexpr (SP2) {
;             PG8_LDB(B0, 0, 0); PG8_LDB(B1, 0, 1); PG8_SCHED; PG8_LDA(At, 0, 0); PG8_STAGE(PG8_SA(1, 1), a1 + hstep, voffA);
;             PG8_WAIT_V(8); PG8_WAIT_L(0); PG8_BAR; PG8_MMA2(0); PG8_BAR; PG8_SCHED;
;             PG8_LDA(At, 0, 1); PG8_STAGE(PG8_SB(0, 0), b2, voffB); PG8_STAGE(PG8_SB(0, 1), b2 + hstep, voffB); PG8_STAGE(PG8_SA(0, 0), a2, voffA);
;             PG8_WAIT_V(8); PG8_WAIT_L(0); PG8_BAR; PG8_MMA2(1); PG8_BAR; PG8_SCHED;
;             PG8_LDB(B0, 1, 0); PG8_LDB(B1, 1, 1); PG8_SCHED; PG8_LDA(At, 1, 0); PG8_STAGE(PG8_SA(0, 1), a2 + hstep, voffA);
;             PG8_WAIT_V(8); PG8_WAIT_L(0); PG8_BAR; PG8_MMA2(0); PG8_BAR; PG8_SCHED;
;             PG8_LDA(At, 1, 1); PG8_STAGE(PG8_SB(1, 0), b3, voffB); PG8_STAGE(PG8_SB(1, 1), b3 + hstep, voffB); PG8_STAGE(PG8_SA(1, 0), a3, voffA);
;             PG8_WAIT_V(8); PG8_WAIT_L(0); PG8_BAR; PG8_MMA2(1); PG8_BAR; PG8_SCHED;
	ds_read_b128 v[84:87], v149
	ds_read_b128 v[154:157], v149 offset:1024
	ds_read_b128 v[158:161], v149 offset:2048
	ds_read_b128 v[162:165], v149 offset:3072
	s_add_u32 s34, s68, 0x40780
	s_addc_u32 s35, s69, 0
	s_mov_b32 m0, s95
	v_lshl_add_u64 v[70:71], s[34:35], 0, v[134:135]
	ds_read_b128 v[166:169], v146
	ds_read_b128 v[170:173], v146 offset:1024
	ds_read_b128 v[174:177], v146 offset:2048
	ds_read_b128 v[178:181], v146 offset:3072
	ds_read_b128 v[182:185], v146 offset:4096
	ds_read_b128 v[186:189], v146 offset:5120
	ds_read_b128 v[190:193], v146 offset:6144
	ds_read_b128 v[194:197], v146 offset:7168
	global_load_lds_dwordx4 v[70:71], off
	v_lshl_add_u64 v[70:71], s[34:35], 0, v[130:131]
	s_mov_b32 m0, s59
	s_nop 0
	global_load_lds_dwordx4 v[70:71], off
	s_waitcnt vmcnt(6)
	s_waitcnt lgkmcnt(0)
	s_barrier
	s_setprio 1
	s_waitcnt lgkmcnt(0)
	v_mfma_f32_16x16x32_bf16 v[120:123], v[84:87], v[166:169], v[120:123]
	v_mfma_f32_16x16x32_bf16 v[88:91], v[158:161], v[166:169], v[88:91]
	v_mfma_f32_16x16x32_bf16 v[92:95], v[84:87], v[174:177], v[92:95]
	v_mfma_f32_16x16x32_bf16 v[96:99], v[158:161], v[174:177], v[96:99]
	v_mfma_f32_16x16x32_bf16 v[100:103], v[84:87], v[182:185], v[100:103]
	v_mfma_f32_16x16x32_bf16 v[104:107], v[158:161], v[182:185], v[104:107]
	v_mfma_f32_16x16x32_bf16 v[108:111], v[84:87], v[190:193], v[108:111]
	v_mfma_f32_16x16x32_bf16 v[120:123], v[154:157], v[170:173], v[120:123]
	v_mfma_f32_16x16x32_bf16 v[88:91], v[162:165], v[170:173], v[88:91]
	v_mfma_f32_16x16x32_bf16 v[92:95], v[154:157], v[178:181], v[92:95]
	v_mfma_f32_16x16x32_bf16 v[96:99], v[162:165], v[178:181], v[96:99]
	v_mfma_f32_16x16x32_bf16 v[100:103], v[154:157], v[186:189], v[100:103]
	v_mfma_f32_16x16x32_bf16 v[104:107], v[162:165], v[186:189], v[104:107]
	v_mfma_f32_16x16x32_bf16 v[166:169], v[154:157], v[194:197], v[108:111]
	v_mfma_f32_16x16x32_bf16 v[108:111], v[158:161], v[190:193], v[112:115]
	v_mfma_f32_16x16x32_bf16 v[170:173], v[162:165], v[194:197], v[108:111]
	s_setprio 0
	s_barrier
	s_mov_b32 m0, s93
	v_lshl_add_u64 v[216:217], s[72:73], 0, v[132:133]
	s_add_u32 s34, s72, 0x40000
	s_nop 1
	ds_read_b128 v[108:111], v146 offset:16384
	ds_read_b128 v[112:115], v146 offset:17408
	ds_read_b128 v[174:177], v146 offset:18432
	ds_read_b128 v[178:181], v146 offset:19456
	ds_read_b128 v[182:185], v146 offset:20480
	ds_read_b128 v[186:189], v146 offset:21504
	ds_read_b128 v[190:193], v146 offset:22528
	ds_read_b128 v[194:197], v146 offset:23552
	global_load_lds_dwordx4 v[216:217], off
	v_lshl_add_u64 v[218:219], s[72:73], 0, v[128:129]
	s_mov_b32 m0, s61
	s_addc_u32 s35, s73, 0
	global_load_lds_dwordx4 v[218:219], off
	v_lshl_add_u64 v[70:71], s[34:35], 0, v[132:133]
	s_mov_b32 m0, s91
	v_lshl_add_u64 v[220:221], s[74:75], 0, v[134:135]
	v_lshl_add_u64 v[70:71], s[34:35], 0, v[128:129]
	s_mov_b32 m0, s92
	v_lshl_add_u64 v[222:223], s[74:75], 0, v[130:131]
	s_mov_b32 m0, s67
	s_nop 0
	global_load_lds_dwordx4 v[220:221], off
	s_mov_b32 m0, s81
	s_nop 0
	global_load_lds_dwordx4 v[222:223], off
	s_waitcnt vmcnt(6)
	s_waitcnt lgkmcnt(0)
	s_barrier
	s_setprio 1
	s_waitcnt lgkmcnt(0)
	v_mfma_f32_16x16x32_bf16 v[56:59], v[84:87], v[108:111], v[56:59]
	v_mfma_f32_16x16x32_bf16 v[60:63], v[158:161], v[108:111], v[60:63]
	v_mfma_f32_16x16x32_bf16 v[108:111], v[84:87], v[174:177], v[116:119]
	v_mfma_f32_16x16x32_bf16 v[198:201], v[154:157], v[178:181], v[108:111]
	v_mfma_f32_16x16x32_bf16 v[108:111], v[158:161], v[174:177], v[124:127]
	v_mfma_f32_16x16x32_bf16 v[174:177], v[162:165], v[178:181], v[108:111]
	v_mfma_f32_16x16x32_bf16 v[108:111], v[84:87], v[182:185], v[140:143]
	v_mfma_f32_16x16x32_bf16 v[76:79], v[84:87], v[190:193], v[76:79]
	v_mfma_f32_16x16x32_bf16 v[56:59], v[154:157], v[112:115], v[56:59]
	v_mfma_f32_16x16x32_bf16 v[60:63], v[162:165], v[112:115], v[60:63]
	v_mfma_f32_16x16x32_bf16 v[140:143], v[154:157], v[186:189], v[108:111]
	v_mfma_f32_16x16x32_bf16 v[108:111], v[158:161], v[182:185], v[150:153]
	v_mfma_f32_16x16x32_bf16 v[154:157], v[154:157], v[194:197], v[76:79]
	v_mfma_f32_16x16x32_bf16 v[76:79], v[158:161], v[190:193], v[80:83]
	v_mfma_f32_16x16x32_bf16 v[150:153], v[162:165], v[186:189], v[108:111]
	v_mfma_f32_16x16x32_bf16 v[158:161], v[162:165], v[194:197], v[76:79]
	s_setprio 0
	s_barrier
; #define PG8_STAGE(bufoff, gbase, voff) do { _Pragma("unroll") for (int _i = 0; _i < 2; ++_i) \
;         __builtin_amdgcn_global_load_lds((const unsigned*)((const char*)(gbase) + (voff)[_i]), (PG8_LAS unsigned*)(lds + (bufoff) + ldsw + _i * 8192), 16, 0, 0); } while (0)
; #define PG8_LDA(dst, b, h) do { _Pragma("unroll") for (int m = 0; m < 4; ++m) _Pragma("unroll") for (int k = 0; k < 2; ++k) dst[m][k] = *(const PG8_LAS bf16x8*)(lds + PG8_SA(b, h) + aoff + m * 2048 + k * 1024); } while (0)
; #define PG8_WAIT_V(n) asm volatile("s_waitcnt vmcnt(" #n ")" ::: "memory")
; #define PG8_WAIT_L(n) asm volatile("s_waitcnt lgkmcnt(" #n ")" ::: "memory")
; #define PG8_BAR __builtin_amdgcn_s_barrier()
; #define PG8_SCHED __builtin_amdgcn_sched_barrier(0)
; #define PG8_MMA2(ai) PG8_MMA(ai, 0, At, B0)
; #define PG8_MMA2(ai) PG8_MMA(ai, 1, At, B1)
; #define PG8_MMA2(ai) do { PG8_MMA(ai, 0, At, B0); PG8_MMA(ai, 1, At, B1); } while (0)
;     ...
;             PG8_WAIT_V(8); PG8_WAIT_L(0); PG8_BAR; PG8_MMA2(0); PG8_BAR; PG8_SCHED;
;             PG8_LDA(At, 1, 1); PG8_STAGE(PG8_SB(1, 0), b3, voffB); PG8_STAGE(PG8_SB(1, 1), b3 + hstep, voffB); PG8_STAGE(PG8_SA(1, 0), a3, voffA);
;             PG8_WAIT_V(8); PG8_WAIT_L(0); PG8_BAR; PG8_MMA2(1); PG8_BAR; PG8_SCHED;
;     ...
;         if constexpr (ALIGN_EPI) { if (wr == 0) PG8_BAR; }
	ds_read_b128 v[162:165], v68
	ds_read_b128 v[178:181], v68 offset:1024
	ds_read_b128 v[182:185], v68 offset:2048
	ds_read_b128 v[186:189], v68 offset:3072
	s_add_u32 s34, s74, 0x40000
	s_addc_u32 s35, s75, 0
	s_mov_b32 m0, s83
	v_lshl_add_u64 v[108:109], s[34:35], 0, v[134:135]
	ds_read_b128 v[68:71], v146 offset:32768
	ds_read_b128 v[76:79], v146 offset:33792
	ds_read_b128 v[80:83], v146 offset:34816
	ds_read_b128 v[84:87], v146 offset:35840
	ds_read_b128 v[190:193], v146 offset:36864
	ds_read_b128 v[194:197], v146 offset:37888
	ds_read_b128 v[208:211], v146 offset:38912
	ds_read_b128 v[212:215], v146 offset:39936
	global_load_lds_dwordx4 v[108:109], off
	v_lshl_add_u64 v[108:109], s[34:35], 0, v[130:131]
	s_mov_b32 m0, s84
	s_nop 0
	global_load_lds_dwordx4 v[108:109], off
	s_waitcnt vmcnt(6)
	s_waitcnt lgkmcnt(0)
	s_barrier
	s_setprio 1
	s_waitcnt lgkmcnt(0)
	v_mfma_f32_16x16x32_bf16 v[108:111], v[162:165], v[68:71], v[120:123]
	v_mfma_f32_16x16x32_bf16 v[68:71], v[182:185], v[68:71], v[88:91]
	v_mfma_f32_16x16x32_bf16 v[120:123], v[186:189], v[76:79], v[68:71]
	v_mfma_f32_16x16x32_bf16 v[68:71], v[162:165], v[80:83], v[92:95]
	v_mfma_f32_16x16x32_bf16 v[116:119], v[178:181], v[84:87], v[68:71]
	v_mfma_f32_16x16x32_bf16 v[68:71], v[182:185], v[80:83], v[96:99]
	v_mfma_f32_16x16x32_bf16 v[112:115], v[186:189], v[84:87], v[68:71]
	v_mfma_f32_16x16x32_bf16 v[68:71], v[162:165], v[190:193], v[100:103]
	v_mfma_f32_16x16x32_bf16 v[124:127], v[178:181], v[76:79], v[108:111]
	v_mfma_f32_16x16x32_bf16 v[108:111], v[178:181], v[194:197], v[68:71]
	v_mfma_f32_16x16x32_bf16 v[68:71], v[182:185], v[190:193], v[104:107]
	v_mfma_f32_16x16x32_bf16 v[104:107], v[186:189], v[194:197], v[68:71]
	v_mfma_f32_16x16x32_bf16 v[68:71], v[162:165], v[208:211], v[166:169]
	v_mfma_f32_16x16x32_bf16 v[100:103], v[178:181], v[212:215], v[68:71]
	v_mfma_f32_16x16x32_bf16 v[68:71], v[182:185], v[208:211], v[170:173]
	v_mfma_f32_16x16x32_bf16 v[96:99], v[186:189], v[212:215], v[68:71]
	s_setprio 0
	s_barrier
	s_mov_b32 m0, s97
	v_lshl_add_u64 v[84:85], v[216:217], 0, s[14:15]
	s_add_u32 s34, s72, 0x40080
	s_nop 1
	ds_read_b128 v[68:71], v146 offset:49152
	ds_read_b128 v[76:79], v146 offset:50176
	ds_read_b128 v[80:83], v146 offset:51200
	ds_read_b128 v[166:169], v146 offset:52224
	ds_read_b128 v[170:173], v146 offset:53248
	ds_read_b128 v[190:193], v146 offset:54272
	ds_read_b128 v[194:197], v146 offset:55296
	ds_read_b128 v[208:211], v146 offset:56320
	global_load_lds_dwordx4 v[84:85], off
	v_lshl_add_u64 v[84:85], v[218:219], 0, s[14:15]
	s_mov_b32 m0, s82
	s_addc_u32 s35, s73, 0
	global_load_lds_dwordx4 v[84:85], off
	v_lshl_add_u64 v[84:85], s[34:35], 0, v[132:133]
	s_mov_b32 m0, s94
	s_nop 0
	v_lshl_add_u64 v[84:85], s[34:35], 0, v[128:129]
	s_mov_b32 m0, s96
	s_nop 0
	v_lshl_add_u64 v[84:85], v[220:221], 0, s[14:15]
	s_mov_b32 m0, s85
	s_nop 0
	global_load_lds_dwordx4 v[84:85], off
	v_lshl_add_u64 v[84:85], v[222:223], 0, s[14:15]
	s_mov_b32 m0, s86
	s_nop 0
	global_load_lds_dwordx4 v[84:85], off
	s_waitcnt vmcnt(6)
	s_waitcnt lgkmcnt(0)
	s_barrier
	s_setprio 1
	s_waitcnt lgkmcnt(0)
	v_mfma_f32_16x16x32_bf16 v[56:59], v[162:165], v[68:71], v[56:59]
	v_mfma_f32_16x16x32_bf16 v[92:95], v[178:181], v[76:79], v[56:59]
	v_mfma_f32_16x16x32_bf16 v[56:59], v[182:185], v[68:71], v[60:63]
	v_mfma_f32_16x16x32_bf16 v[88:91], v[186:189], v[76:79], v[56:59]
	v_mfma_f32_16x16x32_bf16 v[56:59], v[162:165], v[80:83], v[198:201]
	v_mfma_f32_16x16x32_bf16 v[84:87], v[178:181], v[166:169], v[56:59]
	v_mfma_f32_16x16x32_bf16 v[56:59], v[182:185], v[80:83], v[174:177]
	v_mfma_f32_16x16x32_bf16 v[80:83], v[186:189], v[166:169], v[56:59]
	v_mfma_f32_16x16x32_bf16 v[56:59], v[162:165], v[170:173], v[140:143]
	v_mfma_f32_16x16x32_bf16 v[76:79], v[178:181], v[190:193], v[56:59]
	v_mfma_f32_16x16x32_bf16 v[56:59], v[182:185], v[170:173], v[150:153]
	v_mfma_f32_16x16x32_bf16 v[68:71], v[186:189], v[190:193], v[56:59]
	v_mfma_f32_16x16x32_bf16 v[56:59], v[162:165], v[194:197], v[154:157]
	v_mfma_f32_16x16x32_bf16 v[60:63], v[178:181], v[208:211], v[56:59]
	v_mfma_f32_16x16x32_bf16 v[56:59], v[182:185], v[194:197], v[158:161]
	v_mfma_f32_16x16x32_bf16 v[56:59], v[186:189], v[208:211], v[56:59]
	s_setprio 0
	s_barrier
	s_andn2_b64 vcc, exec, s[16:17]
	s_cbranch_vccnz .LBB0_2261
	s_barrier

; __device__ __forceinline__ unsigned cvt_pk_bf16(float lo, float hi) { unsigned r; asm volatile("v_cvt_pk_bf16_f32 %0, %1, %2" : "=v"(r) : "v"(lo), "v"(hi)); return r; }
; __device__ __forceinline__ float fast_sigmoid(float x) { return __builtin_amdgcn_rcpf(1.0f + __builtin_amdgcn_exp2f(-1.4426950408889634f * x)); }
; __device__ __forceinline__ float silu_f(float x) { return x * fast_sigmoid(x); }
;     __device__ __forceinline__ void operator()(const f32x4 (&acc)[2][2][4][2], const Unit& u, int wr, int wc, int fr, int fq) const {
;         const int row0 = u.pm * BM + wr * 64 + fr, col0 = u.pn * HALF + wc * 32 + 8 * fq;
; #pragma unroll
;         for (int ai = 0; ai < 2; ++ai)
; #pragma unroll
;             for (int m = 0; m < 4; ++m) {
;                 bf16_t* p = O + (size_t)(row0 + ai * HALF + m * 16) * DFF_ + col0;
;                 const f32x4 a0 = acc[ai][0][m][0], a1 = acc[ai][0][m][1], b0 = acc[ai][1][m][0], b1 = acc[ai][1][m][1];
;                 float h[8];
; #pragma unroll
;                 for (int e = 0; e < 4; ++e) { h[e] = silu_f(a0[e]) * b0[e]; h[4 + e] = silu_f(a1[e]) * b1[e]; }
;                 u32x4 w; w.x = cvt_pk_bf16(h[0], h[1]); w.y = cvt_pk_bf16(h[2], h[3]); w.z = cvt_pk_bf16(h[4], h[5]); w.w = cvt_pk_bf16(h[6], h[7]);
;                 *(u32x4*)p = w;
;             }
.LBB0_2464:
	s_andn2_b64 vcc, exec, s[6:7]
	s_mov_b64 s[6:7], -1
	v_mov_b32_e32 v160, 0xbfb8aa3b
	v_mov_b32_e32 v161, 0xbfb8aa3b
	v_mov_b32_e32 v162, 1.0
	v_mov_b32_e32 v163, 1.0
	v_lshl_or_b32 v164, s58, 7, v148
	v_lshl_add_u32 v166, s26, 8, v146
	v_mov_b64_e32 v[168:169], s[10:11]
	v_ashrrev_i32_e32 v165, 31, v164
	v_mad_i64_i32 v[170:171], s[34:35], v166, s57, v[168:169]
	v_lshlrev_b64 v[164:165], 1, v[164:165]
	v_lshl_add_u64 v[170:171], v[170:171], 0, v[164:165]
	v_pk_mul_f32 v[152:153], v[124:125], v[160:161]
	v_pk_mul_f32 v[154:155], v[126:127], v[160:161]
	v_pk_mul_f32 v[156:157], v[120:121], v[160:161]
	v_pk_mul_f32 v[158:159], v[122:123], v[160:161]
	v_exp_f32_e32 v152, v152
	v_exp_f32_e32 v153, v153
	v_exp_f32_e32 v154, v154
	v_exp_f32_e32 v155, v155
	v_exp_f32_e32 v156, v156
	v_exp_f32_e32 v157, v157
	v_exp_f32_e32 v158, v158
	v_exp_f32_e32 v159, v159
	v_pk_add_f32 v[152:153], v[152:153], v[162:163]
	v_pk_add_f32 v[154:155], v[154:155], v[162:163]
	v_pk_add_f32 v[156:157], v[156:157], v[162:163]
	v_pk_add_f32 v[158:159], v[158:159], v[162:163]
	v_rcp_f32_e32 v152, v152
	v_rcp_f32_e32 v153, v153
	v_rcp_f32_e32 v154, v154
	v_rcp_f32_e32 v155, v155
	v_rcp_f32_e32 v156, v156
	v_rcp_f32_e32 v157, v157
	v_rcp_f32_e32 v158, v158
	v_rcp_f32_e32 v159, v159
	v_pk_mul_f32 v[152:153], v[124:125], v[152:153]
	v_pk_mul_f32 v[154:155], v[126:127], v[154:155]
	v_pk_mul_f32 v[156:157], v[120:121], v[156:157]
	v_pk_mul_f32 v[158:159], v[122:123], v[158:159]
	v_pk_mul_f32 v[152:153], v[152:153], v[116:117]
	v_pk_mul_f32 v[154:155], v[154:155], v[118:119]
	v_pk_mul_f32 v[156:157], v[156:157], v[112:113]
	v_pk_mul_f32 v[158:159], v[158:159], v[114:115]
	v_cvt_pk_bf16_f32 v194, v152, v153
	v_cvt_pk_bf16_f32 v195, v154, v155
	v_cvt_pk_bf16_f32 v196, v156, v157
	v_cvt_pk_bf16_f32 v197, v158, v159
	global_store_dwordx4 v[170:171], v[194:197], off
	v_pk_mul_f32 v[152:153], v[108:109], v[160:161]
	v_pk_mul_f32 v[154:155], v[110:111], v[160:161]
	v_pk_mul_f32 v[156:157], v[104:105], v[160:161]
	v_pk_mul_f32 v[158:159], v[106:107], v[160:161]
	v_exp_f32_e32 v152, v152
	v_exp_f32_e32 v153, v153
	v_exp_f32_e32 v154, v154
	v_exp_f32_e32 v155, v155
	v_exp_f32_e32 v156, v156
	v_exp_f32_e32 v157, v157
	v_exp_f32_e32 v158, v158
	v_exp_f32_e32 v159, v159
	v_pk_add_f32 v[152:153], v[152:153], v[162:163]
	v_pk_add_f32 v[154:155], v[154:155], v[162:163]
	v_pk_add_f32 v[156:157], v[156:157], v[162:163]
	v_pk_add_f32 v[158:159], v[158:159], v[162:163]
	v_rcp_f32_e32 v152, v152
	v_rcp_f32_e32 v153, v153
	v_rcp_f32_e32 v154, v154
	v_rcp_f32_e32 v155, v155
	v_rcp_f32_e32 v156, v156
	v_rcp_f32_e32 v157, v157
	v_rcp_f32_e32 v158, v158
	v_rcp_f32_e32 v159, v159
	s_mov_b64 s[34:35], 0x16000
	v_lshl_add_u64 v[188:189], v[170:171], 0, s[34:35]
	v_pk_mul_f32 v[152:153], v[108:109], v[152:153]
	v_pk_mul_f32 v[154:155], v[110:111], v[154:155]
	v_pk_mul_f32 v[156:157], v[104:105], v[156:157]
	v_pk_mul_f32 v[158:159], v[106:107], v[158:159]
	v_pk_mul_f32 v[152:153], v[152:153], v[100:101]
	v_pk_mul_f32 v[154:155], v[154:155], v[102:103]
	v_pk_mul_f32 v[156:157], v[156:157], v[96:97]
	v_pk_mul_f32 v[158:159], v[158:159], v[98:99]
	v_cvt_pk_bf16_f32 v222, v152, v153
	v_cvt_pk_bf16_f32 v223, v154, v155
	v_cvt_pk_bf16_f32 v224, v156, v157
	v_cvt_pk_bf16_f32 v225, v158, v159
	global_store_dwordx4 v[188:189], v[222:225], off
	v_pk_mul_f32 v[152:153], v[92:93], v[160:161]
	v_pk_mul_f32 v[154:155], v[94:95], v[160:161]
	v_pk_mul_f32 v[156:157], v[88:89], v[160:161]
	v_pk_mul_f32 v[158:159], v[90:91], v[160:161]
	v_exp_f32_e32 v152, v152
	v_exp_f32_e32 v153, v153
	v_exp_f32_e32 v154, v154
	v_exp_f32_e32 v155, v155
	v_exp_f32_e32 v156, v156
	v_exp_f32_e32 v157, v157
	v_exp_f32_e32 v158, v158
	v_exp_f32_e32 v159, v159
	v_pk_add_f32 v[152:153], v[152:153], v[162:163]
	v_pk_add_f32 v[154:155], v[154:155], v[162:163]
	v_pk_add_f32 v[156:157], v[156:157], v[162:163]
	v_pk_add_f32 v[158:159], v[158:159], v[162:163]
	v_rcp_f32_e32 v152, v152
	v_rcp_f32_e32 v153, v153
	v_rcp_f32_e32 v154, v154
	v_rcp_f32_e32 v155, v155
	v_rcp_f32_e32 v156, v156
	v_rcp_f32_e32 v157, v157
	v_rcp_f32_e32 v158, v158
	v_rcp_f32_e32 v159, v159
	s_mov_b64 s[34:35], 0x2c000
	v_lshl_add_u64 v[190:191], v[170:171], 0, s[34:35]
	v_pk_mul_f32 v[152:153], v[92:93], v[152:153]
	v_pk_mul_f32 v[154:155], v[94:95], v[154:155]
	v_pk_mul_f32 v[156:157], v[88:89], v[156:157]
	v_pk_mul_f32 v[158:159], v[90:91], v[158:159]
	v_pk_mul_f32 v[152:153], v[152:153], v[84:85]
	v_pk_mul_f32 v[154:155], v[154:155], v[86:87]
	v_pk_mul_f32 v[156:157], v[156:157], v[80:81]
	v_pk_mul_f32 v[158:159], v[158:159], v[82:83]
	v_cvt_pk_bf16_f32 v226, v152, v153
	v_cvt_pk_bf16_f32 v227, v154, v155
	v_cvt_pk_bf16_f32 v228, v156, v157
	v_cvt_pk_bf16_f32 v229, v158, v159
	global_store_dwordx4 v[190:191], v[226:229], off
	v_pk_mul_f32 v[152:153], v[76:77], v[160:161]
	v_pk_mul_f32 v[154:155], v[78:79], v[160:161]
	v_pk_mul_f32 v[156:157], v[72:73], v[160:161]
	v_pk_mul_f32 v[158:159], v[74:75], v[160:161]
	v_exp_f32_e32 v152, v152
	v_exp_f32_e32 v153, v153
	v_exp_f32_e32 v154, v154
	v_exp_f32_e32 v155, v155
	v_exp_f32_e32 v156, v156
	v_exp_f32_e32 v157, v157
	v_exp_f32_e32 v158, v158
	v_exp_f32_e32 v159, v159
	v_pk_add_f32 v[152:153], v[152:153], v[162:163]
	v_pk_add_f32 v[154:155], v[154:155], v[162:163]
	v_pk_add_f32 v[156:157], v[156:157], v[162:163]
	v_pk_add_f32 v[158:159], v[158:159], v[162:163]
	v_rcp_f32_e32 v152, v152
	v_rcp_f32_e32 v153, v153
	v_rcp_f32_e32 v154, v154
	v_rcp_f32_e32 v155, v155
	v_rcp_f32_e32 v156, v156
	v_rcp_f32_e32 v157, v157
	v_rcp_f32_e32 v158, v158
	v_rcp_f32_e32 v159, v159
	s_mov_b64 s[34:35], 0x42000
; __device__ __forceinline__ unsigned cvt_pk_bf16(float lo, float hi) { unsigned r; asm volatile("v_cvt_pk_bf16_f32 %0, %1, %2" : "=v"(r) : "v"(lo), "v"(hi)); return r; }
; __device__ __forceinline__ float fast_sigmoid(float x) { return __builtin_amdgcn_rcpf(1.0f + __builtin_amdgcn_exp2f(-1.4426950408889634f * x)); }
; __device__ __forceinline__ float silu_f(float x) { return x * fast_sigmoid(x); }
;     __device__ __forceinline__ void operator()(const f32x4 (&acc)[2][2][4][2], const Unit& u, int wr, int wc, int fr, int fq) const {
;         const int row0 = u.pm * BM + wr * 64 + fr, col0 = u.pn * HALF + wc * 32 + 8 * fq;
; #pragma unroll
;         for (int ai = 0; ai < 2; ++ai)
; #pragma unroll
;             for (int m = 0; m < 4; ++m) {
;                 bf16_t* p = O + (size_t)(row0 + ai * HALF + m * 16) * DFF_ + col0;
;                 const f32x4 a0 = acc[ai][0][m][0], a1 = acc[ai][0][m][1], b0 = acc[ai][1][m][0], b1 = acc[ai][1][m][1];
;                 float h[8];
; #pragma unroll
;                 for (int e = 0; e < 4; ++e) { h[e] = silu_f(a0[e]) * b0[e]; h[4 + e] = silu_f(a1[e]) * b1[e]; }
;                 u32x4 w; w.x = cvt_pk_bf16(h[0], h[1]); w.y = cvt_pk_bf16(h[2], h[3]); w.z = cvt_pk_bf16(h[4], h[5]); w.w = cvt_pk_bf16(h[6], h[7]);
;                 *(u32x4*)p = w;
;             }
	v_lshl_add_u64 v[192:193], v[170:171], 0, s[34:35]
	v_pk_mul_f32 v[152:153], v[76:77], v[152:153]
	v_pk_mul_f32 v[154:155], v[78:79], v[154:155]
	v_pk_mul_f32 v[156:157], v[72:73], v[156:157]
	v_pk_mul_f32 v[158:159], v[74:75], v[158:159]
	v_pk_mul_f32 v[152:153], v[152:153], v[68:69]
	v_pk_mul_f32 v[154:155], v[154:155], v[70:71]
	v_pk_mul_f32 v[156:157], v[156:157], v[64:65]
	v_pk_mul_f32 v[158:159], v[158:159], v[66:67]
	v_cvt_pk_bf16_f32 v230, v152, v153
	v_cvt_pk_bf16_f32 v231, v154, v155
	v_cvt_pk_bf16_f32 v232, v156, v157
	v_cvt_pk_bf16_f32 v233, v158, v159
	global_store_dwordx4 v[192:193], v[230:233], off
	v_pk_mul_f32 v[152:153], v[60:61], v[160:161]
	v_pk_mul_f32 v[154:155], v[62:63], v[160:161]
	v_pk_mul_f32 v[156:157], v[56:57], v[160:161]
	v_pk_mul_f32 v[158:159], v[58:59], v[160:161]
	v_exp_f32_e32 v152, v152
	v_exp_f32_e32 v153, v153
	v_exp_f32_e32 v154, v154
	v_exp_f32_e32 v155, v155
	v_exp_f32_e32 v156, v156
	v_exp_f32_e32 v157, v157
	v_exp_f32_e32 v158, v158
	v_exp_f32_e32 v159, v159
	v_pk_add_f32 v[152:153], v[152:153], v[162:163]
	v_pk_add_f32 v[154:155], v[154:155], v[162:163]
	v_pk_add_f32 v[156:157], v[156:157], v[162:163]
	v_pk_add_f32 v[158:159], v[158:159], v[162:163]
	v_rcp_f32_e32 v152, v152
	v_rcp_f32_e32 v153, v153
	v_rcp_f32_e32 v154, v154
	v_rcp_f32_e32 v155, v155
	v_rcp_f32_e32 v156, v156
	v_rcp_f32_e32 v157, v157
	v_rcp_f32_e32 v158, v158
	v_rcp_f32_e32 v159, v159
	s_mov_b64 s[34:35], 0xb0000
	v_lshl_add_u64 v[186:187], v[170:171], 0, s[34:35]
	v_pk_mul_f32 v[152:153], v[60:61], v[152:153]
	v_pk_mul_f32 v[154:155], v[62:63], v[154:155]
	v_pk_mul_f32 v[156:157], v[56:57], v[156:157]
	v_pk_mul_f32 v[158:159], v[58:59], v[158:159]
	v_pk_mul_f32 v[152:153], v[152:153], v[52:53]
	v_pk_mul_f32 v[154:155], v[154:155], v[54:55]
	v_pk_mul_f32 v[156:157], v[156:157], v[48:49]
	v_pk_mul_f32 v[158:159], v[158:159], v[50:51]
	v_cvt_pk_bf16_f32 v194, v152, v153
	v_cvt_pk_bf16_f32 v195, v154, v155
	v_cvt_pk_bf16_f32 v196, v156, v157
	v_cvt_pk_bf16_f32 v197, v158, v159
	global_store_dwordx4 v[186:187], v[194:197], off
	v_pk_mul_f32 v[152:153], v[44:45], v[160:161]
	v_pk_mul_f32 v[154:155], v[46:47], v[160:161]
	v_pk_mul_f32 v[156:157], v[40:41], v[160:161]
	v_pk_mul_f32 v[158:159], v[42:43], v[160:161]
	v_exp_f32_e32 v152, v152
	v_exp_f32_e32 v153, v153
	v_exp_f32_e32 v154, v154
	v_exp_f32_e32 v155, v155
	v_exp_f32_e32 v156, v156
	v_exp_f32_e32 v157, v157
	v_exp_f32_e32 v158, v158
	v_exp_f32_e32 v159, v159
	v_pk_add_f32 v[152:153], v[152:153], v[162:163]
	v_pk_add_f32 v[154:155], v[154:155], v[162:163]
	v_pk_add_f32 v[156:157], v[156:157], v[162:163]
	v_pk_add_f32 v[158:159], v[158:159], v[162:163]
	v_rcp_f32_e32 v152, v152
	v_rcp_f32_e32 v153, v153
	v_rcp_f32_e32 v154, v154
	v_rcp_f32_e32 v155, v155
	v_rcp_f32_e32 v156, v156
	v_rcp_f32_e32 v157, v157
	v_rcp_f32_e32 v158, v158
	v_rcp_f32_e32 v159, v159
	s_mov_b64 s[34:35], 0xc6000
	v_lshl_add_u64 v[188:189], v[170:171], 0, s[34:35]
	v_pk_mul_f32 v[152:153], v[44:45], v[152:153]
	v_pk_mul_f32 v[154:155], v[46:47], v[154:155]
	v_pk_mul_f32 v[156:157], v[40:41], v[156:157]
	v_pk_mul_f32 v[158:159], v[42:43], v[158:159]
	v_pk_mul_f32 v[152:153], v[152:153], v[36:37]
	v_pk_mul_f32 v[154:155], v[154:155], v[38:39]
	v_pk_mul_f32 v[156:157], v[156:157], v[32:33]
	v_pk_mul_f32 v[158:159], v[158:159], v[34:35]
	v_cvt_pk_bf16_f32 v222, v152, v153
	v_cvt_pk_bf16_f32 v223, v154, v155
	v_cvt_pk_bf16_f32 v224, v156, v157
	v_cvt_pk_bf16_f32 v225, v158, v159
	global_store_dwordx4 v[188:189], v[222:225], off
	v_pk_mul_f32 v[152:153], v[28:29], v[160:161]
	v_pk_mul_f32 v[154:155], v[30:31], v[160:161]
	v_pk_mul_f32 v[156:157], v[24:25], v[160:161]
	v_pk_mul_f32 v[158:159], v[26:27], v[160:161]
	v_exp_f32_e32 v152, v152
	v_exp_f32_e32 v153, v153
	v_exp_f32_e32 v154, v154
	v_exp_f32_e32 v155, v155
	v_exp_f32_e32 v156, v156
	v_exp_f32_e32 v157, v157
	v_exp_f32_e32 v158, v158
	v_exp_f32_e32 v159, v159
	v_pk_add_f32 v[152:153], v[152:153], v[162:163]
	v_pk_add_f32 v[154:155], v[154:155], v[162:163]
	v_pk_add_f32 v[156:157], v[156:157], v[162:163]
	v_pk_add_f32 v[158:159], v[158:159], v[162:163]
	v_rcp_f32_e32 v152, v152
	v_rcp_f32_e32 v153, v153
	v_rcp_f32_e32 v154, v154
	v_rcp_f32_e32 v155, v155
	v_rcp_f32_e32 v156, v156
	v_rcp_f32_e32 v157, v157
	v_rcp_f32_e32 v158, v158
	v_rcp_f32_e32 v159, v159
	s_mov_b64 s[34:35], 0xdc000
	v_lshl_add_u64 v[190:191], v[170:171], 0, s[34:35]
	v_pk_mul_f32 v[152:153], v[28:29], v[152:153]
	v_pk_mul_f32 v[154:155], v[30:31], v[154:155]
	v_pk_mul_f32 v[156:157], v[24:25], v[156:157]
	v_pk_mul_f32 v[158:159], v[26:27], v[158:159]
	v_pk_mul_f32 v[152:153], v[152:153], v[20:21]
	v_pk_mul_f32 v[154:155], v[154:155], v[22:23]
	v_pk_mul_f32 v[156:157], v[156:157], v[16:17]
	v_pk_mul_f32 v[158:159], v[158:159], v[18:19]
	v_cvt_pk_bf16_f32 v226, v152, v153
	v_cvt_pk_bf16_f32 v227, v154, v155
	v_cvt_pk_bf16_f32 v228, v156, v157
	v_cvt_pk_bf16_f32 v229, v158, v159
	global_store_dwordx4 v[190:191], v[226:229], off
	v_pk_mul_f32 v[152:153], v[12:13], v[160:161]
	v_pk_mul_f32 v[154:155], v[14:15], v[160:161]
	v_pk_mul_f32 v[156:157], v[8:9], v[160:161]
	v_pk_mul_f32 v[158:159], v[10:11], v[160:161]
	v_exp_f32_e32 v152, v152
	v_exp_f32_e32 v153, v153
	v_exp_f32_e32 v154, v154
	v_exp_f32_e32 v155, v155
	v_exp_f32_e32 v156, v156
	v_exp_f32_e32 v157, v157
	v_exp_f32_e32 v158, v158
	v_exp_f32_e32 v159, v159
	v_pk_add_f32 v[152:153], v[152:153], v[162:163]
	v_pk_add_f32 v[154:155], v[154:155], v[162:163]
	v_pk_add_f32 v[156:157], v[156:157], v[162:163]
	v_pk_add_f32 v[158:159], v[158:159], v[162:163]
	v_rcp_f32_e32 v152, v152
	v_rcp_f32_e32 v153, v153
	v_rcp_f32_e32 v154, v154
	v_rcp_f32_e32 v155, v155
	v_rcp_f32_e32 v156, v156
	v_rcp_f32_e32 v157, v157
	v_rcp_f32_e32 v158, v158
	v_rcp_f32_e32 v159, v159
	s_mov_b64 s[34:35], 0xf2000
	v_lshl_add_u64 v[192:193], v[170:171], 0, s[34:35]
	v_pk_mul_f32 v[152:153], v[12:13], v[152:153]
	v_pk_mul_f32 v[154:155], v[14:15], v[154:155]
	v_pk_mul_f32 v[156:157], v[8:9], v[156:157]
	v_pk_mul_f32 v[158:159], v[10:11], v[158:159]
	v_pk_mul_f32 v[152:153], v[152:153], v[4:5]
	v_pk_mul_f32 v[154:155], v[154:155], v[6:7]
	v_pk_mul_f32 v[156:157], v[156:157], v[0:1]
	v_pk_mul_f32 v[158:159], v[158:159], v[2:3]
	v_cvt_pk_bf16_f32 v230, v152, v153
	v_cvt_pk_bf16_f32 v231, v154, v155
	v_cvt_pk_bf16_f32 v232, v156, v157
	v_cvt_pk_bf16_f32 v233, v158, v159
	global_store_dwordx4 v[192:193], v[230:233], off
	s_cbranch_vccnz .LBB0_2457
	s_andn2_b64 vcc, exec, s[8:9]
	s_cbranch_vccnz .LBB0_2456
	s_barrier
	s_branch .LBB0_2456
